# adds: attention QK fragments read ahead of MFMAs, redundant self-max removed in softmax max tree, pooling-diff loop waits merged, prologue pooling-fold loads batched, final-norm fold batched, Up-epilo
# speedup vs baseline: 1.0148x; 1.0148x over previous
; __global__ void __launch_bounds__(NTH, 2) mega(Params p) {
;     ...
;         for (int it = gw; it < DEPTH * 4 * 16 * 8; it += NGW) {
;             const int kc = it & 7, nb = (it >> 3) & 15, g = (it >> 7) & 3, L = it >> 9, n = nb * 64 + lane;
;             const float* wp = kp->in[I_WPOOL] + ((size_t)L * 512 + g * 128 + kc * 16) * 128; const float* ps = kp->in[I_PSC] + L * 512 + g * 128; const float* wb = kp->in[I_WBR] + ((size_t)L * 3 * 512 + g * 128) * 1024 + n;
;             float acc16[16];
; #pragma unroll
;             for (int q = 0; q < 16; ++q) acc16[q] = 0.f;
; #pragma nounroll
;             for (int c0 = 0; c0 < 128; c0 += 32) {
;                 float wv[32];
; #pragma unroll
;                 for (int c = 0; c < 32; ++c) wv[c] = ps[c0 + c] * wb[(size_t)(c0 + c) * 1024];
; #pragma unroll
;                 for (int q = 0; q < 16; ++q)
; #pragma unroll
;                     for (int c = 0; c < 32; ++c) acc16[q] += wp[q * 128 + c0 + c] * wv[c];
.LBB0_74:
	s_lshl_b64 s[0:1], s[8:9], 2
	s_add_u32 s12, s23, s0
	s_addc_u32 s13, s24, s1
	s_lshl_b64 s[26:27], s[8:9], 12
	v_lshl_add_u64 v[156:157], v[28:29], 0, s[26:27]
	global_load_dwordx4 v[2:5], v21, s[12:13] offset:48
	global_load_dwordx4 v[6:9], v21, s[12:13] offset:32
	global_load_dwordx4 v[10:13], v21, s[12:13] offset:16
	global_load_dwordx4 v[14:17], v21, s[12:13]
	s_or_b32 s26, s8, 1
	global_load_dword v140, v[156:157], off
	s_mov_b32 s27, s9
	s_lshl_b64 s[26:27], s[26:27], 12
	v_lshl_add_u64 v[156:157], v[28:29], 0, s[26:27]
	global_load_dword v141, v[156:157], off
	s_or_b32 s26, s8, 2
	s_mov_b32 s27, s9
	s_lshl_b64 s[26:27], s[26:27], 12
	v_lshl_add_u64 v[156:157], v[28:29], 0, s[26:27]
	global_load_dword v142, v[156:157], off
	s_or_b32 s26, s8, 3
	s_mov_b32 s27, s9
	s_lshl_b64 s[26:27], s[26:27], 12
	v_lshl_add_u64 v[156:157], v[28:29], 0, s[26:27]
	global_load_dword v143, v[156:157], off
	s_or_b32 s26, s8, 4
	s_mov_b32 s27, s9
	s_lshl_b64 s[26:27], s[26:27], 12
	v_lshl_add_u64 v[156:157], v[28:29], 0, s[26:27]
	global_load_dword v144, v[156:157], off
	s_or_b32 s26, s8, 5
	s_mov_b32 s27, s9
	s_lshl_b64 s[26:27], s[26:27], 12
	v_lshl_add_u64 v[156:157], v[28:29], 0, s[26:27]
	global_load_dword v145, v[156:157], off
	s_or_b32 s26, s8, 6
	s_mov_b32 s27, s9
	s_lshl_b64 s[26:27], s[26:27], 12
	v_lshl_add_u64 v[156:157], v[28:29], 0, s[26:27]
	global_load_dword v146, v[156:157], off
	s_or_b32 s26, s8, 7
	s_mov_b32 s27, s9
	s_lshl_b64 s[26:27], s[26:27], 12
	v_lshl_add_u64 v[156:157], v[28:29], 0, s[26:27]
	global_load_dword v147, v[156:157], off
	s_or_b32 s26, s8, 8
	s_mov_b32 s27, s9
	s_lshl_b64 s[26:27], s[26:27], 12
	v_lshl_add_u64 v[156:157], v[28:29], 0, s[26:27]
	global_load_dword v148, v[156:157], off
	s_or_b32 s26, s8, 9
	s_mov_b32 s27, s9
	s_lshl_b64 s[26:27], s[26:27], 12
	v_lshl_add_u64 v[156:157], v[28:29], 0, s[26:27]
	global_load_dword v149, v[156:157], off
	s_or_b32 s26, s8, 10
	s_mov_b32 s27, s9
	s_lshl_b64 s[26:27], s[26:27], 12
	v_lshl_add_u64 v[156:157], v[28:29], 0, s[26:27]
	global_load_dword v150, v[156:157], off
	s_or_b32 s26, s8, 11
	s_mov_b32 s27, s9
	s_lshl_b64 s[26:27], s[26:27], 12
	v_lshl_add_u64 v[156:157], v[28:29], 0, s[26:27]
	global_load_dword v151, v[156:157], off
	s_or_b32 s26, s8, 12
	s_mov_b32 s27, s9
	s_lshl_b64 s[26:27], s[26:27], 12
	v_lshl_add_u64 v[156:157], v[28:29], 0, s[26:27]
	global_load_dword v152, v[156:157], off
	s_or_b32 s26, s8, 13
	s_mov_b32 s27, s9
	s_lshl_b64 s[26:27], s[26:27], 12
	v_lshl_add_u64 v[156:157], v[28:29], 0, s[26:27]
	global_load_dword v153, v[156:157], off
	s_or_b32 s26, s8, 14
	s_mov_b32 s27, s9
	s_lshl_b64 s[26:27], s[26:27], 12
	v_lshl_add_u64 v[156:157], v[28:29], 0, s[26:27]
	global_load_dword v154, v[156:157], off
	s_or_b32 s26, s8, 15
	s_mov_b32 s27, s9
	s_lshl_b64 s[26:27], s[26:27], 12
	v_lshl_add_u64 v[156:157], v[28:29], 0, s[26:27]
	global_load_dword v155, v[156:157], off
	s_or_b32 s26, s8, 16
	s_mov_b32 s27, s9
	s_waitcnt vmcnt(0)
	v_mul_f32_e32 v68, v14, v140
	v_mul_f32_e32 v70, v15, v141
	v_mul_f32_e32 v72, v16, v142
	v_mul_f32_e32 v74, v17, v143
	v_mul_f32_e32 v76, v10, v144
	v_mul_f32_e32 v78, v11, v145
	v_mul_f32_e32 v80, v12, v146
	v_mul_f32_e32 v82, v13, v147
	v_mul_f32_e32 v84, v6, v148
	v_mul_f32_e32 v86, v7, v149
	v_mul_f32_e32 v88, v8, v150
	v_mul_f32_e32 v90, v9, v151
	v_mul_f32_e32 v92, v2, v152
	v_mul_f32_e32 v94, v3, v153
	v_mul_f32_e32 v96, v4, v154
	v_mul_f32_e32 v98, v5, v155
	global_load_dwordx4 v[2:5], v21, s[12:13] offset:112
	global_load_dwordx4 v[6:9], v21, s[12:13] offset:96
	global_load_dwordx4 v[10:13], v21, s[12:13] offset:80
	global_load_dwordx4 v[14:17], v21, s[12:13] offset:64
	s_lshl_b64 s[12:13], s[26:27], 12
	v_lshl_add_u64 v[156:157], v[28:29], 0, s[12:13]
	global_load_dword v140, v[156:157], off
	s_or_b32 s12, s8, 17
	s_mov_b32 s13, s9
	s_lshl_b64 s[12:13], s[12:13], 12
	v_lshl_add_u64 v[156:157], v[28:29], 0, s[12:13]
	global_load_dword v141, v[156:157], off
	s_or_b32 s12, s8, 18
	s_mov_b32 s13, s9
	s_lshl_b64 s[12:13], s[12:13], 12
	v_lshl_add_u64 v[156:157], v[28:29], 0, s[12:13]
	global_load_dword v142, v[156:157], off
	s_or_b32 s12, s8, 19
	s_mov_b32 s13, s9
	s_lshl_b64 s[12:13], s[12:13], 12
	v_lshl_add_u64 v[156:157], v[28:29], 0, s[12:13]
	global_load_dword v143, v[156:157], off
	s_or_b32 s12, s8, 20
	s_mov_b32 s13, s9
	s_lshl_b64 s[12:13], s[12:13], 12
	v_lshl_add_u64 v[156:157], v[28:29], 0, s[12:13]
	global_load_dword v144, v[156:157], off
	s_or_b32 s12, s8, 21
	s_mov_b32 s13, s9
	s_lshl_b64 s[12:13], s[12:13], 12
	v_lshl_add_u64 v[156:157], v[28:29], 0, s[12:13]
	global_load_dword v145, v[156:157], off
	s_or_b32 s12, s8, 22
	s_mov_b32 s13, s9
	s_lshl_b64 s[12:13], s[12:13], 12
	v_lshl_add_u64 v[156:157], v[28:29], 0, s[12:13]
	global_load_dword v146, v[156:157], off
	s_or_b32 s12, s8, 23
	s_mov_b32 s13, s9
	s_lshl_b64 s[12:13], s[12:13], 12
	v_lshl_add_u64 v[156:157], v[28:29], 0, s[12:13]
	global_load_dword v147, v[156:157], off
	s_or_b32 s12, s8, 24
	s_mov_b32 s13, s9
	s_lshl_b64 s[12:13], s[12:13], 12
	v_lshl_add_u64 v[156:157], v[28:29], 0, s[12:13]
	global_load_dword v148, v[156:157], off
	s_or_b32 s12, s8, 25
	s_mov_b32 s13, s9
	s_lshl_b64 s[12:13], s[12:13], 12
	v_lshl_add_u64 v[156:157], v[28:29], 0, s[12:13]
	global_load_dword v149, v[156:157], off
	s_or_b32 s12, s8, 26
	s_mov_b32 s13, s9
	s_lshl_b64 s[12:13], s[12:13], 12
	v_lshl_add_u64 v[156:157], v[28:29], 0, s[12:13]
	global_load_dword v150, v[156:157], off
	s_or_b32 s12, s8, 27
	s_mov_b32 s13, s9
	s_lshl_b64 s[12:13], s[12:13], 12
	v_lshl_add_u64 v[156:157], v[28:29], 0, s[12:13]
	global_load_dword v151, v[156:157], off
	s_or_b32 s12, s8, 28
	s_mov_b32 s13, s9
	s_lshl_b64 s[12:13], s[12:13], 12
	v_lshl_add_u64 v[156:157], v[28:29], 0, s[12:13]
	global_load_dword v152, v[156:157], off
	s_or_b32 s12, s8, 29
	s_mov_b32 s13, s9
	s_lshl_b64 s[12:13], s[12:13], 12
	v_lshl_add_u64 v[156:157], v[28:29], 0, s[12:13]
	global_load_dword v153, v[156:157], off
	s_or_b32 s12, s8, 30
	s_mov_b32 s13, s9
	s_lshl_b64 s[12:13], s[12:13], 12
	v_lshl_add_u64 v[156:157], v[28:29], 0, s[12:13]
	global_load_dword v154, v[156:157], off
	s_or_b32 s12, s8, 31
	s_mov_b32 s13, s9
	s_lshl_b64 s[12:13], s[12:13], 12
	s_add_u32 s0, s19, s0
	s_addc_u32 s1, s22, s1
	v_lshl_add_u64 v[156:157], v[28:29], 0, s[12:13]
	global_load_dword v155, v[156:157], off
	s_add_u32 s12, s0, 0x1000
	s_addc_u32 s13, s1, 0
	s_waitcnt vmcnt(0)
; __global__ void __launch_bounds__(NTH, 2) mega(Params p) {
;     ...
;                 for (int c = 0; c < 32; ++c) wv[c] = ps[c0 + c] * wb[(size_t)(c0 + c) * 1024];
; #pragma unroll
;                 for (int q = 0; q < 16; ++q)
; #pragma unroll
;                     for (int c = 0; c < 32; ++c) acc16[q] += wp[q * 128 + c0 + c] * wv[c];
	v_mul_f32_e32 v100, v14, v140
	v_mul_f32_e32 v102, v15, v141
	v_mul_f32_e32 v104, v16, v142
	v_mul_f32_e32 v106, v17, v143
	v_mul_f32_e32 v108, v10, v144
	v_mul_f32_e32 v50, v11, v145
	v_mul_f32_e32 v52, v12, v146
	v_mul_f32_e32 v54, v13, v147
	v_mul_f32_e32 v56, v6, v148
	v_mul_f32_e32 v58, v7, v149
	v_mul_f32_e32 v60, v8, v150
	v_mul_f32_e32 v62, v9, v151
	v_mul_f32_e32 v64, v2, v152
	v_mul_f32_e32 v66, v3, v153
	v_mul_f32_e32 v44, v4, v154
	v_mul_f32_e32 v46, v5, v155
	global_load_dwordx4 v[2:5], v21, s[0:1] offset:32
	global_load_dwordx3 v[18:20], v21, s[0:1] offset:48
	global_load_dwordx4 v[6:9], v21, s[0:1] offset:16
	global_load_dwordx4 v[10:13], v21, s[0:1]
	global_load_dwordx4 v[14:17], v21, s[0:1] offset:76
	global_load_dwordx3 v[22:24], v21, s[0:1] offset:108
	global_load_dwordx4 v[110:113], v21, s[0:1] offset:92
	global_load_dwordx4 v[114:117], v21, s[0:1] offset:60
	global_load_dwordx4 v[118:121], v21, s[0:1] offset:544
	global_load_dwordx3 v[130:132], v21, s[0:1] offset:560
	global_load_dwordx4 v[122:125], v21, s[0:1] offset:528
	global_load_dwordx4 v[126:129], v21, s[0:1] offset:512
	s_waitcnt vmcnt(8)
	v_mov_b32_e32 v134, v10
	s_waitcnt vmcnt(0)
	v_mov_b32_e32 v135, v126
	v_pk_fma_f32 v[42:43], v[134:135], v[68:69], v[42:43] op_sel_hi:[1,0,1]
	v_mov_b32_e32 v126, v11
	v_pk_fma_f32 v[10:11], v[126:127], v[70:71], v[42:43] op_sel_hi:[1,0,1]
	v_mov_b32_e32 v42, v12
	v_mov_b32_e32 v43, v128
	v_pk_fma_f32 v[10:11], v[42:43], v[72:73], v[10:11] op_sel_hi:[1,0,1]
	v_mov_b32_e32 v128, v13
	v_pk_fma_f32 v[10:11], v[128:129], v[74:75], v[10:11] op_sel_hi:[1,0,1]
	v_mov_b32_e32 v12, v6
	v_mov_b32_e32 v13, v122
	v_pk_fma_f32 v[10:11], v[12:13], v[76:77], v[10:11] op_sel_hi:[1,0,1]
	v_mov_b32_e32 v122, v7
	v_pk_fma_f32 v[6:7], v[122:123], v[78:79], v[10:11] op_sel_hi:[1,0,1]
	v_mov_b32_e32 v10, v8
	v_mov_b32_e32 v11, v124
	v_pk_fma_f32 v[6:7], v[10:11], v[80:81], v[6:7] op_sel_hi:[1,0,1]
	v_mov_b32_e32 v124, v9
	v_pk_fma_f32 v[6:7], v[124:125], v[82:83], v[6:7] op_sel_hi:[1,0,1]
	v_mov_b32_e32 v8, v2
	v_mov_b32_e32 v9, v118
	v_pk_fma_f32 v[6:7], v[8:9], v[84:85], v[6:7] op_sel_hi:[1,0,1]
	v_mov_b32_e32 v118, v3
	v_pk_fma_f32 v[2:3], v[118:119], v[86:87], v[6:7] op_sel_hi:[1,0,1]
	v_mov_b32_e32 v6, v4
	v_mov_b32_e32 v7, v120
	v_pk_fma_f32 v[2:3], v[6:7], v[88:89], v[2:3] op_sel_hi:[1,0,1]
	v_mov_b32_e32 v120, v5
	v_pk_fma_f32 v[2:3], v[120:121], v[90:91], v[2:3] op_sel_hi:[1,0,1]
	v_mov_b32_e32 v4, v18
	v_mov_b32_e32 v5, v130
	v_pk_fma_f32 v[2:3], v[4:5], v[92:93], v[2:3] op_sel_hi:[1,0,1]
	v_mov_b32_e32 v130, v19
	v_pk_fma_f32 v[2:3], v[130:131], v[94:95], v[2:3] op_sel_hi:[1,0,1]
	v_mov_b32_e32 v4, v20
	v_mov_b32_e32 v5, v132
	v_pk_fma_f32 v[42:43], v[4:5], v[96:97], v[2:3] op_sel_hi:[1,0,1]
	global_load_dwordx4 v[2:5], v21, s[0:1] offset:588
	global_load_dwordx3 v[18:20], v21, s[0:1] offset:620
	global_load_dwordx4 v[6:9], v21, s[0:1] offset:604
	global_load_dwordx4 v[10:13], v21, s[0:1] offset:572
	v_mov_b32_e32 v118, v114
	s_waitcnt vmcnt(0)
	v_mov_b32_e32 v119, v10
	v_pk_fma_f32 v[42:43], v[118:119], v[98:99], v[42:43] op_sel_hi:[1,0,1]
	v_mov_b32_e32 v10, v115
	v_pk_fma_f32 v[10:11], v[10:11], v[100:101], v[42:43] op_sel_hi:[1,0,1]
	v_mov_b32_e32 v42, v116
	v_mov_b32_e32 v43, v12
	v_pk_fma_f32 v[10:11], v[42:43], v[102:103], v[10:11] op_sel_hi:[1,0,1]
	v_mov_b32_e32 v12, v117
	v_pk_fma_f32 v[10:11], v[12:13], v[104:105], v[10:11] op_sel_hi:[1,0,1]
	v_mov_b32_e32 v12, v14
	v_mov_b32_e32 v13, v2
	v_pk_fma_f32 v[10:11], v[12:13], v[106:107], v[10:11] op_sel_hi:[1,0,1]
	v_mov_b32_e32 v2, v15
	v_pk_fma_f32 v[2:3], v[2:3], v[108:109], v[10:11] op_sel_hi:[1,0,1]
	v_mov_b32_e32 v10, v16
	v_mov_b32_e32 v11, v4
	v_pk_fma_f32 v[2:3], v[10:11], v[50:51], v[2:3] op_sel_hi:[1,0,1]
	v_mov_b32_e32 v4, v17
	v_pk_fma_f32 v[2:3], v[4:5], v[52:53], v[2:3] op_sel_hi:[1,0,1]
	v_mov_b32_e32 v4, v110
	v_mov_b32_e32 v5, v6
	v_pk_fma_f32 v[2:3], v[4:5], v[54:55], v[2:3] op_sel_hi:[1,0,1]
	v_mov_b32_e32 v6, v111
	v_pk_fma_f32 v[2:3], v[6:7], v[56:57], v[2:3] op_sel_hi:[1,0,1]
	v_mov_b32_e32 v4, v112
	v_mov_b32_e32 v5, v8
	v_pk_fma_f32 v[2:3], v[4:5], v[58:59], v[2:3] op_sel_hi:[1,0,1]
	v_mov_b32_e32 v8, v113
	v_pk_fma_f32 v[2:3], v[8:9], v[60:61], v[2:3] op_sel_hi:[1,0,1]
	v_mov_b32_e32 v4, v22
	v_mov_b32_e32 v5, v18
	v_pk_fma_f32 v[2:3], v[4:5], v[62:63], v[2:3] op_sel_hi:[1,0,1]
	v_mov_b32_e32 v18, v23
	v_pk_fma_f32 v[2:3], v[18:19], v[64:65], v[2:3] op_sel_hi:[1,0,1]
	v_mov_b32_e32 v4, v24
	v_mov_b32_e32 v5, v20
	global_load_dwordx2 v[12:13], v21, s[0:1] offset:120
	v_pk_fma_f32 v[2:3], v[4:5], v[66:67], v[2:3] op_sel_hi:[1,0,1]
	global_load_dwordx2 v[4:5], v21, s[0:1] offset:632
	s_waitcnt vmcnt(1)
	v_mov_b32_e32 v6, v12
	s_waitcnt vmcnt(0)
	v_mov_b32_e32 v7, v4
	v_pk_fma_f32 v[2:3], v[6:7], v[44:45], v[2:3] op_sel_hi:[1,0,1]
	v_mov_b32_e32 v4, v13
	v_pk_fma_f32 v[42:43], v[4:5], v[46:47], v[2:3] op_sel_hi:[1,0,1]
	global_load_dwordx4 v[2:5], v21, s[0:1] offset:1056
	global_load_dwordx3 v[10:12], v21, s[0:1] offset:1072
	global_load_dwordx4 v[6:9], v21, s[0:1] offset:1040
	global_load_dwordx4 v[14:17], v21, s[0:1] offset:1024
	global_load_dwordx4 v[110:113], v21, s[0:1] offset:1100
	global_load_dwordx3 v[18:20], v21, s[0:1] offset:1132
	global_load_dwordx4 v[114:117], v21, s[0:1] offset:1116
	global_load_dwordx4 v[118:121], v21, s[0:1] offset:1084
	global_load_dwordx4 v[122:125], v21, s[0:1] offset:1568
	global_load_dwordx3 v[22:24], v21, s[0:1] offset:1584
	global_load_dwordx4 v[126:129], v21, s[0:1] offset:1552
	global_load_dwordx4 v[130:133], v21, s[0:1] offset:1536
	s_waitcnt vmcnt(8)
	v_mov_b32_e32 v134, v14
	s_waitcnt vmcnt(0)
; __global__ void __launch_bounds__(NTH, 2) mega(Params p) {
;     ...
;                 for (int q = 0; q < 16; ++q)
; #pragma unroll
;                     for (int c = 0; c < 32; ++c) acc16[q] += wp[q * 128 + c0 + c] * wv[c];
	v_mov_b32_e32 v135, v130
	v_pk_fma_f32 v[40:41], v[134:135], v[68:69], v[40:41] op_sel_hi:[1,0,1]
	v_mov_b32_e32 v130, v15
	v_pk_fma_f32 v[14:15], v[130:131], v[70:71], v[40:41] op_sel_hi:[1,0,1]
	v_mov_b32_e32 v40, v16
	v_mov_b32_e32 v41, v132
	v_pk_fma_f32 v[14:15], v[40:41], v[72:73], v[14:15] op_sel_hi:[1,0,1]
	v_mov_b32_e32 v132, v17
	v_pk_fma_f32 v[14:15], v[132:133], v[74:75], v[14:15] op_sel_hi:[1,0,1]
	v_mov_b32_e32 v16, v6
	v_mov_b32_e32 v17, v126
	v_pk_fma_f32 v[14:15], v[16:17], v[76:77], v[14:15] op_sel_hi:[1,0,1]
	v_mov_b32_e32 v126, v7
	v_pk_fma_f32 v[6:7], v[126:127], v[78:79], v[14:15] op_sel_hi:[1,0,1]
	v_mov_b32_e32 v14, v8
	v_mov_b32_e32 v15, v128
	v_pk_fma_f32 v[6:7], v[14:15], v[80:81], v[6:7] op_sel_hi:[1,0,1]
	v_mov_b32_e32 v128, v9
	v_pk_fma_f32 v[6:7], v[128:129], v[82:83], v[6:7] op_sel_hi:[1,0,1]
	v_mov_b32_e32 v8, v2
	v_mov_b32_e32 v9, v122
	v_pk_fma_f32 v[6:7], v[8:9], v[84:85], v[6:7] op_sel_hi:[1,0,1]
	v_mov_b32_e32 v122, v3
	v_pk_fma_f32 v[2:3], v[122:123], v[86:87], v[6:7] op_sel_hi:[1,0,1]
	v_mov_b32_e32 v6, v4
	v_mov_b32_e32 v7, v124
	v_pk_fma_f32 v[2:3], v[6:7], v[88:89], v[2:3] op_sel_hi:[1,0,1]
	v_mov_b32_e32 v124, v5
	v_pk_fma_f32 v[2:3], v[124:125], v[90:91], v[2:3] op_sel_hi:[1,0,1]
	v_mov_b32_e32 v4, v10
	v_mov_b32_e32 v5, v22
	v_pk_fma_f32 v[2:3], v[4:5], v[92:93], v[2:3] op_sel_hi:[1,0,1]
	v_mov_b32_e32 v22, v11
	v_pk_fma_f32 v[2:3], v[22:23], v[94:95], v[2:3] op_sel_hi:[1,0,1]
	v_mov_b32_e32 v4, v12
	v_mov_b32_e32 v5, v24
	v_pk_fma_f32 v[22:23], v[4:5], v[96:97], v[2:3] op_sel_hi:[1,0,1]
	global_load_dwordx4 v[2:5], v21, s[0:1] offset:1612
	global_load_dwordx3 v[14:16], v21, s[0:1] offset:1644
	global_load_dwordx4 v[6:9], v21, s[0:1] offset:1628
	global_load_dwordx4 v[10:13], v21, s[0:1] offset:1596
	v_mov_b32_e32 v40, v118
	s_waitcnt vmcnt(0)
	v_mov_b32_e32 v41, v10
	v_pk_fma_f32 v[22:23], v[40:41], v[98:99], v[22:23] op_sel_hi:[1,0,1]
	v_mov_b32_e32 v10, v119
	v_pk_fma_f32 v[10:11], v[10:11], v[100:101], v[22:23] op_sel_hi:[1,0,1]
	v_mov_b32_e32 v22, v120
	v_mov_b32_e32 v23, v12
	v_pk_fma_f32 v[10:11], v[22:23], v[102:103], v[10:11] op_sel_hi:[1,0,1]
	v_mov_b32_e32 v12, v121
	v_pk_fma_f32 v[10:11], v[12:13], v[104:105], v[10:11] op_sel_hi:[1,0,1]
	v_mov_b32_e32 v12, v110
	v_mov_b32_e32 v13, v2
	v_pk_fma_f32 v[10:11], v[12:13], v[106:107], v[10:11] op_sel_hi:[1,0,1]
	v_mov_b32_e32 v2, v111
	v_pk_fma_f32 v[2:3], v[2:3], v[108:109], v[10:11] op_sel_hi:[1,0,1]
	v_mov_b32_e32 v10, v112
	v_mov_b32_e32 v11, v4
	v_pk_fma_f32 v[2:3], v[10:11], v[50:51], v[2:3] op_sel_hi:[1,0,1]
	v_mov_b32_e32 v4, v113
	v_pk_fma_f32 v[2:3], v[4:5], v[52:53], v[2:3] op_sel_hi:[1,0,1]
	v_mov_b32_e32 v4, v114
	v_mov_b32_e32 v5, v6
	v_pk_fma_f32 v[2:3], v[4:5], v[54:55], v[2:3] op_sel_hi:[1,0,1]
	v_mov_b32_e32 v6, v115
	v_pk_fma_f32 v[2:3], v[6:7], v[56:57], v[2:3] op_sel_hi:[1,0,1]
	v_mov_b32_e32 v4, v116
	v_mov_b32_e32 v5, v8
	v_pk_fma_f32 v[2:3], v[4:5], v[58:59], v[2:3] op_sel_hi:[1,0,1]
	v_mov_b32_e32 v8, v117
	v_pk_fma_f32 v[2:3], v[8:9], v[60:61], v[2:3] op_sel_hi:[1,0,1]
	v_mov_b32_e32 v4, v18
	v_mov_b32_e32 v5, v14
	v_pk_fma_f32 v[2:3], v[4:5], v[62:63], v[2:3] op_sel_hi:[1,0,1]
	v_mov_b32_e32 v14, v19
	v_pk_fma_f32 v[2:3], v[14:15], v[64:65], v[2:3] op_sel_hi:[1,0,1]
	v_mov_b32_e32 v4, v20
	v_mov_b32_e32 v5, v16
	global_load_dwordx2 v[12:13], v21, s[0:1] offset:1144
	v_pk_fma_f32 v[2:3], v[4:5], v[66:67], v[2:3] op_sel_hi:[1,0,1]
	global_load_dwordx2 v[4:5], v21, s[0:1] offset:1656
	s_waitcnt vmcnt(1)
	v_mov_b32_e32 v6, v12
	s_waitcnt vmcnt(0)
	v_mov_b32_e32 v7, v4
	v_pk_fma_f32 v[2:3], v[6:7], v[44:45], v[2:3] op_sel_hi:[1,0,1]
	v_mov_b32_e32 v4, v13
	v_pk_fma_f32 v[40:41], v[4:5], v[46:47], v[2:3] op_sel_hi:[1,0,1]
	global_load_dwordx4 v[2:5], v21, s[0:1] offset:2080
	global_load_dwordx3 v[10:12], v21, s[0:1] offset:2096
	global_load_dwordx4 v[6:9], v21, s[0:1] offset:2064
	global_load_dwordx4 v[14:17], v21, s[0:1] offset:2048
	global_load_dwordx4 v[110:113], v21, s[0:1] offset:2124
	global_load_dwordx3 v[18:20], v21, s[0:1] offset:2156
	global_load_dwordx4 v[114:117], v21, s[0:1] offset:2140
	global_load_dwordx4 v[118:121], v21, s[0:1] offset:2108
	global_load_dwordx4 v[122:125], v21, s[0:1] offset:2592
	global_load_dwordx3 v[22:24], v21, s[0:1] offset:2608
	global_load_dwordx4 v[126:129], v21, s[0:1] offset:2576
	global_load_dwordx4 v[130:133], v21, s[0:1] offset:2560
	s_waitcnt vmcnt(8)
	v_mov_b32_e32 v134, v14
	s_waitcnt vmcnt(0)
	v_mov_b32_e32 v135, v130
	v_pk_fma_f32 v[38:39], v[134:135], v[68:69], v[38:39] op_sel_hi:[1,0,1]
	v_mov_b32_e32 v130, v15
	v_pk_fma_f32 v[14:15], v[130:131], v[70:71], v[38:39] op_sel_hi:[1,0,1]
	v_mov_b32_e32 v38, v16
	v_mov_b32_e32 v39, v132
	v_pk_fma_f32 v[14:15], v[38:39], v[72:73], v[14:15] op_sel_hi:[1,0,1]
	v_mov_b32_e32 v132, v17
	v_pk_fma_f32 v[14:15], v[132:133], v[74:75], v[14:15] op_sel_hi:[1,0,1]
	v_mov_b32_e32 v16, v6
	v_mov_b32_e32 v17, v126
	v_pk_fma_f32 v[14:15], v[16:17], v[76:77], v[14:15] op_sel_hi:[1,0,1]
	v_mov_b32_e32 v126, v7
	v_pk_fma_f32 v[6:7], v[126:127], v[78:79], v[14:15] op_sel_hi:[1,0,1]
	v_mov_b32_e32 v14, v8
	v_mov_b32_e32 v15, v128
	v_pk_fma_f32 v[6:7], v[14:15], v[80:81], v[6:7] op_sel_hi:[1,0,1]
	v_mov_b32_e32 v128, v9
	v_pk_fma_f32 v[6:7], v[128:129], v[82:83], v[6:7] op_sel_hi:[1,0,1]
	v_mov_b32_e32 v8, v2
	v_mov_b32_e32 v9, v122
	v_pk_fma_f32 v[6:7], v[8:9], v[84:85], v[6:7] op_sel_hi:[1,0,1]
	v_mov_b32_e32 v122, v3
	v_pk_fma_f32 v[2:3], v[122:123], v[86:87], v[6:7] op_sel_hi:[1,0,1]
	v_mov_b32_e32 v6, v4
	v_mov_b32_e32 v7, v124
	v_pk_fma_f32 v[2:3], v[6:7], v[88:89], v[2:3] op_sel_hi:[1,0,1]
	v_mov_b32_e32 v124, v5
	v_pk_fma_f32 v[2:3], v[124:125], v[90:91], v[2:3] op_sel_hi:[1,0,1]
	v_mov_b32_e32 v4, v10
	v_mov_b32_e32 v5, v22
	v_pk_fma_f32 v[2:3], v[4:5], v[92:93], v[2:3] op_sel_hi:[1,0,1]
	v_mov_b32_e32 v22, v11
	v_pk_fma_f32 v[2:3], v[22:23], v[94:95], v[2:3] op_sel_hi:[1,0,1]
	v_mov_b32_e32 v4, v12
	v_mov_b32_e32 v5, v24
	v_pk_fma_f32 v[22:23], v[4:5], v[96:97], v[2:3] op_sel_hi:[1,0,1]
	global_load_dwordx4 v[2:5], v21, s[0:1] offset:2636
	global_load_dwordx3 v[14:16], v21, s[0:1] offset:2668
	global_load_dwordx4 v[6:9], v21, s[0:1] offset:2652
	global_load_dwordx4 v[10:13], v21, s[0:1] offset:2620
	v_mov_b32_e32 v38, v118
	s_waitcnt vmcnt(0)
; __global__ void __launch_bounds__(NTH, 2) mega(Params p) {
;     ...
;                 for (int q = 0; q < 16; ++q)
; #pragma unroll
;                     for (int c = 0; c < 32; ++c) acc16[q] += wp[q * 128 + c0 + c] * wv[c];
	v_mov_b32_e32 v39, v10
	v_pk_fma_f32 v[22:23], v[38:39], v[98:99], v[22:23] op_sel_hi:[1,0,1]
	v_mov_b32_e32 v10, v119
	v_pk_fma_f32 v[10:11], v[10:11], v[100:101], v[22:23] op_sel_hi:[1,0,1]
	v_mov_b32_e32 v22, v120
	v_mov_b32_e32 v23, v12
	v_pk_fma_f32 v[10:11], v[22:23], v[102:103], v[10:11] op_sel_hi:[1,0,1]
	v_mov_b32_e32 v12, v121
	v_pk_fma_f32 v[10:11], v[12:13], v[104:105], v[10:11] op_sel_hi:[1,0,1]
	v_mov_b32_e32 v12, v110
	v_mov_b32_e32 v13, v2
	v_pk_fma_f32 v[10:11], v[12:13], v[106:107], v[10:11] op_sel_hi:[1,0,1]
	v_mov_b32_e32 v2, v111
	v_pk_fma_f32 v[2:3], v[2:3], v[108:109], v[10:11] op_sel_hi:[1,0,1]
	v_mov_b32_e32 v10, v112
	v_mov_b32_e32 v11, v4
	v_pk_fma_f32 v[2:3], v[10:11], v[50:51], v[2:3] op_sel_hi:[1,0,1]
	v_mov_b32_e32 v4, v113
	v_pk_fma_f32 v[2:3], v[4:5], v[52:53], v[2:3] op_sel_hi:[1,0,1]
	v_mov_b32_e32 v4, v114
	v_mov_b32_e32 v5, v6
	v_pk_fma_f32 v[2:3], v[4:5], v[54:55], v[2:3] op_sel_hi:[1,0,1]
	v_mov_b32_e32 v6, v115
	v_pk_fma_f32 v[2:3], v[6:7], v[56:57], v[2:3] op_sel_hi:[1,0,1]
	v_mov_b32_e32 v4, v116
	v_mov_b32_e32 v5, v8
	v_pk_fma_f32 v[2:3], v[4:5], v[58:59], v[2:3] op_sel_hi:[1,0,1]
	v_mov_b32_e32 v8, v117
	v_pk_fma_f32 v[2:3], v[8:9], v[60:61], v[2:3] op_sel_hi:[1,0,1]
	v_mov_b32_e32 v4, v18
	v_mov_b32_e32 v5, v14
	v_pk_fma_f32 v[2:3], v[4:5], v[62:63], v[2:3] op_sel_hi:[1,0,1]
	v_mov_b32_e32 v14, v19
	v_pk_fma_f32 v[2:3], v[14:15], v[64:65], v[2:3] op_sel_hi:[1,0,1]
	v_mov_b32_e32 v4, v20
	v_mov_b32_e32 v5, v16
	global_load_dwordx2 v[12:13], v21, s[0:1] offset:2168
	v_pk_fma_f32 v[2:3], v[4:5], v[66:67], v[2:3] op_sel_hi:[1,0,1]
	global_load_dwordx2 v[4:5], v21, s[0:1] offset:2680
	s_waitcnt vmcnt(1)
	v_mov_b32_e32 v6, v12
	s_waitcnt vmcnt(0)
	v_mov_b32_e32 v7, v4
	v_pk_fma_f32 v[2:3], v[6:7], v[44:45], v[2:3] op_sel_hi:[1,0,1]
	v_mov_b32_e32 v4, v13
	v_pk_fma_f32 v[38:39], v[4:5], v[46:47], v[2:3] op_sel_hi:[1,0,1]
	global_load_dwordx4 v[2:5], v21, s[0:1] offset:3104
	global_load_dwordx3 v[10:12], v21, s[0:1] offset:3120
	global_load_dwordx4 v[6:9], v21, s[0:1] offset:3088
	global_load_dwordx4 v[14:17], v21, s[0:1] offset:3072
	global_load_dwordx4 v[110:113], v21, s[0:1] offset:3148
	global_load_dwordx3 v[18:20], v21, s[0:1] offset:3180
	global_load_dwordx4 v[114:117], v21, s[0:1] offset:3164
	global_load_dwordx4 v[118:121], v21, s[0:1] offset:3132
	global_load_dwordx4 v[122:125], v21, s[0:1] offset:3616
	global_load_dwordx3 v[22:24], v21, s[0:1] offset:3632
	global_load_dwordx4 v[126:129], v21, s[0:1] offset:3600
	global_load_dwordx4 v[130:133], v21, s[0:1] offset:3584
	s_waitcnt vmcnt(8)
	v_mov_b32_e32 v134, v14
	s_waitcnt vmcnt(0)
	v_mov_b32_e32 v135, v130
	v_pk_fma_f32 v[36:37], v[134:135], v[68:69], v[36:37] op_sel_hi:[1,0,1]
	v_mov_b32_e32 v130, v15
	v_pk_fma_f32 v[14:15], v[130:131], v[70:71], v[36:37] op_sel_hi:[1,0,1]
	v_mov_b32_e32 v36, v16
	v_mov_b32_e32 v37, v132
	v_pk_fma_f32 v[14:15], v[36:37], v[72:73], v[14:15] op_sel_hi:[1,0,1]
	v_mov_b32_e32 v132, v17
	v_pk_fma_f32 v[14:15], v[132:133], v[74:75], v[14:15] op_sel_hi:[1,0,1]
	v_mov_b32_e32 v16, v6
	v_mov_b32_e32 v17, v126
	v_pk_fma_f32 v[14:15], v[16:17], v[76:77], v[14:15] op_sel_hi:[1,0,1]
	v_mov_b32_e32 v126, v7
	v_pk_fma_f32 v[6:7], v[126:127], v[78:79], v[14:15] op_sel_hi:[1,0,1]
	v_mov_b32_e32 v14, v8
	v_mov_b32_e32 v15, v128
	v_pk_fma_f32 v[6:7], v[14:15], v[80:81], v[6:7] op_sel_hi:[1,0,1]
	v_mov_b32_e32 v128, v9
	v_pk_fma_f32 v[6:7], v[128:129], v[82:83], v[6:7] op_sel_hi:[1,0,1]
	v_mov_b32_e32 v8, v2
	v_mov_b32_e32 v9, v122
	v_pk_fma_f32 v[6:7], v[8:9], v[84:85], v[6:7] op_sel_hi:[1,0,1]
	v_mov_b32_e32 v122, v3
	v_pk_fma_f32 v[2:3], v[122:123], v[86:87], v[6:7] op_sel_hi:[1,0,1]
	v_mov_b32_e32 v6, v4
	v_mov_b32_e32 v7, v124
	v_pk_fma_f32 v[2:3], v[6:7], v[88:89], v[2:3] op_sel_hi:[1,0,1]
	v_mov_b32_e32 v124, v5
	v_pk_fma_f32 v[2:3], v[124:125], v[90:91], v[2:3] op_sel_hi:[1,0,1]
	v_mov_b32_e32 v4, v10
	v_mov_b32_e32 v5, v22
	v_pk_fma_f32 v[2:3], v[4:5], v[92:93], v[2:3] op_sel_hi:[1,0,1]
	v_mov_b32_e32 v22, v11
	v_pk_fma_f32 v[2:3], v[22:23], v[94:95], v[2:3] op_sel_hi:[1,0,1]
	v_mov_b32_e32 v4, v12
	v_mov_b32_e32 v5, v24
	v_pk_fma_f32 v[22:23], v[4:5], v[96:97], v[2:3] op_sel_hi:[1,0,1]
	global_load_dwordx4 v[2:5], v21, s[0:1] offset:3660
	global_load_dwordx3 v[14:16], v21, s[0:1] offset:3692
	global_load_dwordx4 v[6:9], v21, s[0:1] offset:3676
	global_load_dwordx4 v[10:13], v21, s[0:1] offset:3644
	v_mov_b32_e32 v36, v118
	s_waitcnt vmcnt(0)
	v_mov_b32_e32 v37, v10
	v_pk_fma_f32 v[22:23], v[36:37], v[98:99], v[22:23] op_sel_hi:[1,0,1]
	v_mov_b32_e32 v10, v119
	v_pk_fma_f32 v[10:11], v[10:11], v[100:101], v[22:23] op_sel_hi:[1,0,1]
	v_mov_b32_e32 v22, v120
	v_mov_b32_e32 v23, v12
	v_pk_fma_f32 v[10:11], v[22:23], v[102:103], v[10:11] op_sel_hi:[1,0,1]
	v_mov_b32_e32 v12, v121
	v_pk_fma_f32 v[10:11], v[12:13], v[104:105], v[10:11] op_sel_hi:[1,0,1]
	v_mov_b32_e32 v12, v110
	v_mov_b32_e32 v13, v2
	v_pk_fma_f32 v[10:11], v[12:13], v[106:107], v[10:11] op_sel_hi:[1,0,1]
	v_mov_b32_e32 v2, v111
	v_pk_fma_f32 v[2:3], v[2:3], v[108:109], v[10:11] op_sel_hi:[1,0,1]
	v_mov_b32_e32 v10, v112
	v_mov_b32_e32 v11, v4
	v_pk_fma_f32 v[2:3], v[10:11], v[50:51], v[2:3] op_sel_hi:[1,0,1]
	v_mov_b32_e32 v4, v113
	v_pk_fma_f32 v[2:3], v[4:5], v[52:53], v[2:3] op_sel_hi:[1,0,1]
	v_mov_b32_e32 v4, v114
	v_mov_b32_e32 v5, v6
	v_pk_fma_f32 v[2:3], v[4:5], v[54:55], v[2:3] op_sel_hi:[1,0,1]
	v_mov_b32_e32 v6, v115
	v_pk_fma_f32 v[2:3], v[6:7], v[56:57], v[2:3] op_sel_hi:[1,0,1]
	v_mov_b32_e32 v4, v116
	v_mov_b32_e32 v5, v8
	v_pk_fma_f32 v[2:3], v[4:5], v[58:59], v[2:3] op_sel_hi:[1,0,1]
	v_mov_b32_e32 v8, v117
	v_pk_fma_f32 v[2:3], v[8:9], v[60:61], v[2:3] op_sel_hi:[1,0,1]
	v_mov_b32_e32 v4, v18
	v_mov_b32_e32 v5, v14
	v_pk_fma_f32 v[2:3], v[4:5], v[62:63], v[2:3] op_sel_hi:[1,0,1]
	v_mov_b32_e32 v14, v19
	v_pk_fma_f32 v[2:3], v[14:15], v[64:65], v[2:3] op_sel_hi:[1,0,1]
	v_mov_b32_e32 v4, v20
	v_mov_b32_e32 v5, v16
	global_load_dwordx2 v[12:13], v21, s[0:1] offset:3192
	v_pk_fma_f32 v[2:3], v[4:5], v[66:67], v[2:3] op_sel_hi:[1,0,1]
	global_load_dwordx2 v[4:5], v21, s[0:1] offset:3704
	s_waitcnt vmcnt(1)
; __global__ void __launch_bounds__(NTH, 2) mega(Params p) {
;     ...
;                 for (int q = 0; q < 16; ++q)
; #pragma unroll
;                     for (int c = 0; c < 32; ++c) acc16[q] += wp[q * 128 + c0 + c] * wv[c];
	v_mov_b32_e32 v6, v12
	s_waitcnt vmcnt(0)
	v_mov_b32_e32 v7, v4
	v_pk_fma_f32 v[2:3], v[6:7], v[44:45], v[2:3] op_sel_hi:[1,0,1]
	v_mov_b32_e32 v4, v13
	v_pk_fma_f32 v[36:37], v[4:5], v[46:47], v[2:3] op_sel_hi:[1,0,1]
	global_load_dwordx4 v[2:5], v21, s[12:13] offset:32
	global_load_dwordx3 v[10:12], v21, s[12:13] offset:48
	global_load_dwordx4 v[6:9], v21, s[12:13] offset:16
	global_load_dwordx4 v[14:17], v25, s[0:1]
	s_add_u32 s12, s0, 0x103c
	s_addc_u32 s13, s1, 0
	global_load_dwordx4 v[110:113], v21, s[12:13] offset:16
	global_load_dwordx3 v[18:20], v21, s[12:13] offset:48
	global_load_dwordx4 v[114:117], v21, s[12:13] offset:32
	global_load_dwordx4 v[118:121], v25, s[0:1] offset:60
	s_add_u32 s12, s0, 0x1200
	s_addc_u32 s13, s1, 0
	global_load_dwordx4 v[122:125], v21, s[12:13] offset:32
	global_load_dwordx3 v[22:24], v21, s[12:13] offset:48
	global_load_dwordx4 v[126:129], v21, s[12:13] offset:16
	global_load_dwordx4 v[130:133], v25, s[0:1] offset:512
	s_add_u32 s12, s0, 0x123c
	s_addc_u32 s13, s1, 0
	s_waitcnt vmcnt(8)
	v_mov_b32_e32 v134, v14
	s_waitcnt vmcnt(0)
	v_mov_b32_e32 v135, v130
	v_pk_fma_f32 v[34:35], v[134:135], v[68:69], v[34:35] op_sel_hi:[1,0,1]
	v_mov_b32_e32 v130, v15
	v_pk_fma_f32 v[14:15], v[130:131], v[70:71], v[34:35] op_sel_hi:[1,0,1]
	v_mov_b32_e32 v34, v16
	v_mov_b32_e32 v35, v132
	v_pk_fma_f32 v[14:15], v[34:35], v[72:73], v[14:15] op_sel_hi:[1,0,1]
	v_mov_b32_e32 v132, v17
	v_pk_fma_f32 v[14:15], v[132:133], v[74:75], v[14:15] op_sel_hi:[1,0,1]
	v_mov_b32_e32 v16, v6
	v_mov_b32_e32 v17, v126
	v_pk_fma_f32 v[14:15], v[16:17], v[76:77], v[14:15] op_sel_hi:[1,0,1]
	v_mov_b32_e32 v126, v7
	v_pk_fma_f32 v[6:7], v[126:127], v[78:79], v[14:15] op_sel_hi:[1,0,1]
	v_mov_b32_e32 v14, v8
	v_mov_b32_e32 v15, v128
	v_pk_fma_f32 v[6:7], v[14:15], v[80:81], v[6:7] op_sel_hi:[1,0,1]
	v_mov_b32_e32 v128, v9
	v_pk_fma_f32 v[6:7], v[128:129], v[82:83], v[6:7] op_sel_hi:[1,0,1]
	v_mov_b32_e32 v8, v2
	v_mov_b32_e32 v9, v122
	v_pk_fma_f32 v[6:7], v[8:9], v[84:85], v[6:7] op_sel_hi:[1,0,1]
	v_mov_b32_e32 v122, v3
	v_pk_fma_f32 v[2:3], v[122:123], v[86:87], v[6:7] op_sel_hi:[1,0,1]
	v_mov_b32_e32 v6, v4
	v_mov_b32_e32 v7, v124
	v_pk_fma_f32 v[2:3], v[6:7], v[88:89], v[2:3] op_sel_hi:[1,0,1]
	v_mov_b32_e32 v124, v5
	v_pk_fma_f32 v[2:3], v[124:125], v[90:91], v[2:3] op_sel_hi:[1,0,1]
	v_mov_b32_e32 v4, v10
	v_mov_b32_e32 v5, v22
	v_pk_fma_f32 v[2:3], v[4:5], v[92:93], v[2:3] op_sel_hi:[1,0,1]
	v_mov_b32_e32 v22, v11
	v_pk_fma_f32 v[2:3], v[22:23], v[94:95], v[2:3] op_sel_hi:[1,0,1]
	v_mov_b32_e32 v4, v12
	v_mov_b32_e32 v5, v24
	v_pk_fma_f32 v[22:23], v[4:5], v[96:97], v[2:3] op_sel_hi:[1,0,1]
	global_load_dwordx4 v[2:5], v21, s[12:13] offset:16
	global_load_dwordx3 v[14:16], v21, s[12:13] offset:48
	global_load_dwordx4 v[6:9], v21, s[12:13] offset:32
	global_load_dwordx4 v[10:13], v25, s[0:1] offset:572
	v_mov_b32_e32 v34, v118
	s_add_u32 s12, s0, 0x1400
	s_addc_u32 s13, s1, 0
	s_waitcnt vmcnt(0)
	v_mov_b32_e32 v35, v10
	v_pk_fma_f32 v[22:23], v[34:35], v[98:99], v[22:23] op_sel_hi:[1,0,1]
	v_mov_b32_e32 v10, v119
	v_pk_fma_f32 v[10:11], v[10:11], v[100:101], v[22:23] op_sel_hi:[1,0,1]
	v_mov_b32_e32 v22, v120
	v_mov_b32_e32 v23, v12
	v_pk_fma_f32 v[10:11], v[22:23], v[102:103], v[10:11] op_sel_hi:[1,0,1]
	v_mov_b32_e32 v12, v121
	v_pk_fma_f32 v[10:11], v[12:13], v[104:105], v[10:11] op_sel_hi:[1,0,1]
	v_mov_b32_e32 v12, v110
	v_mov_b32_e32 v13, v2
	v_pk_fma_f32 v[10:11], v[12:13], v[106:107], v[10:11] op_sel_hi:[1,0,1]
	v_mov_b32_e32 v2, v111
	v_pk_fma_f32 v[2:3], v[2:3], v[108:109], v[10:11] op_sel_hi:[1,0,1]
	v_mov_b32_e32 v10, v112
	v_mov_b32_e32 v11, v4
	v_pk_fma_f32 v[2:3], v[10:11], v[50:51], v[2:3] op_sel_hi:[1,0,1]
	v_mov_b32_e32 v4, v113
	v_pk_fma_f32 v[2:3], v[4:5], v[52:53], v[2:3] op_sel_hi:[1,0,1]
	v_mov_b32_e32 v4, v114
	v_mov_b32_e32 v5, v6
	v_pk_fma_f32 v[2:3], v[4:5], v[54:55], v[2:3] op_sel_hi:[1,0,1]
	v_mov_b32_e32 v6, v115
	v_pk_fma_f32 v[2:3], v[6:7], v[56:57], v[2:3] op_sel_hi:[1,0,1]
	v_mov_b32_e32 v4, v116
	v_mov_b32_e32 v5, v8
	v_pk_fma_f32 v[2:3], v[4:5], v[58:59], v[2:3] op_sel_hi:[1,0,1]
	v_mov_b32_e32 v8, v117
	v_pk_fma_f32 v[2:3], v[8:9], v[60:61], v[2:3] op_sel_hi:[1,0,1]
	v_mov_b32_e32 v4, v18
	v_mov_b32_e32 v5, v14
	v_pk_fma_f32 v[2:3], v[4:5], v[62:63], v[2:3] op_sel_hi:[1,0,1]
	v_mov_b32_e32 v14, v19
	v_pk_fma_f32 v[2:3], v[14:15], v[64:65], v[2:3] op_sel_hi:[1,0,1]
	v_mov_b32_e32 v4, v20
	v_mov_b32_e32 v5, v16
	global_load_dwordx2 v[12:13], v25, s[0:1] offset:120
	v_pk_fma_f32 v[2:3], v[4:5], v[66:67], v[2:3] op_sel_hi:[1,0,1]
	global_load_dwordx2 v[4:5], v25, s[0:1] offset:632
	s_waitcnt vmcnt(1)
	v_mov_b32_e32 v6, v12
	s_waitcnt vmcnt(0)
	v_mov_b32_e32 v7, v4
	v_pk_fma_f32 v[2:3], v[6:7], v[44:45], v[2:3] op_sel_hi:[1,0,1]
	v_mov_b32_e32 v4, v13
	v_pk_fma_f32 v[34:35], v[4:5], v[46:47], v[2:3] op_sel_hi:[1,0,1]
	global_load_dwordx4 v[2:5], v21, s[12:13] offset:32
	global_load_dwordx3 v[10:12], v21, s[12:13] offset:48
	global_load_dwordx4 v[6:9], v21, s[12:13] offset:16
	global_load_dwordx4 v[14:17], v25, s[0:1] offset:1024
	s_add_u32 s12, s0, 0x143c
	s_addc_u32 s13, s1, 0
	global_load_dwordx4 v[110:113], v21, s[12:13] offset:16
	global_load_dwordx3 v[18:20], v21, s[12:13] offset:48
	global_load_dwordx4 v[114:117], v21, s[12:13] offset:32
	global_load_dwordx4 v[118:121], v25, s[0:1] offset:1084
	s_add_u32 s12, s0, 0x1600
	s_addc_u32 s13, s1, 0
	global_load_dwordx4 v[122:125], v21, s[12:13] offset:32
	global_load_dwordx3 v[22:24], v21, s[12:13] offset:48
	global_load_dwordx4 v[126:129], v21, s[12:13] offset:16
	global_load_dwordx4 v[130:133], v25, s[0:1] offset:1536
	s_add_u32 s12, s0, 0x163c
	s_addc_u32 s13, s1, 0
	s_waitcnt vmcnt(8)
; __global__ void __launch_bounds__(NTH, 2) mega(Params p) {
;     ...
;                 for (int q = 0; q < 16; ++q)
; #pragma unroll
;                     for (int c = 0; c < 32; ++c) acc16[q] += wp[q * 128 + c0 + c] * wv[c];
	v_mov_b32_e32 v134, v14
	s_waitcnt vmcnt(0)
	v_mov_b32_e32 v135, v130
	v_pk_fma_f32 v[32:33], v[134:135], v[68:69], v[32:33] op_sel_hi:[1,0,1]
	v_mov_b32_e32 v130, v15
	v_pk_fma_f32 v[14:15], v[130:131], v[70:71], v[32:33] op_sel_hi:[1,0,1]
	v_mov_b32_e32 v32, v16
	v_mov_b32_e32 v33, v132
	v_pk_fma_f32 v[14:15], v[32:33], v[72:73], v[14:15] op_sel_hi:[1,0,1]
	v_mov_b32_e32 v132, v17
	v_pk_fma_f32 v[14:15], v[132:133], v[74:75], v[14:15] op_sel_hi:[1,0,1]
	v_mov_b32_e32 v16, v6
	v_mov_b32_e32 v17, v126
	v_pk_fma_f32 v[14:15], v[16:17], v[76:77], v[14:15] op_sel_hi:[1,0,1]
	v_mov_b32_e32 v126, v7
	v_pk_fma_f32 v[6:7], v[126:127], v[78:79], v[14:15] op_sel_hi:[1,0,1]
	v_mov_b32_e32 v14, v8
	v_mov_b32_e32 v15, v128
	v_pk_fma_f32 v[6:7], v[14:15], v[80:81], v[6:7] op_sel_hi:[1,0,1]
	v_mov_b32_e32 v128, v9
	v_pk_fma_f32 v[6:7], v[128:129], v[82:83], v[6:7] op_sel_hi:[1,0,1]
	v_mov_b32_e32 v8, v2
	v_mov_b32_e32 v9, v122
	v_pk_fma_f32 v[6:7], v[8:9], v[84:85], v[6:7] op_sel_hi:[1,0,1]
	v_mov_b32_e32 v122, v3
	v_pk_fma_f32 v[2:3], v[122:123], v[86:87], v[6:7] op_sel_hi:[1,0,1]
	v_mov_b32_e32 v6, v4
	v_mov_b32_e32 v7, v124
	v_pk_fma_f32 v[2:3], v[6:7], v[88:89], v[2:3] op_sel_hi:[1,0,1]
	v_mov_b32_e32 v124, v5
	v_pk_fma_f32 v[2:3], v[124:125], v[90:91], v[2:3] op_sel_hi:[1,0,1]
	v_mov_b32_e32 v4, v10
	v_mov_b32_e32 v5, v22
	v_pk_fma_f32 v[2:3], v[4:5], v[92:93], v[2:3] op_sel_hi:[1,0,1]
	v_mov_b32_e32 v22, v11
	v_pk_fma_f32 v[2:3], v[22:23], v[94:95], v[2:3] op_sel_hi:[1,0,1]
	v_mov_b32_e32 v4, v12
	v_mov_b32_e32 v5, v24
	v_pk_fma_f32 v[22:23], v[4:5], v[96:97], v[2:3] op_sel_hi:[1,0,1]
	global_load_dwordx4 v[2:5], v21, s[12:13] offset:16
	global_load_dwordx3 v[14:16], v21, s[12:13] offset:48
	global_load_dwordx4 v[6:9], v21, s[12:13] offset:32
	global_load_dwordx4 v[10:13], v25, s[0:1] offset:1596
	v_mov_b32_e32 v32, v118
	s_add_u32 s12, s0, 0x1800
	s_addc_u32 s13, s1, 0
	s_waitcnt vmcnt(0)
	v_mov_b32_e32 v33, v10
	v_pk_fma_f32 v[22:23], v[32:33], v[98:99], v[22:23] op_sel_hi:[1,0,1]
	v_mov_b32_e32 v10, v119
	v_pk_fma_f32 v[10:11], v[10:11], v[100:101], v[22:23] op_sel_hi:[1,0,1]
	v_mov_b32_e32 v22, v120
	v_mov_b32_e32 v23, v12
	v_pk_fma_f32 v[10:11], v[22:23], v[102:103], v[10:11] op_sel_hi:[1,0,1]
	v_mov_b32_e32 v12, v121
	v_pk_fma_f32 v[10:11], v[12:13], v[104:105], v[10:11] op_sel_hi:[1,0,1]
	v_mov_b32_e32 v12, v110
	v_mov_b32_e32 v13, v2
	v_pk_fma_f32 v[10:11], v[12:13], v[106:107], v[10:11] op_sel_hi:[1,0,1]
	v_mov_b32_e32 v2, v111
	v_pk_fma_f32 v[2:3], v[2:3], v[108:109], v[10:11] op_sel_hi:[1,0,1]
	v_mov_b32_e32 v10, v112
	v_mov_b32_e32 v11, v4
	v_pk_fma_f32 v[2:3], v[10:11], v[50:51], v[2:3] op_sel_hi:[1,0,1]
	v_mov_b32_e32 v4, v113
	v_pk_fma_f32 v[2:3], v[4:5], v[52:53], v[2:3] op_sel_hi:[1,0,1]
	v_mov_b32_e32 v4, v114
	v_mov_b32_e32 v5, v6
	v_pk_fma_f32 v[2:3], v[4:5], v[54:55], v[2:3] op_sel_hi:[1,0,1]
	v_mov_b32_e32 v6, v115
	v_pk_fma_f32 v[2:3], v[6:7], v[56:57], v[2:3] op_sel_hi:[1,0,1]
	v_mov_b32_e32 v4, v116
	v_mov_b32_e32 v5, v8
	v_pk_fma_f32 v[2:3], v[4:5], v[58:59], v[2:3] op_sel_hi:[1,0,1]
	v_mov_b32_e32 v8, v117
	v_pk_fma_f32 v[2:3], v[8:9], v[60:61], v[2:3] op_sel_hi:[1,0,1]
	v_mov_b32_e32 v4, v18
	v_mov_b32_e32 v5, v14
	v_pk_fma_f32 v[2:3], v[4:5], v[62:63], v[2:3] op_sel_hi:[1,0,1]
	v_mov_b32_e32 v14, v19
	v_pk_fma_f32 v[2:3], v[14:15], v[64:65], v[2:3] op_sel_hi:[1,0,1]
	v_mov_b32_e32 v4, v20
	v_mov_b32_e32 v5, v16
	global_load_dwordx2 v[12:13], v25, s[0:1] offset:1144
	v_pk_fma_f32 v[2:3], v[4:5], v[66:67], v[2:3] op_sel_hi:[1,0,1]
	global_load_dwordx2 v[4:5], v25, s[0:1] offset:1656
	s_waitcnt vmcnt(1)
	v_mov_b32_e32 v6, v12
	s_waitcnt vmcnt(0)
	v_mov_b32_e32 v7, v4
	v_pk_fma_f32 v[2:3], v[6:7], v[44:45], v[2:3] op_sel_hi:[1,0,1]
	v_mov_b32_e32 v4, v13
	v_pk_fma_f32 v[32:33], v[4:5], v[46:47], v[2:3] op_sel_hi:[1,0,1]
	global_load_dwordx4 v[2:5], v21, s[12:13] offset:32
	global_load_dwordx3 v[10:12], v21, s[12:13] offset:48
	global_load_dwordx4 v[6:9], v21, s[12:13] offset:16
	global_load_dwordx4 v[14:17], v25, s[0:1] offset:2048
	s_add_u32 s12, s0, 0x183c
	s_addc_u32 s13, s1, 0
	global_load_dwordx4 v[110:113], v21, s[12:13] offset:16
	global_load_dwordx3 v[18:20], v21, s[12:13] offset:48
	global_load_dwordx4 v[114:117], v21, s[12:13] offset:32
	global_load_dwordx4 v[118:121], v25, s[0:1] offset:2108
	s_add_u32 s12, s0, 0x1a00
	s_addc_u32 s13, s1, 0
	global_load_dwordx4 v[122:125], v21, s[12:13] offset:32
	global_load_dwordx3 v[22:24], v21, s[12:13] offset:48
	global_load_dwordx4 v[126:129], v21, s[12:13] offset:16
	global_load_dwordx4 v[130:133], v25, s[0:1] offset:2560
	s_add_u32 s12, s0, 0x1a3c
	s_addc_u32 s13, s1, 0
	s_waitcnt vmcnt(8)
	v_mov_b32_e32 v134, v14
	s_waitcnt vmcnt(0)
	v_mov_b32_e32 v135, v130
	v_pk_fma_f32 v[30:31], v[134:135], v[68:69], v[30:31] op_sel_hi:[1,0,1]
	v_mov_b32_e32 v130, v15
	v_pk_fma_f32 v[14:15], v[130:131], v[70:71], v[30:31] op_sel_hi:[1,0,1]
	v_mov_b32_e32 v30, v16
	v_mov_b32_e32 v31, v132
	v_pk_fma_f32 v[14:15], v[30:31], v[72:73], v[14:15] op_sel_hi:[1,0,1]
	v_mov_b32_e32 v132, v17
	v_pk_fma_f32 v[14:15], v[132:133], v[74:75], v[14:15] op_sel_hi:[1,0,1]
	v_mov_b32_e32 v16, v6
	v_mov_b32_e32 v17, v126
	v_pk_fma_f32 v[14:15], v[16:17], v[76:77], v[14:15] op_sel_hi:[1,0,1]
	v_mov_b32_e32 v126, v7
	v_pk_fma_f32 v[6:7], v[126:127], v[78:79], v[14:15] op_sel_hi:[1,0,1]
	v_mov_b32_e32 v14, v8
	v_mov_b32_e32 v15, v128
	v_pk_fma_f32 v[6:7], v[14:15], v[80:81], v[6:7] op_sel_hi:[1,0,1]
	v_mov_b32_e32 v128, v9
	v_pk_fma_f32 v[6:7], v[128:129], v[82:83], v[6:7] op_sel_hi:[1,0,1]
	v_mov_b32_e32 v8, v2
	v_mov_b32_e32 v9, v122
	v_pk_fma_f32 v[6:7], v[8:9], v[84:85], v[6:7] op_sel_hi:[1,0,1]
	v_mov_b32_e32 v122, v3
	v_pk_fma_f32 v[2:3], v[122:123], v[86:87], v[6:7] op_sel_hi:[1,0,1]
	v_mov_b32_e32 v6, v4
	v_mov_b32_e32 v7, v124
	v_pk_fma_f32 v[2:3], v[6:7], v[88:89], v[2:3] op_sel_hi:[1,0,1]
	v_mov_b32_e32 v124, v5
	v_pk_fma_f32 v[2:3], v[124:125], v[90:91], v[2:3] op_sel_hi:[1,0,1]
	v_mov_b32_e32 v4, v10
	v_mov_b32_e32 v5, v22
	v_pk_fma_f32 v[2:3], v[4:5], v[92:93], v[2:3] op_sel_hi:[1,0,1]
	v_mov_b32_e32 v22, v11
	v_pk_fma_f32 v[2:3], v[22:23], v[94:95], v[2:3] op_sel_hi:[1,0,1]
	v_mov_b32_e32 v4, v12
	v_mov_b32_e32 v5, v24
	v_pk_fma_f32 v[22:23], v[4:5], v[96:97], v[2:3] op_sel_hi:[1,0,1]
	global_load_dwordx4 v[2:5], v21, s[12:13] offset:16
	global_load_dwordx3 v[14:16], v21, s[12:13] offset:48
	global_load_dwordx4 v[6:9], v21, s[12:13] offset:32
	global_load_dwordx4 v[10:13], v25, s[0:1] offset:2620
	v_mov_b32_e32 v30, v118
	s_add_u32 s12, s0, 0x1c00
	s_addc_u32 s13, s1, 0
	s_waitcnt vmcnt(0)
; __global__ void __launch_bounds__(NTH, 2) mega(Params p) {
;     ...
;                 for (int q = 0; q < 16; ++q)
; #pragma unroll
;                     for (int c = 0; c < 32; ++c) acc16[q] += wp[q * 128 + c0 + c] * wv[c];
	v_mov_b32_e32 v31, v10
	v_pk_fma_f32 v[22:23], v[30:31], v[98:99], v[22:23] op_sel_hi:[1,0,1]
	v_mov_b32_e32 v10, v119
	v_pk_fma_f32 v[10:11], v[10:11], v[100:101], v[22:23] op_sel_hi:[1,0,1]
	v_mov_b32_e32 v22, v120
	v_mov_b32_e32 v23, v12
	v_pk_fma_f32 v[10:11], v[22:23], v[102:103], v[10:11] op_sel_hi:[1,0,1]
	v_mov_b32_e32 v12, v121
	v_pk_fma_f32 v[10:11], v[12:13], v[104:105], v[10:11] op_sel_hi:[1,0,1]
	v_mov_b32_e32 v12, v110
	v_mov_b32_e32 v13, v2
	v_pk_fma_f32 v[10:11], v[12:13], v[106:107], v[10:11] op_sel_hi:[1,0,1]
	v_mov_b32_e32 v2, v111
	v_pk_fma_f32 v[2:3], v[2:3], v[108:109], v[10:11] op_sel_hi:[1,0,1]
	v_mov_b32_e32 v10, v112
	v_mov_b32_e32 v11, v4
	v_pk_fma_f32 v[2:3], v[10:11], v[50:51], v[2:3] op_sel_hi:[1,0,1]
	v_mov_b32_e32 v4, v113
	v_pk_fma_f32 v[2:3], v[4:5], v[52:53], v[2:3] op_sel_hi:[1,0,1]
	v_mov_b32_e32 v4, v114
	v_mov_b32_e32 v5, v6
	v_pk_fma_f32 v[2:3], v[4:5], v[54:55], v[2:3] op_sel_hi:[1,0,1]
	v_mov_b32_e32 v6, v115
	v_pk_fma_f32 v[2:3], v[6:7], v[56:57], v[2:3] op_sel_hi:[1,0,1]
	v_mov_b32_e32 v4, v116
	v_mov_b32_e32 v5, v8
	v_pk_fma_f32 v[2:3], v[4:5], v[58:59], v[2:3] op_sel_hi:[1,0,1]
	v_mov_b32_e32 v8, v117
	v_pk_fma_f32 v[2:3], v[8:9], v[60:61], v[2:3] op_sel_hi:[1,0,1]
	v_mov_b32_e32 v4, v18
	v_mov_b32_e32 v5, v14
	v_pk_fma_f32 v[2:3], v[4:5], v[62:63], v[2:3] op_sel_hi:[1,0,1]
	v_mov_b32_e32 v14, v19
	v_pk_fma_f32 v[2:3], v[14:15], v[64:65], v[2:3] op_sel_hi:[1,0,1]
	v_mov_b32_e32 v4, v20
	v_mov_b32_e32 v5, v16
	global_load_dwordx2 v[12:13], v25, s[0:1] offset:2168
	v_pk_fma_f32 v[2:3], v[4:5], v[66:67], v[2:3] op_sel_hi:[1,0,1]
	global_load_dwordx2 v[4:5], v25, s[0:1] offset:2680
	s_waitcnt vmcnt(1)
	v_mov_b32_e32 v6, v12
	s_waitcnt vmcnt(0)
	v_mov_b32_e32 v7, v4
	v_mov_b32_e32 v4, v13
	global_load_dwordx4 v[10:13], v21, s[12:13] offset:32
	global_load_dwordx3 v[22:24], v21, s[12:13] offset:48
	global_load_dwordx4 v[14:17], v21, s[12:13] offset:16
	global_load_dwordx4 v[110:113], v25, s[0:1] offset:3072
	s_add_u32 s12, s0, 0x1c3c
	v_pk_fma_f32 v[2:3], v[6:7], v[44:45], v[2:3] op_sel_hi:[1,0,1]
	s_addc_u32 s13, s1, 0
	v_pk_fma_f32 v[30:31], v[4:5], v[46:47], v[2:3] op_sel_hi:[1,0,1]
	global_load_dwordx4 v[6:9], v21, s[12:13] offset:16
	global_load_dwordx3 v[18:20], v21, s[12:13] offset:48
	global_load_dwordx4 v[2:5], v21, s[12:13] offset:32
	global_load_dwordx4 v[114:117], v25, s[0:1] offset:3132
	s_add_u32 s12, s0, 0x1e00
	s_addc_u32 s13, s1, 0
	global_load_dwordx4 v[118:121], v21, s[12:13] offset:32
	global_load_dwordx3 v[130:132], v21, s[12:13] offset:48
	global_load_dwordx4 v[122:125], v21, s[12:13] offset:16
	global_load_dwordx4 v[126:129], v25, s[0:1] offset:3584
	s_add_u32 s12, s0, 0x1e3c
	s_addc_u32 s13, s1, 0
	s_waitcnt vmcnt(8)
	v_mov_b32_e32 v134, v110
	s_waitcnt vmcnt(0)
	v_mov_b32_e32 v135, v126
	v_pk_fma_f32 v[48:49], v[134:135], v[68:69], v[48:49] op_sel_hi:[1,0,1]
	v_mov_b32_e32 v126, v111
	v_pk_fma_f32 v[48:49], v[126:127], v[70:71], v[48:49] op_sel_hi:[1,0,1]
	v_mov_b32_e32 v68, v112
	v_mov_b32_e32 v69, v128
	v_pk_fma_f32 v[48:49], v[68:69], v[72:73], v[48:49] op_sel_hi:[1,0,1]
	v_mov_b32_e32 v128, v113
	v_pk_fma_f32 v[48:49], v[128:129], v[74:75], v[48:49] op_sel_hi:[1,0,1]
	v_mov_b32_e32 v68, v14
	v_mov_b32_e32 v69, v122
	v_pk_fma_f32 v[48:49], v[68:69], v[76:77], v[48:49] op_sel_hi:[1,0,1]
	v_mov_b32_e32 v122, v15
	v_pk_fma_f32 v[14:15], v[122:123], v[78:79], v[48:49] op_sel_hi:[1,0,1]
	v_mov_b32_e32 v48, v16
	v_mov_b32_e32 v49, v124
	v_pk_fma_f32 v[14:15], v[48:49], v[80:81], v[14:15] op_sel_hi:[1,0,1]
	v_mov_b32_e32 v124, v17
	v_pk_fma_f32 v[14:15], v[124:125], v[82:83], v[14:15] op_sel_hi:[1,0,1]
	v_mov_b32_e32 v16, v10
	v_mov_b32_e32 v17, v118
	v_pk_fma_f32 v[14:15], v[16:17], v[84:85], v[14:15] op_sel_hi:[1,0,1]
	v_mov_b32_e32 v118, v11
	v_pk_fma_f32 v[10:11], v[118:119], v[86:87], v[14:15] op_sel_hi:[1,0,1]
	v_mov_b32_e32 v14, v12
	v_mov_b32_e32 v15, v120
	v_pk_fma_f32 v[10:11], v[14:15], v[88:89], v[10:11] op_sel_hi:[1,0,1]
	v_mov_b32_e32 v120, v13
	v_pk_fma_f32 v[10:11], v[120:121], v[90:91], v[10:11] op_sel_hi:[1,0,1]
	v_mov_b32_e32 v12, v22
	v_mov_b32_e32 v13, v130
	v_pk_fma_f32 v[10:11], v[12:13], v[92:93], v[10:11] op_sel_hi:[1,0,1]
	v_mov_b32_e32 v130, v23
	v_pk_fma_f32 v[10:11], v[130:131], v[94:95], v[10:11] op_sel_hi:[1,0,1]
	v_mov_b32_e32 v12, v24
	v_mov_b32_e32 v13, v132
	v_pk_fma_f32 v[48:49], v[12:13], v[96:97], v[10:11] op_sel_hi:[1,0,1]
	global_load_dwordx4 v[14:17], v21, s[12:13] offset:16
	global_load_dwordx3 v[22:24], v21, s[12:13] offset:48
	global_load_dwordx4 v[10:13], v21, s[12:13] offset:32
	global_load_dwordx4 v[68:71], v25, s[0:1] offset:3644
	v_mov_b32_e32 v72, v114
	s_waitcnt vmcnt(0)
	v_mov_b32_e32 v73, v68
	v_pk_fma_f32 v[48:49], v[72:73], v[98:99], v[48:49] op_sel_hi:[1,0,1]
	v_mov_b32_e32 v68, v115
	v_pk_fma_f32 v[48:49], v[68:69], v[100:101], v[48:49] op_sel_hi:[1,0,1]
	v_mov_b32_e32 v68, v116
	v_mov_b32_e32 v69, v70
	v_pk_fma_f32 v[48:49], v[68:69], v[102:103], v[48:49] op_sel_hi:[1,0,1]
	v_mov_b32_e32 v70, v117
	v_pk_fma_f32 v[48:49], v[70:71], v[104:105], v[48:49] op_sel_hi:[1,0,1]
	v_mov_b32_e32 v68, v6
	v_mov_b32_e32 v69, v14
	v_pk_fma_f32 v[48:49], v[68:69], v[106:107], v[48:49] op_sel_hi:[1,0,1]
	v_mov_b32_e32 v14, v7
	v_pk_fma_f32 v[14:15], v[14:15], v[108:109], v[48:49] op_sel_hi:[1,0,1]
	v_mov_b32_e32 v48, v8
	v_mov_b32_e32 v49, v16
	v_pk_fma_f32 v[14:15], v[48:49], v[50:51], v[14:15] op_sel_hi:[1,0,1]
	v_mov_b32_e32 v16, v9
	v_pk_fma_f32 v[8:9], v[16:17], v[52:53], v[14:15] op_sel_hi:[1,0,1]
	v_mov_b32_e32 v14, v2
	v_mov_b32_e32 v15, v10
	v_pk_fma_f32 v[8:9], v[14:15], v[54:55], v[8:9] op_sel_hi:[1,0,1]
	v_mov_b32_e32 v10, v3
	v_pk_fma_f32 v[2:3], v[10:11], v[56:57], v[8:9] op_sel_hi:[1,0,1]
	v_mov_b32_e32 v8, v4
	v_mov_b32_e32 v9, v12
	v_pk_fma_f32 v[2:3], v[8:9], v[58:59], v[2:3] op_sel_hi:[1,0,1]
	v_mov_b32_e32 v12, v5
	v_pk_fma_f32 v[2:3], v[12:13], v[60:61], v[2:3] op_sel_hi:[1,0,1]
	v_mov_b32_e32 v4, v18
	v_mov_b32_e32 v5, v22
	v_pk_fma_f32 v[2:3], v[4:5], v[62:63], v[2:3] op_sel_hi:[1,0,1]
	v_mov_b32_e32 v22, v19
	v_pk_fma_f32 v[2:3], v[22:23], v[64:65], v[2:3] op_sel_hi:[1,0,1]
	v_mov_b32_e32 v4, v20
	v_mov_b32_e32 v5, v24
	global_load_dwordx2 v[6:7], v25, s[0:1] offset:3192
	v_pk_fma_f32 v[2:3], v[4:5], v[66:67], v[2:3] op_sel_hi:[1,0,1]
	global_load_dwordx2 v[4:5], v25, s[0:1] offset:3704
	s_add_i32 s0, s8, 32
	s_cmpk_gt_u32 s8, 0x5f
	s_mov_b32 s8, s0
	s_waitcnt vmcnt(1)
	v_mov_b32_e32 v8, v6
	s_waitcnt vmcnt(0)
	v_mov_b32_e32 v9, v4
	v_pk_fma_f32 v[2:3], v[8:9], v[44:45], v[2:3] op_sel_hi:[1,0,1]
	v_mov_b32_e32 v4, v7
	v_pk_fma_f32 v[48:49], v[4:5], v[46:47], v[2:3] op_sel_hi:[1,0,1]
	s_cbranch_scc0 .LBB0_74
; __device__ __forceinline__ unsigned cvt_pk(float lo, float hi) { f32x2_t v = {lo, hi}; bf16x2_t b = __builtin_convertvector(v, bf16x2_t); return __builtin_bit_cast(unsigned, b); }
; __global__ void __launch_bounds__(NTH, 2) mega(Params p) {
;     ...
;             bf16_t* o = (bf16_t*)(ws + WS_WBR + L * SZ_WBR) + (size_t)n * 512 + g * 128 + kc * 16;
;             u32x4 w0, w1;
;             w0.x = cvt_pk(acc16[0], acc16[1]); w0.y = cvt_pk(acc16[2], acc16[3]); w0.z = cvt_pk(acc16[4], acc16[5]); w0.w = cvt_pk(acc16[6], acc16[7]);
;             w1.x = cvt_pk(acc16[8], acc16[9]); w1.y = cvt_pk(acc16[10], acc16[11]); w1.z = cvt_pk(acc16[12], acc16[13]); w1.w = cvt_pk(acc16[14], acc16[15]);
;             *(u32x4*)o = w0; *(u32x4*)(o + 8) = w1;
	s_mul_i32 s0, s10, 0x300000
	s_mul_hi_i32 s1, s10, 0x300000
	s_add_u32 s0, s16, s0
	s_addc_u32 s1, s17, s1
	v_lshlrev_b32_e32 v20, 10, v26
	v_lshl_add_u64 v[2:3], s[0:1], 0, v[20:21]
	s_lshl_b32 s8, s18, 1
	v_lshl_add_u64 v[2:3], v[2:3], 0, s[8:9]
	s_lshl_b32 s8, s11, 1
	s_add_i32 s14, s14, s15
	v_lshl_add_u64 v[10:11], v[2:3], 0, s[8:9]
	v_cvt_pk_bf16_f32 v2, v42, v43
	v_cvt_pk_bf16_f32 v3, v40, v41
	v_cvt_pk_bf16_f32 v4, v38, v39
	v_cvt_pk_bf16_f32 v5, v36, v37
	v_cvt_pk_bf16_f32 v6, v34, v35
	v_cvt_pk_bf16_f32 v7, v32, v33
	v_cvt_pk_bf16_f32 v8, v30, v31
	v_cvt_pk_bf16_f32 v9, v48, v49
	s_cmpk_gt_i32 s14, 0x7ff
	global_store_dwordx4 v[10:11], v[2:5], off
	global_store_dwordx4 v[10:11], v[6:9], off offset:16
	s_cbranch_scc0 .LBB0_73

; __device__ __forceinline__ void unpk8(u32x4 w, f32x4& a, f32x4& b) { a[0] = bflo(w.x); a[1] = bfhi(w.x); a[2] = bflo(w.y); a[3] = bfhi(w.y); b[0] = bflo(w.z); b[1] = bfhi(w.z); b[2] = bflo(w.w); b[3] = bfhi(w.w); }
; __global__ void __launch_bounds__(NTH, 2) mega(Params p) {
;     ...
;                     for (int q = 0; q < 8; ++q) { const int d = d0 + q, to = t0 + d - w + 1; nw[q] = *(const u32x4*)(ub + (size_t)d * 512);
;                         oa[q] = (f32x4){0.f, 0.f, 0.f, 0.f}; ob[q] = oa[q];
;                         if (to >= 0) unpk8(*(const u32x4*)(ub + (ptrdiff_t)(d - w + 1) * 512), oa[q], ob[q]); else if (!pr) { oa[q] = *(const f32x4*)(hb + (ptrdiff_t)to * 512); ob[q] = *(const f32x4*)(hb + (ptrdiff_t)to * 512 + 4); } }
.LBB0_1041:
	s_or_saveexec_b64 s[18:19], s[18:19]
	v_lshl_add_u64 v[132:133], v[112:113], 0, v[110:111]
	s_xor_b64 exec, exec, s[18:19]
	s_cbranch_execz .LBB0_1043
	v_add_co_u32_e32 v2, vcc, 0xe4401000, v132
	s_nop 1
	v_addc_co_u32_e32 v3, vcc, -1, v133, vcc
	global_load_dwordx4 v[6:9], v[2:3], off offset:-3072
	s_waitcnt vmcnt(0)
	v_lshlrev_b32_e32 v2, 16, v6
	v_and_b32_e32 v3, 0xffff0000, v6
	v_lshlrev_b32_e32 v4, 16, v7
	v_and_b32_e32 v5, 0xffff0000, v7
	v_lshlrev_b32_e32 v6, 16, v8
	v_and_b32_e32 v7, 0xffff0000, v8
	v_lshlrev_b32_e32 v8, 16, v9
	v_and_b32_e32 v9, 0xffff0000, v9

; __device__ __forceinline__ void unpk8(u32x4 w, f32x4& a, f32x4& b) { a[0] = bflo(w.x); a[1] = bfhi(w.x); a[2] = bflo(w.y); a[3] = bfhi(w.y); b[0] = bflo(w.z); b[1] = bfhi(w.z); b[2] = bflo(w.w); b[3] = bfhi(w.w); }
; __global__ void __launch_bounds__(NTH, 2) mega(Params p) {
;     ...
;                     for (int q = 0; q < 8; ++q) { const int d = d0 + q, to = t0 + d - w + 1; nw[q] = *(const u32x4*)(ub + (size_t)d * 512);
;                         oa[q] = (f32x4){0.f, 0.f, 0.f, 0.f}; ob[q] = oa[q];
;                         if (to >= 0) unpk8(*(const u32x4*)(ub + (ptrdiff_t)(d - w + 1) * 512), oa[q], ob[q]); else if (!pr) { oa[q] = *(const f32x4*)(hb + (ptrdiff_t)to * 512); ob[q] = *(const f32x4*)(hb + (ptrdiff_t)to * 512 + 4); } }
.LBB0_1047:
	s_andn2_saveexec_b64 s[18:19], s[18:19]
	s_cbranch_execz .LBB0_1049
	v_add_co_u32_e32 v14, vcc, 0xe4401000, v132
	s_nop 1
	v_addc_co_u32_e32 v15, vcc, -1, v133, vcc
	global_load_dwordx4 v[18:21], v[14:15], off offset:-2048
	s_waitcnt vmcnt(0)
	v_lshlrev_b32_e32 v14, 16, v18
	v_and_b32_e32 v15, 0xffff0000, v18
	v_lshlrev_b32_e32 v16, 16, v19
	v_and_b32_e32 v17, 0xffff0000, v19
	v_lshlrev_b32_e32 v18, 16, v20
	v_and_b32_e32 v19, 0xffff0000, v20
	v_lshlrev_b32_e32 v20, 16, v21
	v_and_b32_e32 v21, 0xffff0000, v21

; __device__ __forceinline__ void unpk8(u32x4 w, f32x4& a, f32x4& b) { a[0] = bflo(w.x); a[1] = bfhi(w.x); a[2] = bflo(w.y); a[3] = bfhi(w.y); b[0] = bflo(w.z); b[1] = bfhi(w.z); b[2] = bflo(w.w); b[3] = bfhi(w.w); }
; __global__ void __launch_bounds__(NTH, 2) mega(Params p) {
;     ...
;                     for (int q = 0; q < 8; ++q) { const int d = d0 + q, to = t0 + d - w + 1; nw[q] = *(const u32x4*)(ub + (size_t)d * 512);
;                         oa[q] = (f32x4){0.f, 0.f, 0.f, 0.f}; ob[q] = oa[q];
;                         if (to >= 0) unpk8(*(const u32x4*)(ub + (ptrdiff_t)(d - w + 1) * 512), oa[q], ob[q]); else if (!pr) { oa[q] = *(const f32x4*)(hb + (ptrdiff_t)to * 512); ob[q] = *(const f32x4*)(hb + (ptrdiff_t)to * 512 + 4); } }
.LBB0_1053:
	s_andn2_saveexec_b64 s[18:19], s[18:19]
	s_cbranch_execz .LBB0_1055
	v_add_co_u32_e32 v26, vcc, 0xe4401000, v132
	s_nop 1
	v_addc_co_u32_e32 v27, vcc, -1, v133, vcc
	global_load_dwordx4 v[30:33], v[26:27], off offset:-1024
	s_waitcnt vmcnt(0)
	v_lshlrev_b32_e32 v26, 16, v30
	v_and_b32_e32 v27, 0xffff0000, v30
	v_lshlrev_b32_e32 v28, 16, v31
	v_and_b32_e32 v29, 0xffff0000, v31
	v_lshlrev_b32_e32 v30, 16, v32
	v_and_b32_e32 v31, 0xffff0000, v32
	v_lshlrev_b32_e32 v32, 16, v33
	v_and_b32_e32 v33, 0xffff0000, v33

; __device__ __forceinline__ void unpk8(u32x4 w, f32x4& a, f32x4& b) { a[0] = bflo(w.x); a[1] = bfhi(w.x); a[2] = bflo(w.y); a[3] = bfhi(w.y); b[0] = bflo(w.z); b[1] = bfhi(w.z); b[2] = bflo(w.w); b[3] = bfhi(w.w); }
; __global__ void __launch_bounds__(NTH, 2) mega(Params p) {
;     ...
;                     for (int q = 0; q < 8; ++q) { const int d = d0 + q, to = t0 + d - w + 1; nw[q] = *(const u32x4*)(ub + (size_t)d * 512);
;                         oa[q] = (f32x4){0.f, 0.f, 0.f, 0.f}; ob[q] = oa[q];
;                         if (to >= 0) unpk8(*(const u32x4*)(ub + (ptrdiff_t)(d - w + 1) * 512), oa[q], ob[q]); else if (!pr) { oa[q] = *(const f32x4*)(hb + (ptrdiff_t)to * 512); ob[q] = *(const f32x4*)(hb + (ptrdiff_t)to * 512 + 4); } }
.LBB0_1059:
	s_andn2_saveexec_b64 s[18:19], s[18:19]
	s_cbranch_execz .LBB0_1061
	v_add_co_u32_e32 v38, vcc, 0xe4401000, v132
	s_nop 1
	v_addc_co_u32_e32 v39, vcc, -1, v133, vcc
	global_load_dwordx4 v[42:45], v[38:39], off
	s_waitcnt vmcnt(0)
	v_lshlrev_b32_e32 v38, 16, v42
	v_and_b32_e32 v39, 0xffff0000, v42
	v_lshlrev_b32_e32 v40, 16, v43
	v_and_b32_e32 v41, 0xffff0000, v43
	v_lshlrev_b32_e32 v42, 16, v44
	v_and_b32_e32 v43, 0xffff0000, v44
	v_lshlrev_b32_e32 v44, 16, v45
	v_and_b32_e32 v45, 0xffff0000, v45

; __device__ __forceinline__ void unpk8(u32x4 w, f32x4& a, f32x4& b) { a[0] = bflo(w.x); a[1] = bfhi(w.x); a[2] = bflo(w.y); a[3] = bfhi(w.y); b[0] = bflo(w.z); b[1] = bfhi(w.z); b[2] = bflo(w.w); b[3] = bfhi(w.w); }
; __global__ void __launch_bounds__(NTH, 2) mega(Params p) {
;     ...
;                     for (int q = 0; q < 8; ++q) { const int d = d0 + q, to = t0 + d - w + 1; nw[q] = *(const u32x4*)(ub + (size_t)d * 512);
;                         oa[q] = (f32x4){0.f, 0.f, 0.f, 0.f}; ob[q] = oa[q];
;                         if (to >= 0) unpk8(*(const u32x4*)(ub + (ptrdiff_t)(d - w + 1) * 512), oa[q], ob[q]); else if (!pr) { oa[q] = *(const f32x4*)(hb + (ptrdiff_t)to * 512); ob[q] = *(const f32x4*)(hb + (ptrdiff_t)to * 512 + 4); } }
.LBB0_1065:
	s_andn2_saveexec_b64 s[18:19], s[18:19]
	s_cbranch_execz .LBB0_1067
	v_add_co_u32_e32 v50, vcc, 0xe4402000, v132
	s_nop 1
	v_addc_co_u32_e32 v51, vcc, -1, v133, vcc
	global_load_dwordx4 v[54:57], v[50:51], off offset:-3072
	s_waitcnt vmcnt(0)
	v_lshlrev_b32_e32 v50, 16, v54
	v_and_b32_e32 v51, 0xffff0000, v54
	v_lshlrev_b32_e32 v52, 16, v55
	v_and_b32_e32 v53, 0xffff0000, v55
	v_lshlrev_b32_e32 v54, 16, v56
	v_and_b32_e32 v55, 0xffff0000, v56
	v_lshlrev_b32_e32 v56, 16, v57
	v_and_b32_e32 v57, 0xffff0000, v57

; __device__ __forceinline__ void unpk8(u32x4 w, f32x4& a, f32x4& b) { a[0] = bflo(w.x); a[1] = bfhi(w.x); a[2] = bflo(w.y); a[3] = bfhi(w.y); b[0] = bflo(w.z); b[1] = bfhi(w.z); b[2] = bflo(w.w); b[3] = bfhi(w.w); }
; __global__ void __launch_bounds__(NTH, 2) mega(Params p) {
;     ...
;                     for (int q = 0; q < 8; ++q) { const int d = d0 + q, to = t0 + d - w + 1; nw[q] = *(const u32x4*)(ub + (size_t)d * 512);
;                         oa[q] = (f32x4){0.f, 0.f, 0.f, 0.f}; ob[q] = oa[q];
;                         if (to >= 0) unpk8(*(const u32x4*)(ub + (ptrdiff_t)(d - w + 1) * 512), oa[q], ob[q]); else if (!pr) { oa[q] = *(const f32x4*)(hb + (ptrdiff_t)to * 512); ob[q] = *(const f32x4*)(hb + (ptrdiff_t)to * 512 + 4); } }
.LBB0_1071:
	s_andn2_saveexec_b64 s[18:19], s[18:19]
	s_cbranch_execz .LBB0_1073
	v_add_co_u32_e32 v62, vcc, 0xe4402000, v132
	s_nop 1
	v_addc_co_u32_e32 v63, vcc, -1, v133, vcc
	global_load_dwordx4 v[66:69], v[62:63], off offset:-2048
	s_waitcnt vmcnt(0)
	v_lshlrev_b32_e32 v62, 16, v66
	v_and_b32_e32 v63, 0xffff0000, v66
	v_lshlrev_b32_e32 v64, 16, v67
	v_and_b32_e32 v65, 0xffff0000, v67
	v_lshlrev_b32_e32 v66, 16, v68
	v_and_b32_e32 v67, 0xffff0000, v68
	v_lshlrev_b32_e32 v68, 16, v69
	v_and_b32_e32 v69, 0xffff0000, v69

; __device__ __forceinline__ void unpk8(u32x4 w, f32x4& a, f32x4& b) { a[0] = bflo(w.x); a[1] = bfhi(w.x); a[2] = bflo(w.y); a[3] = bfhi(w.y); b[0] = bflo(w.z); b[1] = bfhi(w.z); b[2] = bflo(w.w); b[3] = bfhi(w.w); }
; __global__ void __launch_bounds__(NTH, 2) mega(Params p) {
;     ...
;                     for (int q = 0; q < 8; ++q) { const int d = d0 + q, to = t0 + d - w + 1; nw[q] = *(const u32x4*)(ub + (size_t)d * 512);
;                         oa[q] = (f32x4){0.f, 0.f, 0.f, 0.f}; ob[q] = oa[q];
;                         if (to >= 0) unpk8(*(const u32x4*)(ub + (ptrdiff_t)(d - w + 1) * 512), oa[q], ob[q]); else if (!pr) { oa[q] = *(const f32x4*)(hb + (ptrdiff_t)to * 512); ob[q] = *(const f32x4*)(hb + (ptrdiff_t)to * 512 + 4); } }
.LBB0_1077:
	s_andn2_saveexec_b64 s[18:19], s[18:19]
	s_cbranch_execz .LBB0_1079
	v_add_co_u32_e32 v74, vcc, 0xe4402000, v132
	s_nop 1
	v_addc_co_u32_e32 v75, vcc, -1, v133, vcc
	global_load_dwordx4 v[78:81], v[74:75], off offset:-1024
	s_waitcnt vmcnt(0)
	v_lshlrev_b32_e32 v74, 16, v78
	v_and_b32_e32 v75, 0xffff0000, v78
	v_lshlrev_b32_e32 v76, 16, v79
	v_and_b32_e32 v77, 0xffff0000, v79
	v_lshlrev_b32_e32 v78, 16, v80
	v_and_b32_e32 v79, 0xffff0000, v80
	v_lshlrev_b32_e32 v80, 16, v81
	v_and_b32_e32 v81, 0xffff0000, v81

; __device__ __forceinline__ void unpk8(u32x4 w, f32x4& a, f32x4& b) { a[0] = bflo(w.x); a[1] = bfhi(w.x); a[2] = bflo(w.y); a[3] = bfhi(w.y); b[0] = bflo(w.z); b[1] = bfhi(w.z); b[2] = bflo(w.w); b[3] = bfhi(w.w); }
; __global__ void __launch_bounds__(NTH, 2) mega(Params p) {
;     ...
;                     for (int q = 0; q < 8; ++q) { const int d = d0 + q, to = t0 + d - w + 1; nw[q] = *(const u32x4*)(ub + (size_t)d * 512);
;                         oa[q] = (f32x4){0.f, 0.f, 0.f, 0.f}; ob[q] = oa[q];
;                         if (to >= 0) unpk8(*(const u32x4*)(ub + (ptrdiff_t)(d - w + 1) * 512), oa[q], ob[q]); else if (!pr) { oa[q] = *(const f32x4*)(hb + (ptrdiff_t)to * 512); ob[q] = *(const f32x4*)(hb + (ptrdiff_t)to * 512 + 4); } }
.LBB0_1083:
	s_andn2_saveexec_b64 s[18:19], s[18:19]
	s_cbranch_execz .LBB0_1036
	v_add_co_u32_e32 v86, vcc, 0xe4402000, v132
	s_nop 1
	v_addc_co_u32_e32 v87, vcc, -1, v133, vcc
	global_load_dwordx4 v[90:93], v[86:87], off
	s_waitcnt vmcnt(0)
	v_lshlrev_b32_e32 v86, 16, v90
	v_and_b32_e32 v87, 0xffff0000, v90
	v_lshlrev_b32_e32 v88, 16, v91
	v_and_b32_e32 v89, 0xffff0000, v91
	v_lshlrev_b32_e32 v90, 16, v92
	v_and_b32_e32 v91, 0xffff0000, v92
	v_lshlrev_b32_e32 v92, 16, v93
	v_and_b32_e32 v93, 0xffff0000, v93
	s_branch .LBB0_1036

; #define LAS __attribute__((address_space(3)))
; __device__ __forceinline__ void attn_unit(LAS unsigned char* lds, const bf16_t* __restrict__ Q, const bf16_t* __restrict__ K, const bf16_t* __restrict__ VT, const int ldv, ...
;     ...
;             const LAS unsigned char* kt = lds + AT_KT + cur * 9216; const LAS unsigned char* vt = lds + AT_VT + cur * 9216; const LAS unsigned char* ck = lds + AT_CK + cur * 256;
;             f32x16 p0, p1;
; #pragma unroll
;             for (int rg = 0; rg < 4; ++rg) {
;                 const f32x4 c0 = *(const LAS f32x4*)(ck + (8 * rg + 4 * hi) * 4), c1 = *(const LAS f32x4*)(ck + (32 + 8 * rg + 4 * hi) * 4);
; #pragma unroll
;                 for (int i = 0; i < 4; ++i) { p0[4 * rg + i] = cq - c0[i]; p1[4 * rg + i] = cq - c1[i]; }
;             }
; #pragma unroll
;             for (int d0 = 0; d0 < 4; ++d0) {
;                 const bf16x8 a0 = *(const LAS bf16x8*)(kt + (r32 * AT_PITCH + d0 * 16 + hi * 8) * 2);
;                 const bf16x8 a1 = *(const LAS bf16x8*)(kt + ((32 + r32) * AT_PITCH + d0 * 16 + hi * 8) * 2);
;                 p0 = __builtin_amdgcn_mfma_f32_32x32x16_bf16(a0, qf[d0], p0, 0, 0, 0);
;                 p1 = __builtin_amdgcn_mfma_f32_32x32x16_bf16(a1, qf[d0], p1, 0, 0, 0);
;             }
;             if (64 * jt + 63 > qpos0 + 32 * wid) {
; #pragma unroll
;                 for (int r = 0; r < 16; ++r) { const int kp = 64 * jt + (r & 3) + 8 * (r >> 2) + 4 * hi; if (kp > qp) p0[r] = -INFINITY; if (kp + 32 > qp) p1[r] = -INFINITY; }
.LBB0_1270:
	s_sub_i32 s16, s45, 63
	s_cmp_gt_i32 s16, s44
	s_cbranch_scc1 .LBB0_1276
	v_lshl_add_u32 v0, s43, 8, v143
	s_mul_i32 s16, s43, 0x2400
	v_add_u32_e32 v220, s16, v162
	ds_read_b128 v[166:169], v220
	ds_read_b128 v[194:197], v220 offset:4608
	ds_read_b128 v[198:201], v220 offset:32
	ds_read_b128 v[202:205], v220 offset:4640
	ds_read_b128 v[206:209], v220 offset:64
	ds_read_b128 v[238:241], v220 offset:4672
	ds_read_b128 v[242:245], v220 offset:96
	ds_read_b128 v[246:249], v220 offset:4704
	ds_read_b128 v[64:67], v0 offset:36960
	ds_read_b128 v[80:83], v0 offset:37088
	s_cmp_le_i32 s45, s19
	s_waitcnt lgkmcnt(1)
	v_sub_f32_e32 v79, v63, v67
	v_sub_f32_e32 v78, v62, v66
	v_sub_f32_e32 v77, v61, v65
	v_sub_f32_e32 v76, v60, v64
	ds_read_b128 v[64:67], v0 offset:36928
	s_waitcnt lgkmcnt(1)
	v_sub_f32_e32 v95, v63, v83
	v_sub_f32_e32 v94, v62, v82
	v_sub_f32_e32 v93, v61, v81
	v_sub_f32_e32 v92, v60, v80
	ds_read_b128 v[80:83], v0 offset:37056
	s_waitcnt lgkmcnt(1)
	v_sub_f32_e32 v75, v59, v67
	v_sub_f32_e32 v74, v58, v66
	v_sub_f32_e32 v73, v57, v65
	v_sub_f32_e32 v72, v56, v64
	ds_read_b128 v[64:67], v0 offset:36896
	s_waitcnt lgkmcnt(1)
	v_sub_f32_e32 v91, v59, v83
	v_sub_f32_e32 v90, v58, v82
	v_sub_f32_e32 v89, v57, v81
	v_sub_f32_e32 v88, v56, v80
	ds_read_b128 v[80:83], v0 offset:37024
	s_waitcnt lgkmcnt(1)
	v_sub_f32_e32 v71, v55, v67
	v_sub_f32_e32 v70, v54, v66
	v_sub_f32_e32 v69, v53, v65
	v_sub_f32_e32 v68, v52, v64
	ds_read_b128 v[64:67], v0 offset:36864
	s_waitcnt lgkmcnt(1)
	v_sub_f32_e32 v87, v55, v83
	v_sub_f32_e32 v86, v54, v82
	v_sub_f32_e32 v85, v53, v81
	v_sub_f32_e32 v84, v52, v80
	ds_read_b128 v[80:83], v0 offset:36992
	s_waitcnt lgkmcnt(1)
	v_sub_f32_e32 v67, v51, v67
	v_sub_f32_e32 v66, v50, v66
	v_sub_f32_e32 v65, v17, v65
	v_sub_f32_e32 v64, v16, v64
	s_waitcnt lgkmcnt(0)
	v_sub_f32_e32 v83, v51, v83
	v_sub_f32_e32 v82, v50, v82
	v_sub_f32_e32 v81, v17, v81
	v_sub_f32_e32 v80, v16, v80
	s_nop 1
	v_mfma_f32_32x32x16_bf16 v[64:79], v[166:169], v[108:111], v[64:79]
	v_mfma_f32_32x32x16_bf16 v[80:95], v[194:197], v[108:111], v[80:95]
	v_mfma_f32_32x32x16_bf16 v[64:79], v[198:201], v[112:115], v[64:79]
	v_mfma_f32_32x32x16_bf16 v[80:95], v[202:205], v[112:115], v[80:95]
	v_mfma_f32_32x32x16_bf16 v[64:79], v[206:209], v[116:119], v[64:79]
	v_mfma_f32_32x32x16_bf16 v[80:95], v[238:241], v[116:119], v[80:95]
	v_mfma_f32_32x32x16_bf16 v[64:79], v[242:245], v[120:123], v[64:79]
	v_mfma_f32_32x32x16_bf16 v[80:95], v[246:249], v[120:123], v[80:95]
	s_cbranch_scc1 .LBB0_1273
	v_add_u32_e32 v0, s45, v144
	v_subrev_u32_e32 v15, 31, v0
	v_subrev_u32_e32 v14, 63, v0
	v_cmp_le_i32_e32 vcc, v15, v136
	s_nop 6
	v_cndmask_b32_e32 v80, v236, v80, vcc
	v_cmp_lt_i32_e32 vcc, v14, v136
	s_nop 1
	v_cndmask_b32_e32 v65, v236, v65, vcc
	v_cmp_le_i32_e32 vcc, v14, v136
	v_subrev_u32_e32 v14, 30, v0
	s_nop 0
	v_cndmask_b32_e32 v64, v236, v64, vcc
	v_cmp_le_i32_e32 vcc, v14, v136
	v_subrev_u32_e32 v14, 61, v0
	s_nop 0
	v_cndmask_b32_e32 v81, v236, v81, vcc
	v_cmp_le_i32_e32 vcc, v14, v136
	v_subrev_u32_e32 v14, 29, v0
	s_nop 0
	v_cndmask_b32_e32 v66, v236, v66, vcc
	v_cmp_le_i32_e32 vcc, v14, v136
	v_subrev_u32_e32 v14, 60, v0
	s_nop 0
	v_cndmask_b32_e32 v82, v236, v82, vcc
	v_cmp_le_i32_e32 vcc, v14, v136
	v_subrev_u32_e32 v14, 28, v0
	s_nop 0
	v_cndmask_b32_e32 v67, v236, v67, vcc
	v_cmp_le_i32_e32 vcc, v14, v136
	v_subrev_u32_e32 v14, 55, v0
	s_nop 0
	v_cndmask_b32_e32 v83, v236, v83, vcc
	v_cmp_le_i32_e32 vcc, v14, v136
	v_subrev_u32_e32 v14, 23, v0
	s_nop 0
	v_cndmask_b32_e32 v68, v236, v68, vcc
	v_cmp_le_i32_e32 vcc, v14, v136
	v_subrev_u32_e32 v14, 54, v0
	s_nop 0
	v_cndmask_b32_e32 v84, v236, v84, vcc
	v_cmp_le_i32_e32 vcc, v14, v136
	v_subrev_u32_e32 v14, 22, v0
	s_nop 0
	v_cndmask_b32_e32 v69, v236, v69, vcc
	v_cmp_le_i32_e32 vcc, v14, v136
	v_subrev_u32_e32 v14, 53, v0
	s_nop 0
	v_cndmask_b32_e32 v85, v236, v85, vcc
	v_cmp_le_i32_e32 vcc, v14, v136
	v_subrev_u32_e32 v14, 21, v0
	s_nop 0
	v_cndmask_b32_e32 v70, v236, v70, vcc
	v_cmp_le_i32_e32 vcc, v14, v136
	v_subrev_u32_e32 v14, 52, v0
	s_nop 0
	v_cndmask_b32_e32 v86, v236, v86, vcc
	v_cmp_le_i32_e32 vcc, v14, v136
	v_subrev_u32_e32 v14, 20, v0
	s_nop 0
	v_cndmask_b32_e32 v71, v236, v71, vcc
	v_cmp_le_i32_e32 vcc, v14, v136
	v_subrev_u32_e32 v14, 47, v0
	s_nop 0
	v_cndmask_b32_e32 v87, v236, v87, vcc
	v_cmp_le_i32_e32 vcc, v14, v136
	v_add_u32_e32 v14, -15, v0
	s_nop 0
	v_cndmask_b32_e32 v72, v236, v72, vcc
	v_cmp_le_i32_e32 vcc, v14, v136
	v_subrev_u32_e32 v14, 46, v0
	s_nop 0
	v_cndmask_b32_e32 v88, v236, v88, vcc
	v_cmp_le_i32_e32 vcc, v14, v136
	v_add_u32_e32 v14, -14, v0
	s_nop 0
	v_cndmask_b32_e32 v73, v236, v73, vcc
	v_cmp_le_i32_e32 vcc, v14, v136
	v_subrev_u32_e32 v14, 45, v0
	s_nop 0
	v_cndmask_b32_e32 v89, v236, v89, vcc
	v_cmp_le_i32_e32 vcc, v14, v136
	v_add_u32_e32 v14, -13, v0
	s_nop 0
	v_cndmask_b32_e32 v74, v236, v74, vcc
	v_cmp_le_i32_e32 vcc, v14, v136
	v_subrev_u32_e32 v14, 44, v0
	s_nop 0
	v_cndmask_b32_e32 v90, v236, v90, vcc
	v_cmp_le_i32_e32 vcc, v14, v136
	v_add_u32_e32 v14, -12, v0
	s_nop 0
	v_cndmask_b32_e32 v75, v236, v75, vcc
	v_cmp_le_i32_e32 vcc, v14, v136
	v_subrev_u32_e32 v14, 39, v0
	s_nop 0
	v_cndmask_b32_e32 v91, v236, v91, vcc
	v_cmp_le_i32_e32 vcc, v14, v136
	v_add_u32_e32 v14, -7, v0
	s_nop 0
	v_cndmask_b32_e32 v76, v236, v76, vcc
	v_cmp_le_i32_e32 vcc, v14, v136
	v_subrev_u32_e32 v14, 38, v0
	s_nop 0
	v_cndmask_b32_e32 v92, v236, v92, vcc
	v_cmp_le_i32_e32 vcc, v14, v136
	v_add_u32_e32 v14, -6, v0
	s_nop 0
	v_cndmask_b32_e32 v77, v236, v77, vcc
	v_cmp_le_i32_e32 vcc, v14, v136
	v_subrev_u32_e32 v14, 37, v0
	s_nop 0
	v_cndmask_b32_e32 v93, v236, v93, vcc
	v_cmp_le_i32_e32 vcc, v14, v136
	v_add_u32_e32 v14, -5, v0
	s_nop 0
	v_cndmask_b32_e32 v78, v236, v78, vcc
	v_cmp_le_i32_e32 vcc, v14, v136
	v_subrev_u32_e32 v14, 36, v0
	v_add_u32_e32 v0, -4, v0
	v_cndmask_b32_e32 v94, v236, v94, vcc
	v_cmp_le_i32_e32 vcc, v14, v136
	s_nop 1
	v_cndmask_b32_e32 v79, v236, v79, vcc
	v_cmp_le_i32_e32 vcc, v0, v136
	s_nop 1
	v_cndmask_b32_e32 v95, v236, v95, vcc
; __device__ __forceinline__ void attn_unit(LAS unsigned char* lds, const bf16_t* __restrict__ Q, const bf16_t* __restrict__ K, const bf16_t* __restrict__ VT, const int ldv, ...
;     ...
;             float mx = fmaxf(p0[0], p1[0]);
; #pragma unroll
;             for (int r = 1; r < 16; ++r) mx = fmaxf(mx, fmaxf(p0[r], p1[r]));
;             mx = fmaxf(mx, __shfl_xor(mx, 32));
;             const float mnew = fmaxf(mrun, mx);
;             if (__builtin_amdgcn_ballot_w64(mnew > mrun) != 0ull) {
;                 const float alpha = __builtin_amdgcn_exp2f(mrun - mnew); lrun *= alpha;
; #pragma unroll
;                 for (int r = 0; r < 16; ++r) { o0[r] *= alpha; o1[r] *= alpha; }
;             }
.LBB0_1273:
	s_nop 10
	v_max_f32_e32 v0, v65, v81
	v_max_f32_e32 v14, v66, v82
	v_max3_f32 v0, v64, v80, v0
	v_max_f32_e32 v15, v67, v83
	v_max3_f32 v0, v0, v14, v15
	v_max_f32_e32 v14, v68, v84
	v_max_f32_e32 v15, v69, v85
	v_max3_f32 v0, v0, v14, v15
	v_max_f32_e32 v14, v70, v86
	v_max_f32_e32 v15, v71, v87
	v_max3_f32 v0, v0, v14, v15
	v_max_f32_e32 v14, v72, v88
	v_max_f32_e32 v15, v73, v89
	v_max3_f32 v0, v0, v14, v15
	v_max_f32_e32 v14, v74, v90
	v_max_f32_e32 v15, v75, v91
	v_max3_f32 v0, v0, v14, v15
	v_max_f32_e32 v14, v76, v92
	v_max_f32_e32 v15, v77, v93
	v_max3_f32 v0, v0, v14, v15
	v_max_f32_e32 v14, v78, v94
	v_max_f32_e32 v15, v79, v95
	v_max3_f32 v0, v0, v14, v15
	v_max_f32_e32 v165, v79, v79
	ds_bpermute_b32 v14, v137, v0
	s_waitcnt lgkmcnt(0)
	v_max3_f32 v0, v164, v0, v14
	v_cmp_gt_f32_e32 vcc, v0, v164
	s_cbranch_vccz .LBB0_1275
	v_sub_f32_e32 v14, v164, v0
	v_exp_f32_e32 v14, v14
	s_nop 0
	v_pk_mul_f32 v[48:49], v[48:49], v[14:15] op_sel_hi:[1,0]
	v_pk_mul_f32 v[46:47], v[46:47], v[14:15] op_sel_hi:[1,0]
	v_pk_mul_f32 v[44:45], v[44:45], v[14:15] op_sel_hi:[1,0]
	v_pk_mul_f32 v[42:43], v[42:43], v[14:15] op_sel_hi:[1,0]
	v_pk_mul_f32 v[40:41], v[40:41], v[14:15] op_sel_hi:[1,0]
	v_pk_mul_f32 v[38:39], v[38:39], v[14:15] op_sel_hi:[1,0]
	v_pk_mul_f32 v[36:37], v[36:37], v[14:15] op_sel_hi:[1,0]
	v_pk_mul_f32 v[34:35], v[34:35], v[14:15] op_sel_hi:[1,0]
	v_pk_mul_f32 v[32:33], v[32:33], v[14:15] op_sel_hi:[1,0]
	v_pk_mul_f32 v[30:31], v[30:31], v[14:15] op_sel_hi:[1,0]
	v_pk_mul_f32 v[28:29], v[28:29], v[14:15] op_sel_hi:[1,0]
	v_pk_mul_f32 v[26:27], v[26:27], v[14:15] op_sel_hi:[1,0]
	v_pk_mul_f32 v[24:25], v[24:25], v[14:15] op_sel_hi:[1,0]
	v_pk_mul_f32 v[22:23], v[22:23], v[14:15] op_sel_hi:[1,0]
	v_pk_mul_f32 v[20:21], v[20:21], v[14:15] op_sel_hi:[1,0]
	v_pk_mul_f32 v[18:19], v[18:19], v[14:15] op_sel_hi:[1,0]
	v_mul_f32_e32 v163, v163, v14

; __device__ __forceinline__ unsigned cvt_pk(float lo, float hi) { f32x2_t v = {lo, hi}; bf16x2_t b = __builtin_convertvector(v, bf16x2_t); return __builtin_bit_cast(unsigned, b); }
; __device__ __forceinline__ f32x4 sigm4(f32x4 v) { f32x4 o; o[0] = sigm(v[0]); o[1] = sigm(v[1]); o[2] = sigm(v[2]); o[3] = sigm(v[3]); return o; }
; __device__ __forceinline__ float dppr1(float x) { return __int_as_float(__builtin_amdgcn_mov_dpp(__float_as_int(x), 0x121, 0xf, 0xf, true)); }
; __device__ __forceinline__ float dppr2(float x) { return __int_as_float(__builtin_amdgcn_mov_dpp(__float_as_int(x), 0x122, 0xf, 0xf, true)); }
;     template <int GV, int NH> __device__ __forceinline__ void part(f32x4 (&acc)[2][2][4][2], const Unit& u, int wr, int wc, int fr, int fq) const {
;         const int jg = 128 * u.pn + 32 * wc + 8 * fq + 4 * NH;
;         const f32x4 w0 = *(const f32x4*)(cw + GV * DFF + jg), w1 = *(const f32x4*)(cw + NUP + GV * DFF + jg), w2 = *(const f32x4*)(cw + 2 * NUP + GV * DFF + jg), bb = *(const f32x4*)(cb + GV * DFF + jg);
;         const bool f1 = fr >= 1, f2 = fr >= 2;
; #pragma unroll
;         for (int ai = 0; ai < 2; ++ai) {
;             const unsigned rowb = (unsigned)(u.pm * 256 + ai * 128 + wr * 64 + fr) * DFF + jg;
;             f32x4 p1 = (f32x4){0.f, 0.f, 0.f, 0.f}, p2 = p1;
; #pragma unroll
;             for (int m = 0; m < 4; ++m) {
;                 const f32x4 x3 = acc[ai][GV][m][NH];
;                 f32x4 c1, c2, x2, x1;
; #pragma unroll
;                 for (int i = 0; i < 4; ++i) { c1[i] = dppr1(x3[i]); c2[i] = dppr2(x3[i]); x2[i] = f1 ? c1[i] : p1[i]; x1[i] = f2 ? c2[i] : p2[i]; }
;                 p1 = c1; p2 = c2;
;                 const f32x4 o = bb + x1 * w0 + x2 * w1 + x3 * w2;
;                 if (GV == 0) acc[ai][0][m][NH] = o * sigm4(o);
;                 else { const f32x4 r = acc[ai][0][m][NH] * o; u32x2 pk; pk.x = cvt_pk(r[0], r[1]); pk.y = cvt_pk(r[2], r[3]); *(u32x2*)(ACT + rowb + (unsigned)(16 * m) * DFF) = pk; }
;                 __builtin_amdgcn_sched_barrier(0);
.LBB0_1959:
	s_or_b64 exec, exec, s[86:87]
	v_lshlrev_b64 v[160:161], 2, v[158:159]
	v_lshl_add_u64 v[176:177], s[4:5], 0, v[160:161]
	v_lshl_add_u64 v[186:187], s[18:19], 0, v[160:161]
	global_load_dwordx4 v[134:137], v[176:177], off
	global_load_dwordx4 v[142:145], v[186:187], off
	v_lshl_add_u64 v[130:131], s[52:53], 0, v[160:161]
	global_load_dwordx4 v[138:141], v[130:131], off
	v_lshl_add_u64 v[130:131], s[54:55], 0, v[160:161]
	global_load_dwordx4 v[130:133], v[130:131], off
	global_load_dwordx4 v[198:201], v[176:177], off offset:16
	global_load_dwordx4 v[202:205], v[186:187], off offset:16
	v_lshl_add_u64 v[232:233], s[52:53], 0, v[160:161]
	global_load_dwordx4 v[206:209], v[232:233], off offset:16
	v_lshl_add_u64 v[232:233], s[54:55], 0, v[160:161]
	global_load_dwordx4 v[210:213], v[232:233], off offset:16
	v_mov_b32_dpp v159, v126 row_ror:2 row_mask:0xf bank_mask:0xf bound_ctrl:1
	v_mov_b32_dpp v171, v127 row_ror:2 row_mask:0xf bank_mask:0xf bound_ctrl:1
	v_mov_b32_dpp v173, v128 row_ror:2 row_mask:0xf bank_mask:0xf bound_ctrl:1
	v_mov_b32_dpp v175, v129 row_ror:2 row_mask:0xf bank_mask:0xf bound_ctrl:1
	v_mov_b32_dpp v0, v126 row_ror:1 row_mask:0xf bank_mask:0xf bound_ctrl:1
	v_mov_b32_dpp v170, v127 row_ror:1 row_mask:0xf bank_mask:0xf bound_ctrl:1
	v_mov_b32_dpp v172, v128 row_ror:1 row_mask:0xf bank_mask:0xf bound_ctrl:1
	v_mov_b32_dpp v174, v129 row_ror:1 row_mask:0xf bank_mask:0xf bound_ctrl:1
	v_cndmask_b32_e64 v164, 0, v159, s[12:13]
	v_cndmask_b32_e64 v165, 0, v171, s[12:13]
	v_cndmask_b32_e64 v168, 0, v173, s[12:13]
	v_cndmask_b32_e64 v169, 0, v175, s[12:13]
	v_cndmask_b32_e64 v162, v0, 0, s[10:11]
	v_cndmask_b32_e64 v163, v170, 0, s[10:11]
	v_cndmask_b32_e64 v166, v172, 0, s[10:11]
	v_cndmask_b32_e64 v167, v174, 0, s[10:11]
	s_waitcnt vmcnt(0)
	v_pk_fma_f32 v[168:169], v[136:137], v[168:169], v[144:145]
	v_pk_fma_f32 v[164:165], v[134:135], v[164:165], v[142:143]
	v_pk_fma_f32 v[166:167], v[140:141], v[166:167], v[168:169]
	v_pk_fma_f32 v[162:163], v[138:139], v[162:163], v[164:165]
	v_pk_fma_f32 v[128:129], v[128:129], v[132:133], v[166:167]
	v_pk_fma_f32 v[162:163], v[126:127], v[130:131], v[162:163]
	v_mul_f32_e32 v164, 0xbfb8aa3b, v128
	v_mul_f32_e32 v126, 0xbfb8aa3b, v162
	v_mul_f32_e32 v127, 0xbfb8aa3b, v163
	v_mul_f32_e32 v165, 0xbfb8aa3b, v129
	v_exp_f32_e32 v126, v126
	v_exp_f32_e32 v127, v127
	v_exp_f32_e32 v164, v164
	v_exp_f32_e32 v165, v165
	v_add_f32_e32 v126, 1.0, v126
	v_add_f32_e32 v166, 1.0, v127
	v_add_f32_e32 v127, 1.0, v164
	v_add_f32_e32 v165, 1.0, v165
	v_rcp_f32_e32 v164, v126
	v_rcp_f32_e32 v126, v127
	v_rcp_f32_e32 v127, v165
	v_rcp_f32_e32 v165, v166
	v_pk_mul_f32 v[126:127], v[128:129], v[126:127]
	v_pk_mul_f32 v[128:129], v[162:163], v[164:165]
	v_mov_b32_dpp v179, v122 row_ror:2 row_mask:0xf bank_mask:0xf bound_ctrl:1
	v_mov_b32_dpp v178, v122 row_ror:1 row_mask:0xf bank_mask:0xf bound_ctrl:1
	v_cndmask_b32_e64 v164, v159, v179, s[12:13]
	v_mov_b32_dpp v159, v123 row_ror:2 row_mask:0xf bank_mask:0xf bound_ctrl:1
	v_cndmask_b32_e64 v162, v178, v0, s[10:11]
	v_mov_b32_dpp v0, v123 row_ror:1 row_mask:0xf bank_mask:0xf bound_ctrl:1
	v_cndmask_b32_e64 v165, v171, v159, s[12:13]
	v_mov_b32_dpp v171, v124 row_ror:2 row_mask:0xf bank_mask:0xf bound_ctrl:1
	v_cndmask_b32_e64 v163, v0, v170, s[10:11]
	v_mov_b32_dpp v170, v124 row_ror:1 row_mask:0xf bank_mask:0xf bound_ctrl:1
	v_cndmask_b32_e64 v168, v173, v171, s[12:13]
	v_mov_b32_dpp v173, v125 row_ror:2 row_mask:0xf bank_mask:0xf bound_ctrl:1
	v_cndmask_b32_e64 v166, v170, v172, s[10:11]
	v_mov_b32_dpp v172, v125 row_ror:1 row_mask:0xf bank_mask:0xf bound_ctrl:1
	v_cndmask_b32_e64 v169, v175, v173, s[12:13]
	v_cndmask_b32_e64 v167, v172, v174, s[10:11]
	v_pk_fma_f32 v[168:169], v[136:137], v[168:169], v[144:145]
	v_pk_fma_f32 v[164:165], v[134:135], v[164:165], v[142:143]
	s_nop 0
	v_pk_fma_f32 v[162:163], v[138:139], v[162:163], v[164:165]
	v_pk_fma_f32 v[164:165], v[140:141], v[166:167], v[168:169]
	v_pk_fma_f32 v[122:123], v[122:123], v[130:131], v[162:163]
	v_pk_fma_f32 v[124:125], v[124:125], v[132:133], v[164:165]
	v_mul_f32_e32 v162, 0xbfb8aa3b, v122
	v_mul_f32_e32 v163, 0xbfb8aa3b, v123
	v_mul_f32_e32 v164, 0xbfb8aa3b, v124
	v_mul_f32_e32 v165, 0xbfb8aa3b, v125
	v_exp_f32_e32 v162, v162
	v_exp_f32_e32 v163, v163
	v_exp_f32_e32 v164, v164
	v_exp_f32_e32 v165, v165
	v_add_f32_e32 v162, 1.0, v162
	v_add_f32_e32 v163, 1.0, v163
	v_add_f32_e32 v164, 1.0, v164
	v_add_f32_e32 v165, 1.0, v165
	v_rcp_f32_e32 v162, v162
	v_rcp_f32_e32 v163, v163
	v_rcp_f32_e32 v164, v164
	v_rcp_f32_e32 v165, v165
	v_pk_mul_f32 v[122:123], v[122:123], v[162:163]
	v_pk_mul_f32 v[124:125], v[124:125], v[164:165]
	v_mov_b32_dpp v175, v118 row_ror:2 row_mask:0xf bank_mask:0xf bound_ctrl:1
	v_mov_b32_dpp v174, v118 row_ror:1 row_mask:0xf bank_mask:0xf bound_ctrl:1
	v_cndmask_b32_e64 v164, v179, v175, s[12:13]
	v_mov_b32_dpp v179, v119 row_ror:2 row_mask:0xf bank_mask:0xf bound_ctrl:1
	v_cndmask_b32_e64 v162, v174, v178, s[10:11]
	v_mov_b32_dpp v178, v119 row_ror:1 row_mask:0xf bank_mask:0xf bound_ctrl:1
	v_cndmask_b32_e64 v165, v159, v179, s[12:13]
	v_mov_b32_dpp v159, v120 row_ror:2 row_mask:0xf bank_mask:0xf bound_ctrl:1
	v_cndmask_b32_e64 v163, v178, v0, s[10:11]
	v_mov_b32_dpp v0, v120 row_ror:1 row_mask:0xf bank_mask:0xf bound_ctrl:1
	v_cndmask_b32_e64 v168, v171, v159, s[12:13]
	v_mov_b32_dpp v171, v121 row_ror:2 row_mask:0xf bank_mask:0xf bound_ctrl:1
	v_cndmask_b32_e64 v166, v0, v170, s[10:11]
	v_mov_b32_dpp v170, v121 row_ror:1 row_mask:0xf bank_mask:0xf bound_ctrl:1
	v_cndmask_b32_e64 v169, v173, v171, s[12:13]
	v_cndmask_b32_e64 v167, v170, v172, s[10:11]
; __device__ __forceinline__ unsigned cvt_pk(float lo, float hi) { f32x2_t v = {lo, hi}; bf16x2_t b = __builtin_convertvector(v, bf16x2_t); return __builtin_bit_cast(unsigned, b); }
; __device__ __forceinline__ f32x4 sigm4(f32x4 v) { f32x4 o; o[0] = sigm(v[0]); o[1] = sigm(v[1]); o[2] = sigm(v[2]); o[3] = sigm(v[3]); return o; }
; __device__ __forceinline__ float dppr1(float x) { return __int_as_float(__builtin_amdgcn_mov_dpp(__float_as_int(x), 0x121, 0xf, 0xf, true)); }
; __device__ __forceinline__ float dppr2(float x) { return __int_as_float(__builtin_amdgcn_mov_dpp(__float_as_int(x), 0x122, 0xf, 0xf, true)); }
;     template <int GV, int NH> __device__ __forceinline__ void part(f32x4 (&acc)[2][2][4][2], const Unit& u, int wr, int wc, int fr, int fq) const {
;     ...
;             for (int m = 0; m < 4; ++m) {
;                 const f32x4 x3 = acc[ai][GV][m][NH];
;                 f32x4 c1, c2, x2, x1;
; #pragma unroll
;                 for (int i = 0; i < 4; ++i) { c1[i] = dppr1(x3[i]); c2[i] = dppr2(x3[i]); x2[i] = f1 ? c1[i] : p1[i]; x1[i] = f2 ? c2[i] : p2[i]; }
;                 p1 = c1; p2 = c2;
;                 const f32x4 o = bb + x1 * w0 + x2 * w1 + x3 * w2;
;                 if (GV == 0) acc[ai][0][m][NH] = o * sigm4(o);
;                 else { const f32x4 r = acc[ai][0][m][NH] * o; u32x2 pk; pk.x = cvt_pk(r[0], r[1]); pk.y = cvt_pk(r[2], r[3]); *(u32x2*)(ACT + rowb + (unsigned)(16 * m) * DFF) = pk; }
	v_pk_fma_f32 v[168:169], v[136:137], v[168:169], v[144:145]
	v_pk_fma_f32 v[164:165], v[134:135], v[164:165], v[142:143]
	s_nop 0
	v_pk_fma_f32 v[162:163], v[138:139], v[162:163], v[164:165]
	v_pk_fma_f32 v[164:165], v[140:141], v[166:167], v[168:169]
	v_pk_fma_f32 v[118:119], v[118:119], v[130:131], v[162:163]
	v_pk_fma_f32 v[120:121], v[120:121], v[132:133], v[164:165]
	v_mul_f32_e32 v162, 0xbfb8aa3b, v118
	v_mul_f32_e32 v163, 0xbfb8aa3b, v119
	v_mul_f32_e32 v164, 0xbfb8aa3b, v120
	v_mul_f32_e32 v165, 0xbfb8aa3b, v121
	v_exp_f32_e32 v162, v162
	v_exp_f32_e32 v163, v163
	v_exp_f32_e32 v164, v164
	v_exp_f32_e32 v165, v165
	v_add_f32_e32 v162, 1.0, v162
	v_add_f32_e32 v163, 1.0, v163
	v_add_f32_e32 v164, 1.0, v164
	v_add_f32_e32 v165, 1.0, v165
	v_rcp_f32_e32 v162, v162
	v_rcp_f32_e32 v163, v163
	v_rcp_f32_e32 v164, v164
	v_rcp_f32_e32 v165, v165
	v_pk_mul_f32 v[118:119], v[118:119], v[162:163]
	v_pk_mul_f32 v[120:121], v[120:121], v[164:165]
	v_mov_b32_dpp v163, v114 row_ror:2 row_mask:0xf bank_mask:0xf bound_ctrl:1
	v_mov_b32_dpp v165, v115 row_ror:2 row_mask:0xf bank_mask:0xf bound_ctrl:1
	v_mov_b32_dpp v162, v114 row_ror:1 row_mask:0xf bank_mask:0xf bound_ctrl:1
	v_cndmask_b32_e64 v164, v175, v163, s[12:13]
	v_mov_b32_dpp v163, v115 row_ror:1 row_mask:0xf bank_mask:0xf bound_ctrl:1
	v_cndmask_b32_e64 v165, v179, v165, s[12:13]
	v_cndmask_b32_e64 v162, v162, v174, s[10:11]
	v_cndmask_b32_e64 v163, v163, v178, s[10:11]
	v_pk_fma_f32 v[164:165], v[134:135], v[164:165], v[142:143]
	v_mov_b32_dpp v166, v116 row_ror:1 row_mask:0xf bank_mask:0xf bound_ctrl:1
	v_pk_fma_f32 v[162:163], v[138:139], v[162:163], v[164:165]
	v_mov_b32_dpp v167, v116 row_ror:2 row_mask:0xf bank_mask:0xf bound_ctrl:1
	v_cndmask_b32_e64 v166, v166, v0, s[10:11]
	v_mov_b32_dpp v0, v117 row_ror:1 row_mask:0xf bank_mask:0xf bound_ctrl:1
	v_pk_fma_f32 v[114:115], v[114:115], v[130:131], v[162:163]
	v_cndmask_b32_e64 v168, v159, v167, s[12:13]
	v_mov_b32_dpp v159, v117 row_ror:2 row_mask:0xf bank_mask:0xf bound_ctrl:1
	v_cndmask_b32_e64 v167, v0, v170, s[10:11]
	v_mul_f32_e32 v0, 0xbfb8aa3b, v114
	v_cndmask_b32_e64 v169, v171, v159, s[12:13]
	v_exp_f32_e32 v0, v0
	v_mul_f32_e32 v159, 0xbfb8aa3b, v115
	v_pk_fma_f32 v[168:169], v[136:137], v[168:169], v[144:145]
	v_exp_f32_e32 v159, v159
	v_pk_fma_f32 v[164:165], v[140:141], v[166:167], v[168:169]
	v_add_f32_e32 v0, 1.0, v0
	v_pk_fma_f32 v[162:163], v[116:117], v[132:133], v[164:165]
	v_rcp_f32_e32 v116, v0
	v_mul_f32_e32 v117, 0xbfb8aa3b, v162
	v_add_f32_e32 v0, 1.0, v159
	v_exp_f32_e32 v159, v117
	v_mul_f32_e32 v117, 0xbfb8aa3b, v163
	v_exp_f32_e32 v165, v117
	v_rcp_f32_e32 v117, v0
	v_add_f32_e32 v0, 1.0, v159
	v_rcp_f32_e32 v164, v0
	v_add_f32_e32 v0, 1.0, v165
	v_rcp_f32_e32 v165, v0
	v_pk_mul_f32 v[116:117], v[114:115], v[116:117]
	v_pk_mul_f32 v[162:163], v[162:163], v[164:165]
	v_mov_b32_dpp v159, v110 row_ror:2 row_mask:0xf bank_mask:0xf bound_ctrl:1
	v_mov_b32_dpp v171, v111 row_ror:2 row_mask:0xf bank_mask:0xf bound_ctrl:1
	v_mov_b32_dpp v0, v110 row_ror:1 row_mask:0xf bank_mask:0xf bound_ctrl:1
	v_cndmask_b32_e64 v164, 0, v159, s[12:13]
	v_mov_b32_dpp v170, v111 row_ror:1 row_mask:0xf bank_mask:0xf bound_ctrl:1
	v_cndmask_b32_e64 v165, 0, v171, s[12:13]
	v_cndmask_b32_e64 v114, v0, 0, s[10:11]
	v_cndmask_b32_e64 v115, v170, 0, s[10:11]
	v_pk_fma_f32 v[164:165], v[134:135], v[164:165], v[142:143]
	v_mov_b32_dpp v173, v112 row_ror:2 row_mask:0xf bank_mask:0xf bound_ctrl:1
	v_pk_fma_f32 v[114:115], v[138:139], v[114:115], v[164:165]
	v_mov_b32_dpp v175, v113 row_ror:2 row_mask:0xf bank_mask:0xf bound_ctrl:1
	v_pk_fma_f32 v[110:111], v[110:111], v[130:131], v[114:115]
	v_mov_b32_dpp v172, v112 row_ror:1 row_mask:0xf bank_mask:0xf bound_ctrl:1
	v_mul_f32_e32 v114, 0xbfb8aa3b, v110
	v_cndmask_b32_e64 v168, 0, v173, s[12:13]
	v_mov_b32_dpp v174, v113 row_ror:1 row_mask:0xf bank_mask:0xf bound_ctrl:1
	v_cndmask_b32_e64 v169, 0, v175, s[12:13]
	v_exp_f32_e32 v164, v114
	v_cndmask_b32_e64 v166, v172, 0, s[10:11]
	v_cndmask_b32_e64 v167, v174, 0, s[10:11]
	v_pk_fma_f32 v[114:115], v[136:137], v[168:169], v[144:145]
	s_nop 0
	v_pk_fma_f32 v[114:115], v[140:141], v[166:167], v[114:115]
	s_nop 0
	v_pk_fma_f32 v[112:113], v[112:113], v[132:133], v[114:115]
	v_add_f32_e32 v114, 1.0, v164
	v_mul_f32_e32 v115, 0xbfb8aa3b, v111
	v_mul_f32_e32 v164, 0xbfb8aa3b, v112
	v_mul_f32_e32 v165, 0xbfb8aa3b, v113
	v_exp_f32_e32 v115, v115
	v_exp_f32_e32 v164, v164
	v_exp_f32_e32 v165, v165
	v_rcp_f32_e32 v114, v114
	v_add_f32_e32 v115, 1.0, v115
	v_add_f32_e32 v164, 1.0, v164
	v_add_f32_e32 v165, 1.0, v165
	v_rcp_f32_e32 v164, v164
	v_rcp_f32_e32 v165, v165
	v_rcp_f32_e32 v115, v115
	v_pk_mul_f32 v[164:165], v[112:113], v[164:165]
	v_pk_mul_f32 v[166:167], v[110:111], v[114:115]
	v_mov_b32_dpp v179, v106 row_ror:2 row_mask:0xf bank_mask:0xf bound_ctrl:1
	v_mov_b32_dpp v181, v108 row_ror:2 row_mask:0xf bank_mask:0xf bound_ctrl:1
	v_mov_b32_dpp v178, v106 row_ror:1 row_mask:0xf bank_mask:0xf bound_ctrl:1
	v_cndmask_b32_e64 v112, v159, v179, s[12:13]
	v_mov_b32_dpp v159, v107 row_ror:2 row_mask:0xf bank_mask:0xf bound_ctrl:1
	v_mov_b32_dpp v180, v108 row_ror:1 row_mask:0xf bank_mask:0xf bound_ctrl:1
	v_cndmask_b32_e64 v168, v173, v181, s[12:13]
	v_mov_b32_dpp v173, v109 row_ror:2 row_mask:0xf bank_mask:0xf bound_ctrl:1
	v_cndmask_b32_e64 v110, v178, v0, s[10:11]
	v_mov_b32_dpp v0, v107 row_ror:1 row_mask:0xf bank_mask:0xf bound_ctrl:1
	v_cndmask_b32_e64 v113, v171, v159, s[12:13]
	v_cndmask_b32_e64 v114, v180, v172, s[10:11]
	v_mov_b32_dpp v172, v109 row_ror:1 row_mask:0xf bank_mask:0xf bound_ctrl:1
	v_cndmask_b32_e64 v169, v175, v173, s[12:13]
; __device__ __forceinline__ unsigned cvt_pk(float lo, float hi) { f32x2_t v = {lo, hi}; bf16x2_t b = __builtin_convertvector(v, bf16x2_t); return __builtin_bit_cast(unsigned, b); }
; __device__ __forceinline__ f32x4 sigm4(f32x4 v) { f32x4 o; o[0] = sigm(v[0]); o[1] = sigm(v[1]); o[2] = sigm(v[2]); o[3] = sigm(v[3]); return o; }
; __device__ __forceinline__ float dppr1(float x) { return __int_as_float(__builtin_amdgcn_mov_dpp(__float_as_int(x), 0x121, 0xf, 0xf, true)); }
; __device__ __forceinline__ float dppr2(float x) { return __int_as_float(__builtin_amdgcn_mov_dpp(__float_as_int(x), 0x122, 0xf, 0xf, true)); }
;     template <int GV, int NH> __device__ __forceinline__ void part(f32x4 (&acc)[2][2][4][2], const Unit& u, int wr, int wc, int fr, int fq) const {
;     ...
;             for (int m = 0; m < 4; ++m) {
;                 const f32x4 x3 = acc[ai][GV][m][NH];
;                 f32x4 c1, c2, x2, x1;
; #pragma unroll
;                 for (int i = 0; i < 4; ++i) { c1[i] = dppr1(x3[i]); c2[i] = dppr2(x3[i]); x2[i] = f1 ? c1[i] : p1[i]; x1[i] = f2 ? c2[i] : p2[i]; }
;                 p1 = c1; p2 = c2;
;                 const f32x4 o = bb + x1 * w0 + x2 * w1 + x3 * w2;
;                 if (GV == 0) acc[ai][0][m][NH] = o * sigm4(o);
;                 else { const f32x4 r = acc[ai][0][m][NH] * o; u32x2 pk; pk.x = cvt_pk(r[0], r[1]); pk.y = cvt_pk(r[2], r[3]); *(u32x2*)(ACT + rowb + (unsigned)(16 * m) * DFF) = pk; }
	v_cndmask_b32_e64 v111, v0, v170, s[10:11]
	v_cndmask_b32_e64 v115, v172, v174, s[10:11]
	v_pk_fma_f32 v[168:169], v[136:137], v[168:169], v[144:145]
	v_pk_fma_f32 v[112:113], v[134:135], v[112:113], v[142:143]
	s_nop 0
	v_pk_fma_f32 v[110:111], v[138:139], v[110:111], v[112:113]
	v_pk_fma_f32 v[112:113], v[140:141], v[114:115], v[168:169]
	v_pk_fma_f32 v[106:107], v[106:107], v[130:131], v[110:111]
	v_pk_fma_f32 v[108:109], v[108:109], v[132:133], v[112:113]
	v_mul_f32_e32 v110, 0xbfb8aa3b, v106
	v_mul_f32_e32 v111, 0xbfb8aa3b, v107
	v_mul_f32_e32 v112, 0xbfb8aa3b, v108
	v_mul_f32_e32 v113, 0xbfb8aa3b, v109
	v_exp_f32_e32 v110, v110
	v_exp_f32_e32 v111, v111
	v_exp_f32_e32 v112, v112
	v_exp_f32_e32 v113, v113
	v_add_f32_e32 v110, 1.0, v110
	v_add_f32_e32 v111, 1.0, v111
	v_add_f32_e32 v112, 1.0, v112
	v_add_f32_e32 v113, 1.0, v113
	v_rcp_f32_e32 v110, v110
	v_rcp_f32_e32 v111, v111
	v_rcp_f32_e32 v112, v112
	v_rcp_f32_e32 v113, v113
	v_pk_mul_f32 v[168:169], v[106:107], v[110:111]
	v_pk_mul_f32 v[170:171], v[108:109], v[112:113]
	v_mov_b32_dpp v115, v102 row_ror:2 row_mask:0xf bank_mask:0xf bound_ctrl:1
	v_mov_b32_dpp v114, v102 row_ror:1 row_mask:0xf bank_mask:0xf bound_ctrl:1
	v_cndmask_b32_e64 v108, v179, v115, s[12:13]
	v_mov_b32_dpp v179, v103 row_ror:2 row_mask:0xf bank_mask:0xf bound_ctrl:1
	v_cndmask_b32_e64 v106, v114, v178, s[10:11]
	v_mov_b32_dpp v178, v103 row_ror:1 row_mask:0xf bank_mask:0xf bound_ctrl:1
	v_cndmask_b32_e64 v109, v159, v179, s[12:13]
	v_mov_b32_dpp v159, v104 row_ror:2 row_mask:0xf bank_mask:0xf bound_ctrl:1
	v_cndmask_b32_e64 v107, v178, v0, s[10:11]
	v_mov_b32_dpp v0, v104 row_ror:1 row_mask:0xf bank_mask:0xf bound_ctrl:1
	v_cndmask_b32_e64 v112, v181, v159, s[12:13]
	v_mov_b32_dpp v181, v105 row_ror:2 row_mask:0xf bank_mask:0xf bound_ctrl:1
	v_cndmask_b32_e64 v110, v0, v180, s[10:11]
	v_mov_b32_dpp v180, v105 row_ror:1 row_mask:0xf bank_mask:0xf bound_ctrl:1
	v_cndmask_b32_e64 v113, v173, v181, s[12:13]
	v_cndmask_b32_e64 v111, v180, v172, s[10:11]
	v_pk_fma_f32 v[112:113], v[136:137], v[112:113], v[144:145]
	v_pk_fma_f32 v[108:109], v[134:135], v[108:109], v[142:143]
	s_nop 0
	v_pk_fma_f32 v[106:107], v[138:139], v[106:107], v[108:109]
	v_pk_fma_f32 v[108:109], v[140:141], v[110:111], v[112:113]
	v_pk_fma_f32 v[102:103], v[102:103], v[130:131], v[106:107]
	v_pk_fma_f32 v[104:105], v[104:105], v[132:133], v[108:109]
	v_mul_f32_e32 v106, 0xbfb8aa3b, v102
	v_mul_f32_e32 v107, 0xbfb8aa3b, v103
	v_mul_f32_e32 v108, 0xbfb8aa3b, v104
	v_mul_f32_e32 v109, 0xbfb8aa3b, v105
	v_exp_f32_e32 v106, v106
	v_exp_f32_e32 v107, v107
	v_exp_f32_e32 v108, v108
	v_exp_f32_e32 v109, v109
	v_add_f32_e32 v106, 1.0, v106
	v_add_f32_e32 v107, 1.0, v107
	v_add_f32_e32 v108, 1.0, v108
	v_add_f32_e32 v109, 1.0, v109
	v_rcp_f32_e32 v106, v106
	v_rcp_f32_e32 v107, v107
	v_rcp_f32_e32 v108, v108
	v_rcp_f32_e32 v109, v109
	v_pk_mul_f32 v[172:173], v[102:103], v[106:107]
	v_pk_mul_f32 v[174:175], v[104:105], v[108:109]
	v_mov_b32_dpp v103, v98 row_ror:2 row_mask:0xf bank_mask:0xf bound_ctrl:1
	v_mov_b32_dpp v105, v99 row_ror:2 row_mask:0xf bank_mask:0xf bound_ctrl:1
	v_mov_b32_dpp v102, v98 row_ror:1 row_mask:0xf bank_mask:0xf bound_ctrl:1
	v_cndmask_b32_e64 v104, v115, v103, s[12:13]
	v_mov_b32_dpp v103, v99 row_ror:1 row_mask:0xf bank_mask:0xf bound_ctrl:1
	v_cndmask_b32_e64 v105, v179, v105, s[12:13]
	v_cndmask_b32_e64 v102, v102, v114, s[10:11]
	v_cndmask_b32_e64 v103, v103, v178, s[10:11]
	v_pk_fma_f32 v[104:105], v[134:135], v[104:105], v[142:143]
	v_mov_b32_dpp v106, v100 row_ror:1 row_mask:0xf bank_mask:0xf bound_ctrl:1
	v_pk_fma_f32 v[102:103], v[138:139], v[102:103], v[104:105]
	v_mov_b32_dpp v107, v100 row_ror:2 row_mask:0xf bank_mask:0xf bound_ctrl:1
	v_cndmask_b32_e64 v106, v106, v0, s[10:11]
	v_mov_b32_dpp v0, v101 row_ror:1 row_mask:0xf bank_mask:0xf bound_ctrl:1
	v_pk_fma_f32 v[98:99], v[98:99], v[130:131], v[102:103]
	v_cndmask_b32_e64 v108, v159, v107, s[12:13]
	v_cndmask_b32_e64 v107, v0, v180, s[10:11]
	v_mul_f32_e32 v0, 0xbfb8aa3b, v98
	v_mov_b32_dpp v109, v101 row_ror:2 row_mask:0xf bank_mask:0xf bound_ctrl:1
	v_exp_f32_e32 v0, v0
	v_mul_f32_e32 v102, 0xbfb8aa3b, v99
	v_cndmask_b32_e64 v109, v181, v109, s[12:13]
	v_exp_f32_e32 v103, v102
	v_pk_fma_f32 v[108:109], v[136:137], v[108:109], v[144:145]
	v_add_f32_e32 v0, 1.0, v0
	v_pk_fma_f32 v[104:105], v[140:141], v[106:107], v[108:109]
	v_rcp_f32_e32 v102, v0
	v_pk_fma_f32 v[100:101], v[100:101], v[132:133], v[104:105]
	v_add_f32_e32 v0, 1.0, v103
	v_mul_f32_e32 v103, 0xbfb8aa3b, v100
	v_exp_f32_e32 v104, v103
	v_mul_f32_e32 v103, 0xbfb8aa3b, v101
	v_exp_f32_e32 v105, v103
	v_rcp_f32_e32 v103, v0
	v_add_f32_e32 v0, 1.0, v104
	v_rcp_f32_e32 v104, v0
	v_add_f32_e32 v0, 1.0, v105
	v_rcp_f32_e32 v105, v0
	v_pk_mul_f32 v[132:133], v[98:99], v[102:103]
	v_pk_mul_f32 v[134:135], v[100:101], v[104:105]
	v_or_b32_e32 v114, 4, v158
	v_ashrrev_i32_e32 v115, 31, v114
	v_lshlrev_b64 v[130:131], 2, v[114:115]
	v_mov_b32_dpp v115, v94 row_ror:2 row_mask:0xf bank_mask:0xf bound_ctrl:1
	v_mov_b32_dpp v145, v95 row_ror:2 row_mask:0xf bank_mask:0xf bound_ctrl:1
	v_mov_b32_dpp v176, v96 row_ror:2 row_mask:0xf bank_mask:0xf bound_ctrl:1
	v_mov_b32_dpp v178, v97 row_ror:2 row_mask:0xf bank_mask:0xf bound_ctrl:1
	v_mov_b32_dpp v0, v94 row_ror:1 row_mask:0xf bank_mask:0xf bound_ctrl:1
	v_mov_b32_dpp v144, v95 row_ror:1 row_mask:0xf bank_mask:0xf bound_ctrl:1
	v_mov_b32_dpp v159, v96 row_ror:1 row_mask:0xf bank_mask:0xf bound_ctrl:1
	v_mov_b32_dpp v177, v97 row_ror:1 row_mask:0xf bank_mask:0xf bound_ctrl:1
	v_cndmask_b32_e64 v138, 0, v115, s[12:13]
	v_cndmask_b32_e64 v139, 0, v145, s[12:13]
	v_cndmask_b32_e64 v142, 0, v176, s[12:13]
	v_cndmask_b32_e64 v143, 0, v178, s[12:13]
	v_cndmask_b32_e64 v136, v0, 0, s[10:11]
	v_cndmask_b32_e64 v137, v144, 0, s[10:11]
	v_cndmask_b32_e64 v140, v159, 0, s[10:11]
	v_cndmask_b32_e64 v141, v177, 0, s[10:11]
	s_waitcnt vmcnt(2)
; __device__ __forceinline__ unsigned cvt_pk(float lo, float hi) { f32x2_t v = {lo, hi}; bf16x2_t b = __builtin_convertvector(v, bf16x2_t); return __builtin_bit_cast(unsigned, b); }
; __device__ __forceinline__ f32x4 sigm4(f32x4 v) { f32x4 o; o[0] = sigm(v[0]); o[1] = sigm(v[1]); o[2] = sigm(v[2]); o[3] = sigm(v[3]); return o; }
; __device__ __forceinline__ float dppr1(float x) { return __int_as_float(__builtin_amdgcn_mov_dpp(__float_as_int(x), 0x121, 0xf, 0xf, true)); }
; __device__ __forceinline__ float dppr2(float x) { return __int_as_float(__builtin_amdgcn_mov_dpp(__float_as_int(x), 0x122, 0xf, 0xf, true)); }
;     template <int GV, int NH> __device__ __forceinline__ void part(f32x4 (&acc)[2][2][4][2], const Unit& u, int wr, int wc, int fr, int fq) const {
;     ...
;             for (int m = 0; m < 4; ++m) {
;                 const f32x4 x3 = acc[ai][GV][m][NH];
;                 f32x4 c1, c2, x2, x1;
; #pragma unroll
;                 for (int i = 0; i < 4; ++i) { c1[i] = dppr1(x3[i]); c2[i] = dppr2(x3[i]); x2[i] = f1 ? c1[i] : p1[i]; x1[i] = f2 ? c2[i] : p2[i]; }
;                 p1 = c1; p2 = c2;
;                 const f32x4 o = bb + x1 * w0 + x2 * w1 + x3 * w2;
;                 if (GV == 0) acc[ai][0][m][NH] = o * sigm4(o);
;                 else { const f32x4 r = acc[ai][0][m][NH] * o; u32x2 pk; pk.x = cvt_pk(r[0], r[1]); pk.y = cvt_pk(r[2], r[3]); *(u32x2*)(ACT + rowb + (unsigned)(16 * m) * DFF) = pk; }
	v_pk_fma_f32 v[142:143], v[200:201], v[142:143], v[204:205]
	v_pk_fma_f32 v[138:139], v[198:199], v[138:139], v[202:203]
	s_waitcnt vmcnt(1)
	v_pk_fma_f32 v[136:137], v[206:207], v[136:137], v[138:139]
	v_pk_fma_f32 v[138:139], v[208:209], v[140:141], v[142:143]
	s_waitcnt vmcnt(0)
	v_pk_fma_f32 v[94:95], v[94:95], v[210:211], v[136:137]
	v_pk_fma_f32 v[96:97], v[96:97], v[212:213], v[138:139]
	v_mul_f32_e32 v136, 0xbfb8aa3b, v94
	v_mul_f32_e32 v137, 0xbfb8aa3b, v95
	v_mul_f32_e32 v138, 0xbfb8aa3b, v96
	v_mul_f32_e32 v139, 0xbfb8aa3b, v97
	v_exp_f32_e32 v136, v136
	v_exp_f32_e32 v137, v137
	v_exp_f32_e32 v138, v138
	v_exp_f32_e32 v139, v139
	v_add_f32_e32 v136, 1.0, v136
	v_add_f32_e32 v137, 1.0, v137
	v_add_f32_e32 v138, 1.0, v138
	v_add_f32_e32 v139, 1.0, v139
	v_rcp_f32_e32 v136, v136
	v_rcp_f32_e32 v137, v137
	v_rcp_f32_e32 v138, v138
	v_rcp_f32_e32 v139, v139
	v_pk_mul_f32 v[94:95], v[94:95], v[136:137]
	v_pk_mul_f32 v[96:97], v[96:97], v[138:139]
	v_mov_b32_dpp v180, v90 row_ror:2 row_mask:0xf bank_mask:0xf bound_ctrl:1
	v_mov_b32_dpp v179, v90 row_ror:1 row_mask:0xf bank_mask:0xf bound_ctrl:1
	v_cndmask_b32_e64 v138, v115, v180, s[12:13]
	v_mov_b32_dpp v115, v91 row_ror:2 row_mask:0xf bank_mask:0xf bound_ctrl:1
	v_cndmask_b32_e64 v136, v179, v0, s[10:11]
	v_mov_b32_dpp v0, v91 row_ror:1 row_mask:0xf bank_mask:0xf bound_ctrl:1
	v_cndmask_b32_e64 v139, v145, v115, s[12:13]
	v_cndmask_b32_e64 v137, v0, v144, s[10:11]
	v_pk_fma_f32 v[138:139], v[198:199], v[138:139], v[202:203]
	v_mov_b32_dpp v145, v92 row_ror:2 row_mask:0xf bank_mask:0xf bound_ctrl:1
	v_pk_fma_f32 v[136:137], v[206:207], v[136:137], v[138:139]
	v_mov_b32_dpp v144, v92 row_ror:1 row_mask:0xf bank_mask:0xf bound_ctrl:1
	v_pk_fma_f32 v[136:137], v[90:91], v[210:211], v[136:137]
	v_cndmask_b32_e64 v142, v176, v145, s[12:13]
	v_mov_b32_dpp v176, v93 row_ror:2 row_mask:0xf bank_mask:0xf bound_ctrl:1
	v_mul_f32_e32 v90, 0xbfb8aa3b, v136
	v_cndmask_b32_e64 v140, v144, v159, s[10:11]
	v_mov_b32_dpp v159, v93 row_ror:1 row_mask:0xf bank_mask:0xf bound_ctrl:1
	v_cndmask_b32_e64 v143, v178, v176, s[12:13]
	v_exp_f32_e32 v138, v90
	v_cndmask_b32_e64 v141, v159, v177, s[10:11]
	v_pk_fma_f32 v[90:91], v[200:201], v[142:143], v[204:205]
	s_nop 0
	v_pk_fma_f32 v[90:91], v[208:209], v[140:141], v[90:91]
	s_nop 0
	v_pk_fma_f32 v[90:91], v[92:93], v[212:213], v[90:91]
	v_add_f32_e32 v92, 1.0, v138
	v_mul_f32_e32 v93, 0xbfb8aa3b, v137
	v_mul_f32_e32 v138, 0xbfb8aa3b, v90
	v_mul_f32_e32 v139, 0xbfb8aa3b, v91
	v_exp_f32_e32 v93, v93
	v_exp_f32_e32 v138, v138
	v_exp_f32_e32 v139, v139
	v_rcp_f32_e32 v92, v92
	v_add_f32_e32 v93, 1.0, v93
	v_add_f32_e32 v138, 1.0, v138
	v_add_f32_e32 v139, 1.0, v139
	v_rcp_f32_e32 v138, v138
	v_rcp_f32_e32 v139, v139
	v_rcp_f32_e32 v93, v93
	v_pk_mul_f32 v[90:91], v[90:91], v[138:139]
	v_pk_mul_f32 v[92:93], v[136:137], v[92:93]
	v_mov_b32_dpp v178, v86 row_ror:2 row_mask:0xf bank_mask:0xf bound_ctrl:1
	v_mov_b32_dpp v177, v86 row_ror:1 row_mask:0xf bank_mask:0xf bound_ctrl:1
	v_cndmask_b32_e64 v138, v180, v178, s[12:13]
	v_mov_b32_dpp v180, v87 row_ror:2 row_mask:0xf bank_mask:0xf bound_ctrl:1
	v_cndmask_b32_e64 v136, v177, v179, s[10:11]
	v_mov_b32_dpp v179, v87 row_ror:1 row_mask:0xf bank_mask:0xf bound_ctrl:1
	v_cndmask_b32_e64 v139, v115, v180, s[12:13]
	v_cndmask_b32_e64 v137, v179, v0, s[10:11]
	v_pk_fma_f32 v[138:139], v[198:199], v[138:139], v[202:203]
	v_mov_b32_dpp v115, v88 row_ror:2 row_mask:0xf bank_mask:0xf bound_ctrl:1
	v_pk_fma_f32 v[136:137], v[206:207], v[136:137], v[138:139]
	v_mov_b32_dpp v0, v88 row_ror:1 row_mask:0xf bank_mask:0xf bound_ctrl:1
	v_pk_fma_f32 v[136:137], v[86:87], v[210:211], v[136:137]
	v_cndmask_b32_e64 v142, v145, v115, s[12:13]
	v_mov_b32_dpp v145, v89 row_ror:2 row_mask:0xf bank_mask:0xf bound_ctrl:1
	v_mul_f32_e32 v86, 0xbfb8aa3b, v136
	v_cndmask_b32_e64 v140, v0, v144, s[10:11]
	v_mov_b32_dpp v144, v89 row_ror:1 row_mask:0xf bank_mask:0xf bound_ctrl:1
	v_cndmask_b32_e64 v143, v176, v145, s[12:13]
	v_exp_f32_e32 v138, v86
	v_cndmask_b32_e64 v141, v144, v159, s[10:11]
	v_pk_fma_f32 v[86:87], v[200:201], v[142:143], v[204:205]
	s_nop 0
	v_pk_fma_f32 v[86:87], v[208:209], v[140:141], v[86:87]
	s_nop 0
	v_pk_fma_f32 v[86:87], v[88:89], v[212:213], v[86:87]
	v_add_f32_e32 v88, 1.0, v138
	v_mul_f32_e32 v89, 0xbfb8aa3b, v137
	v_mul_f32_e32 v138, 0xbfb8aa3b, v86
	v_mul_f32_e32 v139, 0xbfb8aa3b, v87
	v_exp_f32_e32 v89, v89
	v_exp_f32_e32 v138, v138
	v_exp_f32_e32 v139, v139
	v_rcp_f32_e32 v88, v88
	v_add_f32_e32 v89, 1.0, v89
	v_add_f32_e32 v138, 1.0, v138
	v_add_f32_e32 v139, 1.0, v139
	v_rcp_f32_e32 v138, v138
	v_rcp_f32_e32 v139, v139
	v_rcp_f32_e32 v89, v89
	v_pk_mul_f32 v[86:87], v[86:87], v[138:139]
	v_pk_mul_f32 v[88:89], v[136:137], v[88:89]
	v_mov_b32_dpp v137, v82 row_ror:2 row_mask:0xf bank_mask:0xf bound_ctrl:1
	v_mov_b32_dpp v139, v83 row_ror:2 row_mask:0xf bank_mask:0xf bound_ctrl:1
	v_mov_b32_dpp v136, v82 row_ror:1 row_mask:0xf bank_mask:0xf bound_ctrl:1
	v_cndmask_b32_e64 v138, v178, v137, s[12:13]
	v_mov_b32_dpp v137, v83 row_ror:1 row_mask:0xf bank_mask:0xf bound_ctrl:1
	v_cndmask_b32_e64 v139, v180, v139, s[12:13]
	v_cndmask_b32_e64 v136, v136, v177, s[10:11]
	v_cndmask_b32_e64 v137, v137, v179, s[10:11]
	v_pk_fma_f32 v[138:139], v[198:199], v[138:139], v[202:203]
	v_mov_b32_dpp v140, v84 row_ror:1 row_mask:0xf bank_mask:0xf bound_ctrl:1
	v_pk_fma_f32 v[136:137], v[206:207], v[136:137], v[138:139]
	v_mov_b32_dpp v141, v84 row_ror:2 row_mask:0xf bank_mask:0xf bound_ctrl:1
	v_cndmask_b32_e64 v140, v140, v0, s[10:11]
	v_mov_b32_dpp v0, v85 row_ror:1 row_mask:0xf bank_mask:0xf bound_ctrl:1
; __device__ __forceinline__ unsigned cvt_pk(float lo, float hi) { f32x2_t v = {lo, hi}; bf16x2_t b = __builtin_convertvector(v, bf16x2_t); return __builtin_bit_cast(unsigned, b); }
; __device__ __forceinline__ f32x4 sigm4(f32x4 v) { f32x4 o; o[0] = sigm(v[0]); o[1] = sigm(v[1]); o[2] = sigm(v[2]); o[3] = sigm(v[3]); return o; }
; __device__ __forceinline__ float dppr1(float x) { return __int_as_float(__builtin_amdgcn_mov_dpp(__float_as_int(x), 0x121, 0xf, 0xf, true)); }
; __device__ __forceinline__ float dppr2(float x) { return __int_as_float(__builtin_amdgcn_mov_dpp(__float_as_int(x), 0x122, 0xf, 0xf, true)); }
;     template <int GV, int NH> __device__ __forceinline__ void part(f32x4 (&acc)[2][2][4][2], const Unit& u, int wr, int wc, int fr, int fq) const {
;     ...
;             for (int m = 0; m < 4; ++m) {
;                 const f32x4 x3 = acc[ai][GV][m][NH];
;                 f32x4 c1, c2, x2, x1;
; #pragma unroll
;                 for (int i = 0; i < 4; ++i) { c1[i] = dppr1(x3[i]); c2[i] = dppr2(x3[i]); x2[i] = f1 ? c1[i] : p1[i]; x1[i] = f2 ? c2[i] : p2[i]; }
;                 p1 = c1; p2 = c2;
;                 const f32x4 o = bb + x1 * w0 + x2 * w1 + x3 * w2;
;                 if (GV == 0) acc[ai][0][m][NH] = o * sigm4(o);
;                 else { const f32x4 r = acc[ai][0][m][NH] * o; u32x2 pk; pk.x = cvt_pk(r[0], r[1]); pk.y = cvt_pk(r[2], r[3]); *(u32x2*)(ACT + rowb + (unsigned)(16 * m) * DFF) = pk; }
	v_pk_fma_f32 v[136:137], v[82:83], v[210:211], v[136:137]
	v_cndmask_b32_e64 v142, v115, v141, s[12:13]
	v_mov_b32_dpp v115, v85 row_ror:2 row_mask:0xf bank_mask:0xf bound_ctrl:1
	v_cndmask_b32_e64 v141, v0, v144, s[10:11]
	v_mul_f32_e32 v0, 0xbfb8aa3b, v136
	v_cndmask_b32_e64 v143, v145, v115, s[12:13]
	v_exp_f32_e32 v0, v0
	v_pk_fma_f32 v[82:83], v[200:201], v[142:143], v[204:205]
	v_add_f32_e32 v0, 1.0, v0
	v_pk_fma_f32 v[82:83], v[208:209], v[140:141], v[82:83]
	s_nop 0
	v_pk_fma_f32 v[82:83], v[84:85], v[212:213], v[82:83]
	v_rcp_f32_e32 v84, v0
	v_mul_f32_e32 v85, 0xbfb8aa3b, v82
	v_mul_f32_e32 v0, 0xbfb8aa3b, v137
	v_exp_f32_e32 v85, v85
	v_mul_f32_e32 v115, 0xbfb8aa3b, v83
	v_exp_f32_e32 v0, v0
	v_exp_f32_e32 v115, v115
	v_add_f32_e32 v85, 1.0, v85
	v_rcp_f32_e32 v138, v85
	v_add_f32_e32 v0, 1.0, v0
	v_add_f32_e32 v85, 1.0, v115
	v_rcp_f32_e32 v139, v85
	v_rcp_f32_e32 v85, v0
	v_pk_mul_f32 v[82:83], v[82:83], v[138:139]
	v_pk_mul_f32 v[84:85], v[136:137], v[84:85]
	v_mov_b32_dpp v115, v78 row_ror:2 row_mask:0xf bank_mask:0xf bound_ctrl:1
	v_mov_b32_dpp v145, v79 row_ror:2 row_mask:0xf bank_mask:0xf bound_ctrl:1
	v_mov_b32_dpp v176, v80 row_ror:2 row_mask:0xf bank_mask:0xf bound_ctrl:1
	v_mov_b32_dpp v178, v81 row_ror:2 row_mask:0xf bank_mask:0xf bound_ctrl:1
	v_mov_b32_dpp v0, v78 row_ror:1 row_mask:0xf bank_mask:0xf bound_ctrl:1
	v_cndmask_b32_e64 v138, 0, v115, s[12:13]
	v_mov_b32_dpp v144, v79 row_ror:1 row_mask:0xf bank_mask:0xf bound_ctrl:1
	v_cndmask_b32_e64 v139, 0, v145, s[12:13]
	v_mov_b32_dpp v159, v80 row_ror:1 row_mask:0xf bank_mask:0xf bound_ctrl:1
	v_cndmask_b32_e64 v142, 0, v176, s[12:13]
	v_mov_b32_dpp v177, v81 row_ror:1 row_mask:0xf bank_mask:0xf bound_ctrl:1
	v_cndmask_b32_e64 v143, 0, v178, s[12:13]
	v_cndmask_b32_e64 v136, v0, 0, s[10:11]
	v_cndmask_b32_e64 v137, v144, 0, s[10:11]
	v_cndmask_b32_e64 v140, v159, 0, s[10:11]
	v_cndmask_b32_e64 v141, v177, 0, s[10:11]
	v_pk_fma_f32 v[142:143], v[200:201], v[142:143], v[204:205]
	v_pk_fma_f32 v[138:139], v[198:199], v[138:139], v[202:203]
	s_nop 0
	v_pk_fma_f32 v[136:137], v[206:207], v[136:137], v[138:139]
	v_pk_fma_f32 v[138:139], v[208:209], v[140:141], v[142:143]
	v_pk_fma_f32 v[78:79], v[78:79], v[210:211], v[136:137]
	v_pk_fma_f32 v[80:81], v[80:81], v[212:213], v[138:139]
	v_mul_f32_e32 v136, 0xbfb8aa3b, v78
	v_mul_f32_e32 v137, 0xbfb8aa3b, v79
	v_mul_f32_e32 v138, 0xbfb8aa3b, v80
	v_mul_f32_e32 v139, 0xbfb8aa3b, v81
	v_exp_f32_e32 v136, v136
	v_exp_f32_e32 v137, v137
	v_exp_f32_e32 v138, v138
	v_exp_f32_e32 v139, v139
	v_add_f32_e32 v136, 1.0, v136
	v_add_f32_e32 v137, 1.0, v137
	v_add_f32_e32 v138, 1.0, v138
	v_add_f32_e32 v139, 1.0, v139
	v_rcp_f32_e32 v136, v136
	v_rcp_f32_e32 v137, v137
	v_rcp_f32_e32 v138, v138
	v_rcp_f32_e32 v139, v139
	v_pk_mul_f32 v[136:137], v[78:79], v[136:137]
	v_pk_mul_f32 v[138:139], v[80:81], v[138:139]
	v_mov_b32_dpp v180, v74 row_ror:2 row_mask:0xf bank_mask:0xf bound_ctrl:1
	v_mov_b32_dpp v179, v74 row_ror:1 row_mask:0xf bank_mask:0xf bound_ctrl:1
	v_cndmask_b32_e64 v80, v115, v180, s[12:13]
	v_mov_b32_dpp v115, v75 row_ror:2 row_mask:0xf bank_mask:0xf bound_ctrl:1
	v_cndmask_b32_e64 v78, v179, v0, s[10:11]
	v_mov_b32_dpp v0, v75 row_ror:1 row_mask:0xf bank_mask:0xf bound_ctrl:1
	v_cndmask_b32_e64 v81, v145, v115, s[12:13]
	v_cndmask_b32_e64 v79, v0, v144, s[10:11]
	v_pk_fma_f32 v[80:81], v[198:199], v[80:81], v[202:203]
	v_mov_b32_dpp v145, v76 row_ror:2 row_mask:0xf bank_mask:0xf bound_ctrl:1
	v_pk_fma_f32 v[78:79], v[206:207], v[78:79], v[80:81]
	v_mov_b32_dpp v144, v76 row_ror:1 row_mask:0xf bank_mask:0xf bound_ctrl:1
	v_pk_fma_f32 v[74:75], v[74:75], v[210:211], v[78:79]
	v_cndmask_b32_e64 v142, v176, v145, s[12:13]
	v_mov_b32_dpp v176, v77 row_ror:2 row_mask:0xf bank_mask:0xf bound_ctrl:1
	v_mul_f32_e32 v78, 0xbfb8aa3b, v74
	v_cndmask_b32_e64 v140, v144, v159, s[10:11]
	v_mov_b32_dpp v159, v77 row_ror:1 row_mask:0xf bank_mask:0xf bound_ctrl:1
	v_cndmask_b32_e64 v143, v178, v176, s[12:13]
	v_exp_f32_e32 v80, v78
	v_cndmask_b32_e64 v141, v159, v177, s[10:11]
	v_pk_fma_f32 v[78:79], v[200:201], v[142:143], v[204:205]
	s_nop 0
	v_pk_fma_f32 v[78:79], v[208:209], v[140:141], v[78:79]
	s_nop 0
	v_pk_fma_f32 v[76:77], v[76:77], v[212:213], v[78:79]
	v_add_f32_e32 v78, 1.0, v80
	v_mul_f32_e32 v79, 0xbfb8aa3b, v75
	v_mul_f32_e32 v80, 0xbfb8aa3b, v76
	v_mul_f32_e32 v81, 0xbfb8aa3b, v77
	v_exp_f32_e32 v79, v79
	v_exp_f32_e32 v80, v80
	v_exp_f32_e32 v81, v81
	v_rcp_f32_e32 v78, v78
	v_add_f32_e32 v79, 1.0, v79
	v_add_f32_e32 v80, 1.0, v80
	v_add_f32_e32 v81, 1.0, v81
	v_rcp_f32_e32 v80, v80
	v_rcp_f32_e32 v81, v81
	v_rcp_f32_e32 v79, v79
	v_pk_mul_f32 v[140:141], v[76:77], v[80:81]
	v_pk_mul_f32 v[142:143], v[74:75], v[78:79]
	v_mov_b32_dpp v181, v70 row_ror:2 row_mask:0xf bank_mask:0xf bound_ctrl:1
	v_mov_b32_dpp v178, v70 row_ror:1 row_mask:0xf bank_mask:0xf bound_ctrl:1
	v_cndmask_b32_e64 v76, v180, v181, s[12:13]
	v_mov_b32_dpp v180, v71 row_ror:2 row_mask:0xf bank_mask:0xf bound_ctrl:1
	v_cndmask_b32_e64 v74, v178, v179, s[10:11]
	v_mov_b32_dpp v179, v71 row_ror:1 row_mask:0xf bank_mask:0xf bound_ctrl:1
	v_cndmask_b32_e64 v77, v115, v180, s[12:13]
	v_cndmask_b32_e64 v75, v179, v0, s[10:11]
	v_pk_fma_f32 v[76:77], v[198:199], v[76:77], v[202:203]
	v_mov_b32_dpp v115, v72 row_ror:2 row_mask:0xf bank_mask:0xf bound_ctrl:1
	v_pk_fma_f32 v[74:75], v[206:207], v[74:75], v[76:77]
	v_mov_b32_dpp v187, v73 row_ror:2 row_mask:0xf bank_mask:0xf bound_ctrl:1
	v_pk_fma_f32 v[70:71], v[70:71], v[210:211], v[74:75]
	v_mov_b32_dpp v0, v72 row_ror:1 row_mask:0xf bank_mask:0xf bound_ctrl:1
	v_mul_f32_e32 v74, 0xbfb8aa3b, v70
; __device__ __forceinline__ unsigned cvt_pk(float lo, float hi) { f32x2_t v = {lo, hi}; bf16x2_t b = __builtin_convertvector(v, bf16x2_t); return __builtin_bit_cast(unsigned, b); }
; __device__ __forceinline__ f32x4 sigm4(f32x4 v) { f32x4 o; o[0] = sigm(v[0]); o[1] = sigm(v[1]); o[2] = sigm(v[2]); o[3] = sigm(v[3]); return o; }
; __device__ __forceinline__ float dppr1(float x) { return __int_as_float(__builtin_amdgcn_mov_dpp(__float_as_int(x), 0x121, 0xf, 0xf, true)); }
; __device__ __forceinline__ float dppr2(float x) { return __int_as_float(__builtin_amdgcn_mov_dpp(__float_as_int(x), 0x122, 0xf, 0xf, true)); }
;     template <int GV, int NH> __device__ __forceinline__ void part(f32x4 (&acc)[2][2][4][2], const Unit& u, int wr, int wc, int fr, int fq) const {
;         const int jg = 128 * u.pn + 32 * wc + 8 * fq + 4 * NH;
;         const f32x4 w0 = *(const f32x4*)(cw + GV * DFF + jg), w1 = *(const f32x4*)(cw + NUP + GV * DFF + jg), w2 = *(const f32x4*)(cw + 2 * NUP + GV * DFF + jg), bb = *(const f32x4*)(cb + GV * DFF + jg);
;         const bool f1 = fr >= 1, f2 = fr >= 2;
; #pragma unroll
;         for (int ai = 0; ai < 2; ++ai) {
;             const unsigned rowb = (unsigned)(u.pm * 256 + ai * 128 + wr * 64 + fr) * DFF + jg;
;             f32x4 p1 = (f32x4){0.f, 0.f, 0.f, 0.f}, p2 = p1;
; #pragma unroll
;             for (int m = 0; m < 4; ++m) {
;                 const f32x4 x3 = acc[ai][GV][m][NH];
;                 f32x4 c1, c2, x2, x1;
; #pragma unroll
;                 for (int i = 0; i < 4; ++i) { c1[i] = dppr1(x3[i]); c2[i] = dppr2(x3[i]); x2[i] = f1 ? c1[i] : p1[i]; x1[i] = f2 ? c2[i] : p2[i]; }
;                 p1 = c1; p2 = c2;
;                 const f32x4 o = bb + x1 * w0 + x2 * w1 + x3 * w2;
;                 if (GV == 0) acc[ai][0][m][NH] = o * sigm4(o);
;                 else { const f32x4 r = acc[ai][0][m][NH] * o; u32x2 pk; pk.x = cvt_pk(r[0], r[1]); pk.y = cvt_pk(r[2], r[3]); *(u32x2*)(ACT + rowb + (unsigned)(16 * m) * DFF) = pk; }
;                 __builtin_amdgcn_sched_barrier(0);
	v_cndmask_b32_e64 v80, v145, v115, s[12:13]
	v_mov_b32_dpp v186, v73 row_ror:1 row_mask:0xf bank_mask:0xf bound_ctrl:1
	v_cndmask_b32_e64 v81, v176, v187, s[12:13]
	v_exp_f32_e32 v76, v74
	v_cndmask_b32_e64 v78, v0, v144, s[10:11]
	v_cndmask_b32_e64 v79, v186, v159, s[10:11]
	v_pk_fma_f32 v[74:75], v[200:201], v[80:81], v[204:205]
	s_nop 0
	v_pk_fma_f32 v[74:75], v[208:209], v[78:79], v[74:75]
	s_nop 0
	v_pk_fma_f32 v[72:73], v[72:73], v[212:213], v[74:75]
	v_add_f32_e32 v74, 1.0, v76
	v_mul_f32_e32 v75, 0xbfb8aa3b, v71
	v_mul_f32_e32 v76, 0xbfb8aa3b, v72
	v_mul_f32_e32 v77, 0xbfb8aa3b, v73
	v_exp_f32_e32 v75, v75
	v_exp_f32_e32 v76, v76
	v_exp_f32_e32 v77, v77
	v_rcp_f32_e32 v74, v74
	v_add_f32_e32 v75, 1.0, v75
	v_add_f32_e32 v76, 1.0, v76
	v_add_f32_e32 v77, 1.0, v77
	v_rcp_f32_e32 v76, v76
	v_rcp_f32_e32 v77, v77
	v_rcp_f32_e32 v75, v75
	v_pk_mul_f32 v[144:145], v[72:73], v[76:77]
	v_pk_mul_f32 v[176:177], v[70:71], v[74:75]
	v_mov_b32_dpp v71, v66 row_ror:2 row_mask:0xf bank_mask:0xf bound_ctrl:1
	v_mov_b32_dpp v73, v67 row_ror:2 row_mask:0xf bank_mask:0xf bound_ctrl:1
	v_mov_b32_dpp v70, v66 row_ror:1 row_mask:0xf bank_mask:0xf bound_ctrl:1
	v_cndmask_b32_e64 v72, v181, v71, s[12:13]
	v_mov_b32_dpp v71, v67 row_ror:1 row_mask:0xf bank_mask:0xf bound_ctrl:1
	v_cndmask_b32_e64 v73, v180, v73, s[12:13]
	v_cndmask_b32_e64 v70, v70, v178, s[10:11]
	v_cndmask_b32_e64 v71, v71, v179, s[10:11]
	v_pk_fma_f32 v[72:73], v[198:199], v[72:73], v[202:203]
	v_mov_b32_dpp v74, v68 row_ror:1 row_mask:0xf bank_mask:0xf bound_ctrl:1
	v_pk_fma_f32 v[70:71], v[206:207], v[70:71], v[72:73]
	v_mov_b32_dpp v75, v68 row_ror:2 row_mask:0xf bank_mask:0xf bound_ctrl:1
	v_cndmask_b32_e64 v74, v74, v0, s[10:11]
	v_mov_b32_dpp v0, v69 row_ror:1 row_mask:0xf bank_mask:0xf bound_ctrl:1
	v_pk_fma_f32 v[66:67], v[66:67], v[210:211], v[70:71]
	v_cndmask_b32_e64 v76, v115, v75, s[12:13]
	v_mov_b32_dpp v77, v69 row_ror:2 row_mask:0xf bank_mask:0xf bound_ctrl:1
	v_cndmask_b32_e64 v75, v0, v186, s[10:11]
	v_mul_f32_e32 v0, 0xbfb8aa3b, v66
	v_cndmask_b32_e64 v77, v187, v77, s[12:13]
	v_exp_f32_e32 v0, v0
	v_pk_fma_f32 v[70:71], v[200:201], v[76:77], v[204:205]
	v_add_f32_e32 v0, 1.0, v0
	v_pk_fma_f32 v[70:71], v[208:209], v[74:75], v[70:71]
	s_nop 0
	v_pk_fma_f32 v[68:69], v[68:69], v[212:213], v[70:71]
	v_rcp_f32_e32 v70, v0
	v_mul_f32_e32 v71, 0xbfb8aa3b, v68
	v_mul_f32_e32 v0, 0xbfb8aa3b, v67
	v_exp_f32_e32 v71, v71
	v_mul_f32_e32 v72, 0xbfb8aa3b, v69
	v_exp_f32_e32 v0, v0
	v_exp_f32_e32 v73, v72
	v_add_f32_e32 v71, 1.0, v71
	v_rcp_f32_e32 v72, v71
	v_add_f32_e32 v0, 1.0, v0
	v_add_f32_e32 v71, 1.0, v73
	v_rcp_f32_e32 v73, v71
	v_rcp_f32_e32 v71, v0
	v_pk_mul_f32 v[98:99], v[68:69], v[72:73]
	v_pk_mul_f32 v[100:101], v[66:67], v[70:71]
	v_lshl_add_u64 v[66:67], s[56:57], 0, v[160:161]
	v_lshl_add_u64 v[70:71], s[76:77], 0, v[160:161]
	global_load_dwordx4 v[66:69], v[66:67], off
	v_mov_b32_dpp v111, v62 row_ror:2 row_mask:0xf bank_mask:0xf bound_ctrl:1
	global_load_dwordx4 v[78:81], v[70:71], off
	v_lshl_add_u64 v[70:71], s[58:59], 0, v[160:161]
	global_load_dwordx4 v[74:77], v[70:71], off
	v_lshl_add_u64 v[70:71], s[66:67], 0, v[160:161]
	global_load_dwordx4 v[70:73], v[70:71], off
	v_lshl_add_u64 v[232:233], s[56:57], 0, v[160:161]
	global_load_dwordx4 v[238:241], v[232:233], off offset:16
	v_lshl_add_u64 v[232:233], s[76:77], 0, v[160:161]
	global_load_dwordx4 v[242:245], v[232:233], off offset:16
	v_lshl_add_u64 v[232:233], s[58:59], 0, v[160:161]
	global_load_dwordx4 v[198:201], v[232:233], off offset:16
	v_lshl_add_u64 v[232:233], s[66:67], 0, v[160:161]
	global_load_dwordx4 v[202:205], v[232:233], off offset:16
	v_mov_b32_dpp v113, v63 row_ror:2 row_mask:0xf bank_mask:0xf bound_ctrl:1
	v_mov_b32_dpp v159, v64 row_ror:2 row_mask:0xf bank_mask:0xf bound_ctrl:1
	v_mov_b32_dpp v161, v65 row_ror:2 row_mask:0xf bank_mask:0xf bound_ctrl:1
	v_mov_b32_dpp v110, v62 row_ror:1 row_mask:0xf bank_mask:0xf bound_ctrl:1
	v_mov_b32_dpp v112, v63 row_ror:1 row_mask:0xf bank_mask:0xf bound_ctrl:1
	v_mov_b32_dpp v115, v64 row_ror:1 row_mask:0xf bank_mask:0xf bound_ctrl:1
	v_mov_b32_dpp v160, v65 row_ror:1 row_mask:0xf bank_mask:0xf bound_ctrl:1
	v_cndmask_b32_e64 v104, 0, v111, s[12:13]
	v_cndmask_b32_e64 v105, 0, v113, s[12:13]
	v_cndmask_b32_e64 v108, 0, v159, s[12:13]
	v_cndmask_b32_e64 v109, 0, v161, s[12:13]
	v_cndmask_b32_e64 v102, v110, 0, s[10:11]
	v_cndmask_b32_e64 v103, v112, 0, s[10:11]
	v_cndmask_b32_e64 v106, v115, 0, s[10:11]
	v_cndmask_b32_e64 v107, v160, 0, s[10:11]
	v_add_u32_e32 v0, s25, v188
	s_movk_i32 s16, 0xb00
	v_mul_lo_u32 v178, v0, s16
	v_add_u32_e32 v0, v178, v158
	s_waitcnt vmcnt(6)
	v_pk_fma_f32 v[108:109], v[68:69], v[108:109], v[80:81]
	v_pk_fma_f32 v[104:105], v[66:67], v[104:105], v[78:79]
	s_waitcnt vmcnt(5)
	v_pk_fma_f32 v[106:107], v[76:77], v[106:107], v[108:109]
	v_pk_fma_f32 v[102:103], v[74:75], v[102:103], v[104:105]
	s_waitcnt vmcnt(4)
; __device__ __forceinline__ unsigned cvt_pk(float lo, float hi) { f32x2_t v = {lo, hi}; bf16x2_t b = __builtin_convertvector(v, bf16x2_t); return __builtin_bit_cast(unsigned, b); }
; __device__ __forceinline__ f32x4 sigm4(f32x4 v) { f32x4 o; o[0] = sigm(v[0]); o[1] = sigm(v[1]); o[2] = sigm(v[2]); o[3] = sigm(v[3]); return o; }
; __device__ __forceinline__ float dppr1(float x) { return __int_as_float(__builtin_amdgcn_mov_dpp(__float_as_int(x), 0x121, 0xf, 0xf, true)); }
; __device__ __forceinline__ float dppr2(float x) { return __int_as_float(__builtin_amdgcn_mov_dpp(__float_as_int(x), 0x122, 0xf, 0xf, true)); }
;     template <int GV, int NH> __device__ __forceinline__ void part(f32x4 (&acc)[2][2][4][2], const Unit& u, int wr, int wc, int fr, int fq) const {
;     ...
;             for (int m = 0; m < 4; ++m) {
;                 const f32x4 x3 = acc[ai][GV][m][NH];
;                 f32x4 c1, c2, x2, x1;
; #pragma unroll
;                 for (int i = 0; i < 4; ++i) { c1[i] = dppr1(x3[i]); c2[i] = dppr2(x3[i]); x2[i] = f1 ? c1[i] : p1[i]; x1[i] = f2 ? c2[i] : p2[i]; }
;                 p1 = c1; p2 = c2;
;                 const f32x4 o = bb + x1 * w0 + x2 * w1 + x3 * w2;
;                 if (GV == 0) acc[ai][0][m][NH] = o * sigm4(o);
;                 else { const f32x4 r = acc[ai][0][m][NH] * o; u32x2 pk; pk.x = cvt_pk(r[0], r[1]); pk.y = cvt_pk(r[2], r[3]); *(u32x2*)(ACT + rowb + (unsigned)(16 * m) * DFF) = pk; }
	v_pk_fma_f32 v[64:65], v[64:65], v[72:73], v[106:107]
	v_pk_fma_f32 v[62:63], v[62:63], v[70:71], v[102:103]
	v_pk_mul_f32 v[64:65], v[126:127], v[64:65]
	v_pk_mul_f32 v[62:63], v[128:129], v[62:63]
	s_nop 0
	v_cvt_pk_bf16_f32 v62, v62, v63
	v_cvt_pk_bf16_f32 v63, v64, v65
	v_lshl_add_u64 v[64:65], v[0:1], 1, s[36:37]
	global_store_dwordx2 v[64:65], v[62:63], off
	v_mov_b32_dpp v108, v58 row_ror:2 row_mask:0xf bank_mask:0xf bound_ctrl:1
	v_mov_b32_dpp v0, v58 row_ror:1 row_mask:0xf bank_mask:0xf bound_ctrl:1
	v_cndmask_b32_e64 v102, v111, v108, s[12:13]
	v_mov_b32_dpp v109, v59 row_ror:1 row_mask:0xf bank_mask:0xf bound_ctrl:1
	v_mov_b32_dpp v111, v60 row_ror:1 row_mask:0xf bank_mask:0xf bound_ctrl:1
	v_cndmask_b32_e64 v62, v0, v110, s[10:11]
	v_mov_b32_dpp v110, v59 row_ror:2 row_mask:0xf bank_mask:0xf bound_ctrl:1
	v_cndmask_b32_e64 v63, v109, v112, s[10:11]
	v_mov_b32_dpp v112, v60 row_ror:2 row_mask:0xf bank_mask:0xf bound_ctrl:1
	v_cndmask_b32_e64 v104, v111, v115, s[10:11]
	v_mov_b32_dpp v115, v61 row_ror:2 row_mask:0xf bank_mask:0xf bound_ctrl:1
	v_cndmask_b32_e64 v103, v113, v110, s[12:13]
	v_cndmask_b32_e64 v106, v159, v112, s[12:13]
	v_mov_b32_dpp v113, v61 row_ror:1 row_mask:0xf bank_mask:0xf bound_ctrl:1
	v_cndmask_b32_e64 v107, v161, v115, s[12:13]
	v_cndmask_b32_e64 v105, v113, v160, s[10:11]
	v_pk_fma_f32 v[102:103], v[66:67], v[102:103], v[78:79]
	v_pk_fma_f32 v[106:107], v[68:69], v[106:107], v[80:81]
	v_pk_fma_f32 v[62:63], v[74:75], v[62:63], v[102:103]
	v_pk_fma_f32 v[104:105], v[76:77], v[104:105], v[106:107]
	v_pk_fma_f32 v[58:59], v[58:59], v[70:71], v[62:63]
	v_pk_fma_f32 v[60:61], v[60:61], v[72:73], v[104:105]
	v_pk_mul_f32 v[58:59], v[122:123], v[58:59]
	v_pk_mul_f32 v[60:61], v[124:125], v[60:61]
	s_mov_b32 s0, 0x16000
	v_cvt_pk_bf16_f32 v58, v58, v59
	v_cvt_pk_bf16_f32 v59, v60, v61
	v_add_co_u32_e32 v60, vcc, s0, v64
	s_nop 1
	v_addc_co_u32_e32 v61, vcc, 0, v65, vcc
	global_store_dwordx2 v[60:61], v[58:59], off
	v_mov_b32_dpp v104, v54 row_ror:1 row_mask:0xf bank_mask:0xf bound_ctrl:1
	v_mov_b32_dpp v105, v54 row_ror:2 row_mask:0xf bank_mask:0xf bound_ctrl:1
	v_mov_b32_dpp v106, v55 row_ror:2 row_mask:0xf bank_mask:0xf bound_ctrl:1
	v_cndmask_b32_e64 v58, v104, v0, s[10:11]
	v_cndmask_b32_e64 v60, v108, v105, s[12:13]
	v_mov_b32_dpp v0, v55 row_ror:1 row_mask:0xf bank_mask:0xf bound_ctrl:1
	v_cndmask_b32_e64 v61, v110, v106, s[12:13]
	v_mov_b32_dpp v108, v56 row_ror:2 row_mask:0xf bank_mask:0xf bound_ctrl:1
	v_mov_b32_dpp v110, v57 row_ror:2 row_mask:0xf bank_mask:0xf bound_ctrl:1
	v_cndmask_b32_e64 v59, v0, v109, s[10:11]
	v_mov_b32_dpp v107, v56 row_ror:1 row_mask:0xf bank_mask:0xf bound_ctrl:1
	v_cndmask_b32_e64 v102, v112, v108, s[12:13]
	v_mov_b32_dpp v109, v57 row_ror:1 row_mask:0xf bank_mask:0xf bound_ctrl:1
	v_cndmask_b32_e64 v103, v115, v110, s[12:13]
	v_cndmask_b32_e64 v62, v107, v111, s[10:11]
	v_cndmask_b32_e64 v63, v109, v113, s[10:11]
	v_pk_fma_f32 v[60:61], v[66:67], v[60:61], v[78:79]
	v_pk_fma_f32 v[102:103], v[68:69], v[102:103], v[80:81]
	v_pk_fma_f32 v[58:59], v[74:75], v[58:59], v[60:61]
	v_pk_fma_f32 v[62:63], v[76:77], v[62:63], v[102:103]
	v_pk_fma_f32 v[54:55], v[54:55], v[70:71], v[58:59]
	v_pk_fma_f32 v[56:57], v[56:57], v[72:73], v[62:63]
	v_pk_mul_f32 v[54:55], v[118:119], v[54:55]
	v_pk_mul_f32 v[56:57], v[120:121], v[56:57]
	s_mov_b32 s17, 0x2c000
	v_cvt_pk_bf16_f32 v54, v54, v55
	v_cvt_pk_bf16_f32 v55, v56, v57
	v_add_co_u32_e32 v56, vcc, s17, v64
	s_nop 1
	v_addc_co_u32_e32 v57, vcc, 0, v65, vcc
	global_store_dwordx2 v[56:57], v[54:55], off
	v_mov_b32_dpp v55, v50 row_ror:2 row_mask:0xf bank_mask:0xf bound_ctrl:1
	v_cndmask_b32_e64 v56, v105, v55, s[12:13]
	v_mov_b32_dpp v57, v51 row_ror:2 row_mask:0xf bank_mask:0xf bound_ctrl:1
	v_mov_b32_dpp v55, v51 row_ror:1 row_mask:0xf bank_mask:0xf bound_ctrl:1
	v_cndmask_b32_e64 v55, v55, v0, s[10:11]
	v_mov_b32_dpp v0, v52 row_ror:1 row_mask:0xf bank_mask:0xf bound_ctrl:1
	v_mov_b32_dpp v59, v52 row_ror:2 row_mask:0xf bank_mask:0xf bound_ctrl:1
	v_mov_b32_dpp v61, v53 row_ror:2 row_mask:0xf bank_mask:0xf bound_ctrl:1
	v_mov_b32_dpp v54, v50 row_ror:1 row_mask:0xf bank_mask:0xf bound_ctrl:1
	v_cndmask_b32_e64 v57, v106, v57, s[12:13]
	v_cndmask_b32_e64 v58, v0, v107, s[10:11]
	v_cndmask_b32_e64 v60, v108, v59, s[12:13]
	v_mov_b32_dpp v0, v53 row_ror:1 row_mask:0xf bank_mask:0xf bound_ctrl:1
	v_cndmask_b32_e64 v61, v110, v61, s[12:13]
	v_cndmask_b32_e64 v54, v54, v104, s[10:11]
	v_cndmask_b32_e64 v59, v0, v109, s[10:11]
	v_pk_fma_f32 v[56:57], v[66:67], v[56:57], v[78:79]
	v_pk_fma_f32 v[60:61], v[68:69], v[60:61], v[80:81]
	v_pk_fma_f32 v[54:55], v[74:75], v[54:55], v[56:57]
	v_pk_fma_f32 v[58:59], v[76:77], v[58:59], v[60:61]
	v_pk_fma_f32 v[50:51], v[50:51], v[70:71], v[54:55]
	v_pk_fma_f32 v[52:53], v[52:53], v[72:73], v[58:59]
	v_pk_mul_f32 v[50:51], v[116:117], v[50:51]
	v_pk_mul_f32 v[52:53], v[162:163], v[52:53]
	s_mov_b32 s1, 0x42000
	v_cvt_pk_bf16_f32 v50, v50, v51
	v_cvt_pk_bf16_f32 v51, v52, v53
	v_add_co_u32_e32 v52, vcc, s1, v64
	s_nop 1
	v_addc_co_u32_e32 v53, vcc, 0, v65, vcc
	global_store_dwordx2 v[52:53], v[50:51], off
	v_mov_b32_dpp v60, v46 row_ror:2 row_mask:0xf bank_mask:0xf bound_ctrl:1
	v_mov_b32_dpp v62, v47 row_ror:2 row_mask:0xf bank_mask:0xf bound_ctrl:1
	v_mov_b32_dpp v64, v48 row_ror:2 row_mask:0xf bank_mask:0xf bound_ctrl:1
	v_mov_b32_dpp v102, v49 row_ror:2 row_mask:0xf bank_mask:0xf bound_ctrl:1
	v_mov_b32_dpp v59, v46 row_ror:1 row_mask:0xf bank_mask:0xf bound_ctrl:1
	v_cndmask_b32_e64 v52, 0, v60, s[12:13]
	v_mov_b32_dpp v61, v47 row_ror:1 row_mask:0xf bank_mask:0xf bound_ctrl:1
; __device__ __forceinline__ unsigned cvt_pk(float lo, float hi) { f32x2_t v = {lo, hi}; bf16x2_t b = __builtin_convertvector(v, bf16x2_t); return __builtin_bit_cast(unsigned, b); }
; __device__ __forceinline__ f32x4 sigm4(f32x4 v) { f32x4 o; o[0] = sigm(v[0]); o[1] = sigm(v[1]); o[2] = sigm(v[2]); o[3] = sigm(v[3]); return o; }
; __device__ __forceinline__ float dppr1(float x) { return __int_as_float(__builtin_amdgcn_mov_dpp(__float_as_int(x), 0x121, 0xf, 0xf, true)); }
; __device__ __forceinline__ float dppr2(float x) { return __int_as_float(__builtin_amdgcn_mov_dpp(__float_as_int(x), 0x122, 0xf, 0xf, true)); }
;     template <int GV, int NH> __device__ __forceinline__ void part(f32x4 (&acc)[2][2][4][2], const Unit& u, int wr, int wc, int fr, int fq) const {
;     ...
;             for (int m = 0; m < 4; ++m) {
;                 const f32x4 x3 = acc[ai][GV][m][NH];
;                 f32x4 c1, c2, x2, x1;
; #pragma unroll
;                 for (int i = 0; i < 4; ++i) { c1[i] = dppr1(x3[i]); c2[i] = dppr2(x3[i]); x2[i] = f1 ? c1[i] : p1[i]; x1[i] = f2 ? c2[i] : p2[i]; }
;                 p1 = c1; p2 = c2;
;                 const f32x4 o = bb + x1 * w0 + x2 * w1 + x3 * w2;
;                 if (GV == 0) acc[ai][0][m][NH] = o * sigm4(o);
;                 else { const f32x4 r = acc[ai][0][m][NH] * o; u32x2 pk; pk.x = cvt_pk(r[0], r[1]); pk.y = cvt_pk(r[2], r[3]); *(u32x2*)(ACT + rowb + (unsigned)(16 * m) * DFF) = pk; }
	v_cndmask_b32_e64 v53, 0, v62, s[12:13]
	v_mov_b32_dpp v63, v48 row_ror:1 row_mask:0xf bank_mask:0xf bound_ctrl:1
	v_cndmask_b32_e64 v56, 0, v64, s[12:13]
	v_mov_b32_dpp v65, v49 row_ror:1 row_mask:0xf bank_mask:0xf bound_ctrl:1
	v_cndmask_b32_e64 v57, 0, v102, s[12:13]
	v_cndmask_b32_e64 v50, v59, 0, s[10:11]
	v_cndmask_b32_e64 v51, v61, 0, s[10:11]
	v_cndmask_b32_e64 v54, v63, 0, s[10:11]
	v_cndmask_b32_e64 v55, v65, 0, s[10:11]
	v_pk_fma_f32 v[56:57], v[68:69], v[56:57], v[80:81]
	v_pk_fma_f32 v[52:53], v[66:67], v[52:53], v[78:79]
	v_add_u32_e32 v0, s25, v194
	v_pk_fma_f32 v[54:55], v[76:77], v[54:55], v[56:57]
	v_pk_fma_f32 v[50:51], v[74:75], v[50:51], v[52:53]
	v_mul_lo_u32 v58, v0, s16
	v_pk_fma_f32 v[48:49], v[48:49], v[72:73], v[54:55]
	v_pk_fma_f32 v[46:47], v[46:47], v[70:71], v[50:51]
	v_add_u32_e32 v0, v58, v158
	v_pk_mul_f32 v[48:49], v[164:165], v[48:49]
	v_pk_mul_f32 v[46:47], v[166:167], v[46:47]
	s_nop 0
	v_cvt_pk_bf16_f32 v46, v46, v47
	v_cvt_pk_bf16_f32 v47, v48, v49
	v_lshl_add_u64 v[48:49], v[0:1], 1, s[36:37]
	global_store_dwordx2 v[48:49], v[46:47], off
	v_mov_b32_dpp v56, v42 row_ror:2 row_mask:0xf bank_mask:0xf bound_ctrl:1
	v_mov_b32_dpp v0, v42 row_ror:1 row_mask:0xf bank_mask:0xf bound_ctrl:1
	v_cndmask_b32_e64 v50, v60, v56, s[12:13]
	v_mov_b32_dpp v57, v43 row_ror:1 row_mask:0xf bank_mask:0xf bound_ctrl:1
	v_mov_b32_dpp v60, v44 row_ror:1 row_mask:0xf bank_mask:0xf bound_ctrl:1
	v_cndmask_b32_e64 v46, v0, v59, s[10:11]
	v_mov_b32_dpp v59, v43 row_ror:2 row_mask:0xf bank_mask:0xf bound_ctrl:1
	v_cndmask_b32_e64 v47, v57, v61, s[10:11]
	v_mov_b32_dpp v61, v44 row_ror:2 row_mask:0xf bank_mask:0xf bound_ctrl:1
	v_cndmask_b32_e64 v52, v60, v63, s[10:11]
	v_mov_b32_dpp v63, v45 row_ror:2 row_mask:0xf bank_mask:0xf bound_ctrl:1
	v_cndmask_b32_e64 v51, v62, v59, s[12:13]
	v_cndmask_b32_e64 v54, v64, v61, s[12:13]
	v_mov_b32_dpp v62, v45 row_ror:1 row_mask:0xf bank_mask:0xf bound_ctrl:1
	v_cndmask_b32_e64 v55, v102, v63, s[12:13]
	v_cndmask_b32_e64 v53, v62, v65, s[10:11]
	v_pk_fma_f32 v[50:51], v[66:67], v[50:51], v[78:79]
	v_pk_fma_f32 v[54:55], v[68:69], v[54:55], v[80:81]
	v_pk_fma_f32 v[46:47], v[74:75], v[46:47], v[50:51]
	v_pk_fma_f32 v[52:53], v[76:77], v[52:53], v[54:55]
	v_pk_fma_f32 v[42:43], v[42:43], v[70:71], v[46:47]
	v_pk_fma_f32 v[44:45], v[44:45], v[72:73], v[52:53]
	v_pk_mul_f32 v[42:43], v[168:169], v[42:43]
	v_pk_mul_f32 v[44:45], v[170:171], v[44:45]
	v_cvt_pk_bf16_f32 v42, v42, v43
	v_cvt_pk_bf16_f32 v43, v44, v45
	v_add_co_u32_e32 v44, vcc, s0, v48
	s_nop 1
	v_addc_co_u32_e32 v45, vcc, 0, v49, vcc
	global_store_dwordx2 v[44:45], v[42:43], off
	v_mov_b32_dpp v52, v38 row_ror:1 row_mask:0xf bank_mask:0xf bound_ctrl:1
	v_mov_b32_dpp v53, v38 row_ror:2 row_mask:0xf bank_mask:0xf bound_ctrl:1
	v_mov_b32_dpp v54, v39 row_ror:2 row_mask:0xf bank_mask:0xf bound_ctrl:1
	v_cndmask_b32_e64 v42, v52, v0, s[10:11]
	v_cndmask_b32_e64 v44, v56, v53, s[12:13]
	v_mov_b32_dpp v0, v39 row_ror:1 row_mask:0xf bank_mask:0xf bound_ctrl:1
	v_cndmask_b32_e64 v45, v59, v54, s[12:13]
	v_mov_b32_dpp v56, v40 row_ror:2 row_mask:0xf bank_mask:0xf bound_ctrl:1
	v_mov_b32_dpp v59, v41 row_ror:2 row_mask:0xf bank_mask:0xf bound_ctrl:1
	v_cndmask_b32_e64 v43, v0, v57, s[10:11]
	v_mov_b32_dpp v55, v40 row_ror:1 row_mask:0xf bank_mask:0xf bound_ctrl:1
	v_cndmask_b32_e64 v50, v61, v56, s[12:13]
	v_mov_b32_dpp v57, v41 row_ror:1 row_mask:0xf bank_mask:0xf bound_ctrl:1
	v_cndmask_b32_e64 v51, v63, v59, s[12:13]
	v_cndmask_b32_e64 v46, v55, v60, s[10:11]
	v_cndmask_b32_e64 v47, v57, v62, s[10:11]
	v_pk_fma_f32 v[44:45], v[66:67], v[44:45], v[78:79]
	v_pk_fma_f32 v[50:51], v[68:69], v[50:51], v[80:81]
	v_pk_fma_f32 v[42:43], v[74:75], v[42:43], v[44:45]
	v_pk_fma_f32 v[46:47], v[76:77], v[46:47], v[50:51]
	v_pk_fma_f32 v[38:39], v[38:39], v[70:71], v[42:43]
	v_pk_fma_f32 v[40:41], v[40:41], v[72:73], v[46:47]
	v_pk_mul_f32 v[38:39], v[172:173], v[38:39]
	v_pk_mul_f32 v[40:41], v[174:175], v[40:41]
	v_cvt_pk_bf16_f32 v38, v38, v39
	v_cvt_pk_bf16_f32 v39, v40, v41
	v_add_co_u32_e32 v40, vcc, s17, v48
	s_nop 1
	v_addc_co_u32_e32 v41, vcc, 0, v49, vcc
	global_store_dwordx2 v[40:41], v[38:39], off
	v_mov_b32_dpp v39, v30 row_ror:2 row_mask:0xf bank_mask:0xf bound_ctrl:1
	v_cndmask_b32_e64 v40, v53, v39, s[12:13]
	v_mov_b32_dpp v41, v31 row_ror:2 row_mask:0xf bank_mask:0xf bound_ctrl:1
	v_mov_b32_dpp v39, v31 row_ror:1 row_mask:0xf bank_mask:0xf bound_ctrl:1
	v_cndmask_b32_e64 v39, v39, v0, s[10:11]
	v_mov_b32_dpp v0, v32 row_ror:1 row_mask:0xf bank_mask:0xf bound_ctrl:1
	v_mov_b32_dpp v43, v32 row_ror:2 row_mask:0xf bank_mask:0xf bound_ctrl:1
	v_mov_b32_dpp v45, v33 row_ror:2 row_mask:0xf bank_mask:0xf bound_ctrl:1
	v_mov_b32_dpp v38, v30 row_ror:1 row_mask:0xf bank_mask:0xf bound_ctrl:1
	v_cndmask_b32_e64 v41, v54, v41, s[12:13]
	v_cndmask_b32_e64 v42, v0, v55, s[10:11]
	v_cndmask_b32_e64 v44, v56, v43, s[12:13]
	v_mov_b32_dpp v0, v33 row_ror:1 row_mask:0xf bank_mask:0xf bound_ctrl:1
	v_cndmask_b32_e64 v45, v59, v45, s[12:13]
	v_cndmask_b32_e64 v38, v38, v52, s[10:11]
	v_cndmask_b32_e64 v43, v0, v57, s[10:11]
	v_pk_fma_f32 v[40:41], v[66:67], v[40:41], v[78:79]
	v_pk_fma_f32 v[44:45], v[68:69], v[44:45], v[80:81]
	v_pk_fma_f32 v[38:39], v[74:75], v[38:39], v[40:41]
	v_pk_fma_f32 v[42:43], v[76:77], v[42:43], v[44:45]
	v_pk_fma_f32 v[30:31], v[30:31], v[70:71], v[38:39]
	v_pk_fma_f32 v[32:33], v[32:33], v[72:73], v[42:43]
	v_pk_mul_f32 v[30:31], v[132:133], v[30:31]
	v_pk_mul_f32 v[32:33], v[134:135], v[32:33]
	v_cvt_pk_bf16_f32 v30, v30, v31
	v_cvt_pk_bf16_f32 v31, v32, v33
	v_add_co_u32_e32 v32, vcc, s1, v48
	s_nop 1
	v_addc_co_u32_e32 v33, vcc, 0, v49, vcc
	global_store_dwordx2 v[32:33], v[30:31], off
	v_mov_b32_dpp v60, v34 row_ror:2 row_mask:0xf bank_mask:0xf bound_ctrl:1
	v_mov_b32_dpp v62, v35 row_ror:2 row_mask:0xf bank_mask:0xf bound_ctrl:1
	v_mov_b32_dpp v64, v36 row_ror:2 row_mask:0xf bank_mask:0xf bound_ctrl:1
	v_mov_b32_dpp v66, v37 row_ror:2 row_mask:0xf bank_mask:0xf bound_ctrl:1
	v_mov_b32_dpp v59, v34 row_ror:1 row_mask:0xf bank_mask:0xf bound_ctrl:1
	v_mov_b32_dpp v61, v35 row_ror:1 row_mask:0xf bank_mask:0xf bound_ctrl:1
	v_mov_b32_dpp v63, v36 row_ror:1 row_mask:0xf bank_mask:0xf bound_ctrl:1
	v_mov_b32_dpp v65, v37 row_ror:1 row_mask:0xf bank_mask:0xf bound_ctrl:1
	v_cndmask_b32_e64 v52, 0, v60, s[12:13]
	v_cndmask_b32_e64 v53, 0, v62, s[12:13]
	v_cndmask_b32_e64 v56, 0, v64, s[12:13]
	v_cndmask_b32_e64 v57, 0, v66, s[12:13]
	v_cndmask_b32_e64 v50, v59, 0, s[10:11]
	v_cndmask_b32_e64 v51, v61, 0, s[10:11]
	v_cndmask_b32_e64 v54, v63, 0, s[10:11]
	v_cndmask_b32_e64 v55, v65, 0, s[10:11]
	v_add_u32_e32 v0, v114, v178
	s_waitcnt vmcnt(8)
; __device__ __forceinline__ unsigned cvt_pk(float lo, float hi) { f32x2_t v = {lo, hi}; bf16x2_t b = __builtin_convertvector(v, bf16x2_t); return __builtin_bit_cast(unsigned, b); }
; __device__ __forceinline__ f32x4 sigm4(f32x4 v) { f32x4 o; o[0] = sigm(v[0]); o[1] = sigm(v[1]); o[2] = sigm(v[2]); o[3] = sigm(v[3]); return o; }
; __device__ __forceinline__ float dppr1(float x) { return __int_as_float(__builtin_amdgcn_mov_dpp(__float_as_int(x), 0x121, 0xf, 0xf, true)); }
; __device__ __forceinline__ float dppr2(float x) { return __int_as_float(__builtin_amdgcn_mov_dpp(__float_as_int(x), 0x122, 0xf, 0xf, true)); }
;     template <int GV, int NH> __device__ __forceinline__ void part(f32x4 (&acc)[2][2][4][2], const Unit& u, int wr, int wc, int fr, int fq) const {
;     ...
;             for (int m = 0; m < 4; ++m) {
;                 const f32x4 x3 = acc[ai][GV][m][NH];
;                 f32x4 c1, c2, x2, x1;
; #pragma unroll
;                 for (int i = 0; i < 4; ++i) { c1[i] = dppr1(x3[i]); c2[i] = dppr2(x3[i]); x2[i] = f1 ? c1[i] : p1[i]; x1[i] = f2 ? c2[i] : p2[i]; }
;                 p1 = c1; p2 = c2;
;                 const f32x4 o = bb + x1 * w0 + x2 * w1 + x3 * w2;
;                 if (GV == 0) acc[ai][0][m][NH] = o * sigm4(o);
;                 else { const f32x4 r = acc[ai][0][m][NH] * o; u32x2 pk; pk.x = cvt_pk(r[0], r[1]); pk.y = cvt_pk(r[2], r[3]); *(u32x2*)(ACT + rowb + (unsigned)(16 * m) * DFF) = pk; }
	v_pk_fma_f32 v[52:53], v[238:239], v[52:53], v[242:243]
	v_pk_fma_f32 v[56:57], v[240:241], v[56:57], v[244:245]
	v_pk_fma_f32 v[50:51], v[198:199], v[50:51], v[52:53]
	v_pk_fma_f32 v[54:55], v[200:201], v[54:55], v[56:57]
	v_pk_fma_f32 v[34:35], v[34:35], v[202:203], v[50:51]
	v_pk_fma_f32 v[36:37], v[36:37], v[204:205], v[54:55]
	v_pk_mul_f32 v[34:35], v[94:95], v[34:35]
	v_pk_mul_f32 v[36:37], v[96:97], v[36:37]
	v_cvt_pk_bf16_f32 v34, v34, v35
	v_cvt_pk_bf16_f32 v35, v36, v37
	v_lshl_add_u64 v[36:37], v[0:1], 1, s[36:37]
	global_store_dwordx2 v[36:37], v[34:35], off
	v_mov_b32_dpp v56, v26 row_ror:2 row_mask:0xf bank_mask:0xf bound_ctrl:1
	v_mov_b32_dpp v0, v26 row_ror:1 row_mask:0xf bank_mask:0xf bound_ctrl:1
	v_cndmask_b32_e64 v50, v60, v56, s[12:13]
	v_mov_b32_dpp v57, v27 row_ror:1 row_mask:0xf bank_mask:0xf bound_ctrl:1
	v_mov_b32_dpp v60, v28 row_ror:1 row_mask:0xf bank_mask:0xf bound_ctrl:1
	v_cndmask_b32_e64 v34, v0, v59, s[10:11]
	v_mov_b32_dpp v59, v27 row_ror:2 row_mask:0xf bank_mask:0xf bound_ctrl:1
	v_cndmask_b32_e64 v35, v57, v61, s[10:11]
	v_mov_b32_dpp v61, v28 row_ror:2 row_mask:0xf bank_mask:0xf bound_ctrl:1
	v_cndmask_b32_e64 v52, v60, v63, s[10:11]
	v_mov_b32_dpp v63, v29 row_ror:2 row_mask:0xf bank_mask:0xf bound_ctrl:1
	v_cndmask_b32_e64 v51, v62, v59, s[12:13]
	v_cndmask_b32_e64 v54, v64, v61, s[12:13]
	v_mov_b32_dpp v62, v29 row_ror:1 row_mask:0xf bank_mask:0xf bound_ctrl:1
	v_cndmask_b32_e64 v55, v66, v63, s[12:13]
	v_cndmask_b32_e64 v53, v62, v65, s[10:11]
	v_pk_fma_f32 v[54:55], v[240:241], v[54:55], v[244:245]
	v_pk_fma_f32 v[50:51], v[238:239], v[50:51], v[242:243]
	v_pk_fma_f32 v[52:53], v[200:201], v[52:53], v[54:55]
	v_pk_fma_f32 v[34:35], v[198:199], v[34:35], v[50:51]
	v_pk_fma_f32 v[28:29], v[28:29], v[204:205], v[52:53]
	v_pk_fma_f32 v[26:27], v[26:27], v[202:203], v[34:35]
	v_pk_mul_f32 v[28:29], v[90:91], v[28:29]
	v_pk_mul_f32 v[26:27], v[92:93], v[26:27]
	s_nop 0
	v_cvt_pk_bf16_f32 v26, v26, v27
	v_cvt_pk_bf16_f32 v27, v28, v29
	v_add_co_u32_e32 v28, vcc, s0, v36
	s_nop 1
	v_addc_co_u32_e32 v29, vcc, 0, v37, vcc
	global_store_dwordx2 v[28:29], v[26:27], off
	v_mov_b32_dpp v52, v22 row_ror:1 row_mask:0xf bank_mask:0xf bound_ctrl:1
	v_mov_b32_dpp v53, v22 row_ror:2 row_mask:0xf bank_mask:0xf bound_ctrl:1
	v_mov_b32_dpp v54, v23 row_ror:2 row_mask:0xf bank_mask:0xf bound_ctrl:1
	v_cndmask_b32_e64 v26, v52, v0, s[10:11]
	v_cndmask_b32_e64 v28, v56, v53, s[12:13]
	v_mov_b32_dpp v0, v23 row_ror:1 row_mask:0xf bank_mask:0xf bound_ctrl:1
	v_cndmask_b32_e64 v29, v59, v54, s[12:13]
	v_mov_b32_dpp v56, v24 row_ror:2 row_mask:0xf bank_mask:0xf bound_ctrl:1
	v_mov_b32_dpp v59, v25 row_ror:2 row_mask:0xf bank_mask:0xf bound_ctrl:1
	v_cndmask_b32_e64 v27, v0, v57, s[10:11]
	v_mov_b32_dpp v55, v24 row_ror:1 row_mask:0xf bank_mask:0xf bound_ctrl:1
	v_cndmask_b32_e64 v50, v61, v56, s[12:13]
	v_mov_b32_dpp v57, v25 row_ror:1 row_mask:0xf bank_mask:0xf bound_ctrl:1
	v_cndmask_b32_e64 v51, v63, v59, s[12:13]
	v_cndmask_b32_e64 v34, v55, v60, s[10:11]
	v_cndmask_b32_e64 v35, v57, v62, s[10:11]
	v_pk_fma_f32 v[50:51], v[240:241], v[50:51], v[244:245]
	v_pk_fma_f32 v[28:29], v[238:239], v[28:29], v[242:243]
	v_pk_fma_f32 v[34:35], v[200:201], v[34:35], v[50:51]
	v_pk_fma_f32 v[26:27], v[198:199], v[26:27], v[28:29]
	v_pk_fma_f32 v[24:25], v[24:25], v[204:205], v[34:35]
	v_pk_fma_f32 v[22:23], v[22:23], v[202:203], v[26:27]
	v_pk_mul_f32 v[24:25], v[86:87], v[24:25]
	v_pk_mul_f32 v[22:23], v[88:89], v[22:23]
	s_nop 0
	v_cvt_pk_bf16_f32 v22, v22, v23
	v_cvt_pk_bf16_f32 v23, v24, v25
	v_add_co_u32_e32 v24, vcc, s17, v36
	s_nop 1
	v_addc_co_u32_e32 v25, vcc, 0, v37, vcc
	global_store_dwordx2 v[24:25], v[22:23], off
	v_mov_b32_dpp v23, v18 row_ror:2 row_mask:0xf bank_mask:0xf bound_ctrl:1
	v_cndmask_b32_e64 v24, v53, v23, s[12:13]
	v_mov_b32_dpp v25, v19 row_ror:2 row_mask:0xf bank_mask:0xf bound_ctrl:1
	v_mov_b32_dpp v23, v19 row_ror:1 row_mask:0xf bank_mask:0xf bound_ctrl:1
	v_cndmask_b32_e64 v23, v23, v0, s[10:11]
	v_mov_b32_dpp v0, v20 row_ror:1 row_mask:0xf bank_mask:0xf bound_ctrl:1
	v_mov_b32_dpp v27, v20 row_ror:2 row_mask:0xf bank_mask:0xf bound_ctrl:1
	v_mov_b32_dpp v29, v21 row_ror:2 row_mask:0xf bank_mask:0xf bound_ctrl:1
	v_mov_b32_dpp v22, v18 row_ror:1 row_mask:0xf bank_mask:0xf bound_ctrl:1
	v_cndmask_b32_e64 v25, v54, v25, s[12:13]
	v_cndmask_b32_e64 v26, v0, v55, s[10:11]
	v_cndmask_b32_e64 v28, v56, v27, s[12:13]
	v_mov_b32_dpp v0, v21 row_ror:1 row_mask:0xf bank_mask:0xf bound_ctrl:1
	v_cndmask_b32_e64 v29, v59, v29, s[12:13]
	v_cndmask_b32_e64 v22, v22, v52, s[10:11]
	v_cndmask_b32_e64 v27, v0, v57, s[10:11]
	v_pk_fma_f32 v[28:29], v[240:241], v[28:29], v[244:245]
	v_pk_fma_f32 v[24:25], v[238:239], v[24:25], v[242:243]
	v_pk_fma_f32 v[26:27], v[200:201], v[26:27], v[28:29]
	v_pk_fma_f32 v[22:23], v[198:199], v[22:23], v[24:25]
	v_pk_fma_f32 v[20:21], v[20:21], v[204:205], v[26:27]
	v_pk_fma_f32 v[18:19], v[18:19], v[202:203], v[22:23]
	v_pk_mul_f32 v[20:21], v[82:83], v[20:21]
	v_pk_mul_f32 v[18:19], v[84:85], v[18:19]
	s_nop 0
	v_cvt_pk_bf16_f32 v18, v18, v19
	v_cvt_pk_bf16_f32 v19, v20, v21
	v_add_co_u32_e32 v20, vcc, s1, v36
	s_nop 1
	v_addc_co_u32_e32 v21, vcc, 0, v37, vcc
	global_store_dwordx2 v[20:21], v[18:19], off
	v_mov_b32_dpp v27, v14 row_ror:2 row_mask:0xf bank_mask:0xf bound_ctrl:1
	v_mov_b32_dpp v29, v15 row_ror:2 row_mask:0xf bank_mask:0xf bound_ctrl:1
	v_mov_b32_dpp v35, v16 row_ror:2 row_mask:0xf bank_mask:0xf bound_ctrl:1
	v_mov_b32_dpp v37, v17 row_ror:2 row_mask:0xf bank_mask:0xf bound_ctrl:1
	v_mov_b32_dpp v26, v14 row_ror:1 row_mask:0xf bank_mask:0xf bound_ctrl:1
; __device__ __forceinline__ unsigned cvt_pk(float lo, float hi) { f32x2_t v = {lo, hi}; bf16x2_t b = __builtin_convertvector(v, bf16x2_t); return __builtin_bit_cast(unsigned, b); }
; __device__ __forceinline__ f32x4 sigm4(f32x4 v) { f32x4 o; o[0] = sigm(v[0]); o[1] = sigm(v[1]); o[2] = sigm(v[2]); o[3] = sigm(v[3]); return o; }
; __device__ __forceinline__ float dppr1(float x) { return __int_as_float(__builtin_amdgcn_mov_dpp(__float_as_int(x), 0x121, 0xf, 0xf, true)); }
; __device__ __forceinline__ float dppr2(float x) { return __int_as_float(__builtin_amdgcn_mov_dpp(__float_as_int(x), 0x122, 0xf, 0xf, true)); }
;     template <int GV, int NH> __device__ __forceinline__ void part(f32x4 (&acc)[2][2][4][2], const Unit& u, int wr, int wc, int fr, int fq) const {
;     ...
;             for (int m = 0; m < 4; ++m) {
;                 const f32x4 x3 = acc[ai][GV][m][NH];
;                 f32x4 c1, c2, x2, x1;
; #pragma unroll
;                 for (int i = 0; i < 4; ++i) { c1[i] = dppr1(x3[i]); c2[i] = dppr2(x3[i]); x2[i] = f1 ? c1[i] : p1[i]; x1[i] = f2 ? c2[i] : p2[i]; }
;                 p1 = c1; p2 = c2;
;                 const f32x4 o = bb + x1 * w0 + x2 * w1 + x3 * w2;
;                 if (GV == 0) acc[ai][0][m][NH] = o * sigm4(o);
;                 else { const f32x4 r = acc[ai][0][m][NH] * o; u32x2 pk; pk.x = cvt_pk(r[0], r[1]); pk.y = cvt_pk(r[2], r[3]); *(u32x2*)(ACT + rowb + (unsigned)(16 * m) * DFF) = pk; }
	v_cndmask_b32_e64 v20, 0, v27, s[12:13]
	v_mov_b32_dpp v28, v15 row_ror:1 row_mask:0xf bank_mask:0xf bound_ctrl:1
	v_cndmask_b32_e64 v21, 0, v29, s[12:13]
	v_mov_b32_dpp v34, v16 row_ror:1 row_mask:0xf bank_mask:0xf bound_ctrl:1
	v_cndmask_b32_e64 v24, 0, v35, s[12:13]
	v_mov_b32_dpp v36, v17 row_ror:1 row_mask:0xf bank_mask:0xf bound_ctrl:1
	v_cndmask_b32_e64 v25, 0, v37, s[12:13]
	v_cndmask_b32_e64 v18, v26, 0, s[10:11]
	v_cndmask_b32_e64 v19, v28, 0, s[10:11]
	v_cndmask_b32_e64 v22, v34, 0, s[10:11]
	v_cndmask_b32_e64 v23, v36, 0, s[10:11]
	v_pk_fma_f32 v[20:21], v[238:239], v[20:21], v[242:243]
	v_pk_fma_f32 v[24:25], v[240:241], v[24:25], v[244:245]
	v_pk_fma_f32 v[18:19], v[198:199], v[18:19], v[20:21]
	v_pk_fma_f32 v[22:23], v[200:201], v[22:23], v[24:25]
	v_pk_fma_f32 v[14:15], v[14:15], v[202:203], v[18:19]
	v_pk_fma_f32 v[16:17], v[16:17], v[204:205], v[22:23]
	v_add_u32_e32 v0, v58, v114
	v_pk_mul_f32 v[16:17], v[138:139], v[16:17]
	v_pk_mul_f32 v[14:15], v[136:137], v[14:15]
	s_nop 0
	v_cvt_pk_bf16_f32 v14, v14, v15
	v_cvt_pk_bf16_f32 v15, v16, v17
	v_lshl_add_u64 v[16:17], v[0:1], 1, s[36:37]
	global_store_dwordx2 v[16:17], v[14:15], off
	v_mov_b32_dpp v24, v10 row_ror:2 row_mask:0xf bank_mask:0xf bound_ctrl:1
	v_mov_b32_dpp v0, v10 row_ror:1 row_mask:0xf bank_mask:0xf bound_ctrl:1
	v_cndmask_b32_e64 v18, v27, v24, s[12:13]
	v_mov_b32_dpp v25, v11 row_ror:1 row_mask:0xf bank_mask:0xf bound_ctrl:1
	v_mov_b32_dpp v27, v12 row_ror:1 row_mask:0xf bank_mask:0xf bound_ctrl:1
	v_cndmask_b32_e64 v14, v0, v26, s[10:11]
	v_mov_b32_dpp v26, v11 row_ror:2 row_mask:0xf bank_mask:0xf bound_ctrl:1
	v_cndmask_b32_e64 v15, v25, v28, s[10:11]
	v_mov_b32_dpp v28, v12 row_ror:2 row_mask:0xf bank_mask:0xf bound_ctrl:1
	v_cndmask_b32_e64 v20, v27, v34, s[10:11]
	v_mov_b32_dpp v34, v13 row_ror:2 row_mask:0xf bank_mask:0xf bound_ctrl:1
	v_cndmask_b32_e64 v19, v29, v26, s[12:13]
	v_cndmask_b32_e64 v22, v35, v28, s[12:13]
	v_mov_b32_dpp v29, v13 row_ror:1 row_mask:0xf bank_mask:0xf bound_ctrl:1
	v_cndmask_b32_e64 v23, v37, v34, s[12:13]
	v_cndmask_b32_e64 v21, v29, v36, s[10:11]
	v_pk_fma_f32 v[22:23], v[240:241], v[22:23], v[244:245]
	v_pk_fma_f32 v[18:19], v[238:239], v[18:19], v[242:243]
	v_pk_fma_f32 v[20:21], v[200:201], v[20:21], v[22:23]
	v_pk_fma_f32 v[14:15], v[198:199], v[14:15], v[18:19]
	v_pk_fma_f32 v[12:13], v[12:13], v[204:205], v[20:21]
	v_pk_fma_f32 v[10:11], v[10:11], v[202:203], v[14:15]
	v_pk_mul_f32 v[12:13], v[140:141], v[12:13]
	v_pk_mul_f32 v[10:11], v[142:143], v[10:11]
	s_nop 0
	v_cvt_pk_bf16_f32 v10, v10, v11
	v_cvt_pk_bf16_f32 v11, v12, v13
	v_add_co_u32_e32 v12, vcc, s0, v16
	s_nop 1
	v_addc_co_u32_e32 v13, vcc, 0, v17, vcc
	global_store_dwordx2 v[12:13], v[10:11], off
	v_mov_b32_dpp v20, v6 row_ror:1 row_mask:0xf bank_mask:0xf bound_ctrl:1
	v_mov_b32_dpp v21, v6 row_ror:2 row_mask:0xf bank_mask:0xf bound_ctrl:1
	v_mov_b32_dpp v22, v7 row_ror:2 row_mask:0xf bank_mask:0xf bound_ctrl:1
	v_cndmask_b32_e64 v10, v20, v0, s[10:11]
	v_cndmask_b32_e64 v12, v24, v21, s[12:13]
	v_mov_b32_dpp v0, v7 row_ror:1 row_mask:0xf bank_mask:0xf bound_ctrl:1
	v_cndmask_b32_e64 v13, v26, v22, s[12:13]
	v_mov_b32_dpp v24, v8 row_ror:2 row_mask:0xf bank_mask:0xf bound_ctrl:1
	v_mov_b32_dpp v26, v9 row_ror:2 row_mask:0xf bank_mask:0xf bound_ctrl:1
	v_cndmask_b32_e64 v11, v0, v25, s[10:11]
	v_mov_b32_dpp v23, v8 row_ror:1 row_mask:0xf bank_mask:0xf bound_ctrl:1
	v_cndmask_b32_e64 v18, v28, v24, s[12:13]
	v_mov_b32_dpp v25, v9 row_ror:1 row_mask:0xf bank_mask:0xf bound_ctrl:1
	v_cndmask_b32_e64 v19, v34, v26, s[12:13]
	v_cndmask_b32_e64 v14, v23, v27, s[10:11]
	v_cndmask_b32_e64 v15, v25, v29, s[10:11]
	v_pk_fma_f32 v[18:19], v[240:241], v[18:19], v[244:245]
	v_pk_fma_f32 v[12:13], v[238:239], v[12:13], v[242:243]
	v_pk_fma_f32 v[14:15], v[200:201], v[14:15], v[18:19]
	v_pk_fma_f32 v[10:11], v[198:199], v[10:11], v[12:13]
	v_pk_fma_f32 v[8:9], v[8:9], v[204:205], v[14:15]
	v_pk_fma_f32 v[6:7], v[6:7], v[202:203], v[10:11]
	v_pk_mul_f32 v[8:9], v[144:145], v[8:9]
	v_pk_mul_f32 v[6:7], v[176:177], v[6:7]
	s_nop 0
	v_cvt_pk_bf16_f32 v6, v6, v7
	v_cvt_pk_bf16_f32 v7, v8, v9
	v_add_co_u32_e32 v8, vcc, s17, v16
	s_nop 1
	v_addc_co_u32_e32 v9, vcc, 0, v17, vcc
	global_store_dwordx2 v[8:9], v[6:7], off
	v_mov_b32_dpp v7, v2 row_ror:2 row_mask:0xf bank_mask:0xf bound_ctrl:1
	v_cndmask_b32_e64 v8, v21, v7, s[12:13]
	v_mov_b32_dpp v9, v3 row_ror:2 row_mask:0xf bank_mask:0xf bound_ctrl:1
	v_mov_b32_dpp v7, v3 row_ror:1 row_mask:0xf bank_mask:0xf bound_ctrl:1
	v_cndmask_b32_e64 v7, v7, v0, s[10:11]
	v_mov_b32_dpp v0, v4 row_ror:1 row_mask:0xf bank_mask:0xf bound_ctrl:1
	v_mov_b32_dpp v11, v4 row_ror:2 row_mask:0xf bank_mask:0xf bound_ctrl:1
	v_mov_b32_dpp v13, v5 row_ror:2 row_mask:0xf bank_mask:0xf bound_ctrl:1
	v_mov_b32_dpp v6, v2 row_ror:1 row_mask:0xf bank_mask:0xf bound_ctrl:1
	v_cndmask_b32_e64 v9, v22, v9, s[12:13]
	v_cndmask_b32_e64 v10, v0, v23, s[10:11]
	v_cndmask_b32_e64 v12, v24, v11, s[12:13]
	v_mov_b32_dpp v0, v5 row_ror:1 row_mask:0xf bank_mask:0xf bound_ctrl:1
	v_cndmask_b32_e64 v13, v26, v13, s[12:13]
	v_cndmask_b32_e64 v6, v6, v20, s[10:11]
	v_cndmask_b32_e64 v11, v0, v25, s[10:11]
	v_pk_fma_f32 v[12:13], v[240:241], v[12:13], v[244:245]
	v_pk_fma_f32 v[8:9], v[238:239], v[8:9], v[242:243]
	v_pk_fma_f32 v[10:11], v[200:201], v[10:11], v[12:13]
	v_pk_fma_f32 v[6:7], v[198:199], v[6:7], v[8:9]
	v_pk_fma_f32 v[4:5], v[4:5], v[204:205], v[10:11]
	v_pk_fma_f32 v[2:3], v[2:3], v[202:203], v[6:7]
	v_pk_mul_f32 v[4:5], v[98:99], v[4:5]
	v_pk_mul_f32 v[2:3], v[100:101], v[2:3]
	s_nop 0
	v_cvt_pk_bf16_f32 v2, v2, v3
	v_cvt_pk_bf16_f32 v3, v4, v5
	v_add_co_u32_e32 v4, vcc, 0x42000, v16
	s_nop 1
	v_addc_co_u32_e32 v5, vcc, 0, v17, vcc
	global_store_dwordx2 v[4:5], v[2:3], off
	s_andn2_b64 vcc, exec, s[14:15]
	s_mov_b64 s[14:15], -1
	s_cbranch_vccnz .LBB0_1918
	s_andn2_b64 vcc, exec, s[2:3]
	s_cbranch_vccnz .LBB0_1917
	s_barrier
	s_branch .LBB0_1917

; __device__ __forceinline__ void fold_parts(f32x4 (&v)[4], float* xrow, const float* part, int rs, int nsplit, int lane) {
;     for (int z = 0; z < nsplit; ++z) { const float* pr = part + ((size_t)z * MS + rs) * DM + 4 * lane;
; #pragma unroll
;         for (int j = 0; j < 4; ++j) v[j] += *(const f32x4*)(pr + 256 * j); }
; __global__ void __launch_bounds__(NTH, 2) mega(Params p) {
;     ...
;             for (int u = 0; u < 4; ++u) { int m = m0 + u * NGW; ss[u] = 0.f; if (m >= M) m = m0; const float* xr = X + (size_t)m * DM + 4 * lane;
; #pragma unroll
;                 for (int j = 0; j < 4; ++j) v[u][j] = *(const f32x4*)(xr + 256 * j); }
; #pragma unroll
;             for (int u = 0; u < 4; ++u) { const int m = m0 + u * NGW; if (m < M) { float* xr = X + (size_t)m * DM + 4 * lane;
;                 if (m >= MP) fold_parts(v[u], xr, (const float*)(ws + WS_RA), m - MP, 11, lane);
.LBB0_2189:
	s_add_i32 s16, s80, s2
	s_add_i32 s11, s2, 0x8000
	s_add_i32 s9, s16, 0x8000
	s_cmp_gt_i32 s9, 0x83ff
	s_cselect_b32 s0, s11, s9
	s_ashr_i32 s1, s0, 31
	s_add_i32 s14, s82, s2
	s_lshl_b64 s[0:1], s[0:1], 12
	s_add_i32 s12, s14, 0x8000
	s_cmp_gt_i32 s12, 0x83ff
	s_waitcnt vmcnt(4)
	v_lshl_add_u64 v[16:17], v[96:97], 0, s[0:1]
	s_cselect_b32 s0, s11, s12
	s_ashr_i32 s1, s0, 31
	s_add_i32 s10, s65, s2
	s_lshl_b64 s[0:1], s[0:1], 12
	s_add_i32 s8, s10, 0x8000
	v_lshl_add_u64 v[80:81], v[100:101], 0, s[6:7]
	s_cmp_gt_i32 s8, 0x83ff
	global_load_dwordx4 v[72:75], v[80:81], off
	global_load_dwordx4 v[68:71], v[80:81], off offset:1024
	global_load_dwordx4 v[64:67], v[80:81], off offset:2048
	global_load_dwordx4 v[76:79], v[80:81], off offset:3072
	global_load_dwordx4 v[60:63], v[16:17], off
	global_load_dwordx4 v[56:59], v[16:17], off offset:1024
	global_load_dwordx4 v[52:55], v[16:17], off offset:2048
	global_load_dwordx4 v[48:51], v[16:17], off offset:3072
	v_lshl_add_u64 v[16:17], v[96:97], 0, s[0:1]
	s_cselect_b32 s0, s11, s8
	s_ashr_i32 s1, s0, 31
	s_lshl_b64 s[0:1], s[0:1], 12
	v_lshl_add_u64 v[82:83], v[96:97], 0, s[0:1]
	global_load_dwordx4 v[44:47], v[16:17], off
	global_load_dwordx4 v[40:43], v[16:17], off offset:1024
	global_load_dwordx4 v[36:39], v[16:17], off offset:2048
	global_load_dwordx4 v[32:35], v[16:17], off offset:3072
	global_load_dwordx4 v[28:31], v[82:83], off
	global_load_dwordx4 v[24:27], v[82:83], off offset:1024
	global_load_dwordx4 v[20:23], v[82:83], off offset:2048
	s_nop 0
	global_load_dwordx4 v[16:19], v[82:83], off offset:3072
	s_cmp_lt_i32 s11, 0x8000
	s_cbranch_scc1 .LBB0_2191
	s_lshl_b64 s[0:1], s[2:3], 12
	v_lshl_add_u64 v[82:83], v[98:99], 0, s[0:1]
	s_mov_b32 s101, 0
	global_load_dwordx4 v[116:119], v[82:83], off
	global_load_dwordx4 v[120:123], v[82:83], off offset:1024
	global_load_dwordx4 v[124:127], v[82:83], off offset:2048
	global_load_dwordx4 v[128:131], v[82:83], off offset:3072
	s_mov_b32 s100, s18
	v_lshl_add_u64 v[212:213], v[82:83], 0, s[100:101]
	global_load_dwordx4 v[132:135], v[212:213], off
	global_load_dwordx4 v[136:139], v[212:213], off offset:1024
	global_load_dwordx4 v[140:143], v[212:213], off offset:2048
	global_load_dwordx4 v[144:147], v[212:213], off offset:3072
	s_mov_b32 s100, s19
	v_lshl_add_u64 v[212:213], v[82:83], 0, s[100:101]
	global_load_dwordx4 v[148:151], v[212:213], off
	global_load_dwordx4 v[152:155], v[212:213], off offset:1024
	global_load_dwordx4 v[156:159], v[212:213], off offset:2048
	global_load_dwordx4 v[160:163], v[212:213], off offset:3072
	s_mov_b32 s100, s20
	v_lshl_add_u64 v[212:213], v[82:83], 0, s[100:101]
	global_load_dwordx4 v[164:167], v[212:213], off
	global_load_dwordx4 v[168:171], v[212:213], off offset:1024
	global_load_dwordx4 v[172:175], v[212:213], off offset:2048
	global_load_dwordx4 v[176:179], v[212:213], off offset:3072
	s_mov_b32 s100, s21
	v_lshl_add_u64 v[212:213], v[82:83], 0, s[100:101]
	global_load_dwordx4 v[180:183], v[212:213], off
	global_load_dwordx4 v[184:187], v[212:213], off offset:1024
	global_load_dwordx4 v[188:191], v[212:213], off offset:2048
	global_load_dwordx4 v[192:195], v[212:213], off offset:3072
	s_mov_b32 s100, s22
	v_lshl_add_u64 v[212:213], v[82:83], 0, s[100:101]
	global_load_dwordx4 v[196:199], v[212:213], off
	global_load_dwordx4 v[200:203], v[212:213], off offset:1024
	global_load_dwordx4 v[204:207], v[212:213], off offset:2048
	global_load_dwordx4 v[208:211], v[212:213], off offset:3072
	s_waitcnt vmcnt(0)
; __device__ __forceinline__ void fold_parts(f32x4 (&v)[4], float* xrow, const float* part, int rs, int nsplit, int lane) {
;     for (int z = 0; z < nsplit; ++z) { const float* pr = part + ((size_t)z * MS + rs) * DM + 4 * lane;
; #pragma unroll
;         for (int j = 0; j < 4; ++j) v[j] += *(const f32x4*)(pr + 256 * j); }
	v_pk_add_f32 v[72:73], v[72:73], v[116:117]
	v_pk_add_f32 v[74:75], v[74:75], v[118:119]
	v_pk_add_f32 v[68:69], v[68:69], v[120:121]
	v_pk_add_f32 v[70:71], v[70:71], v[122:123]
	v_pk_add_f32 v[64:65], v[64:65], v[124:125]
	v_pk_add_f32 v[66:67], v[66:67], v[126:127]
	v_pk_add_f32 v[76:77], v[76:77], v[128:129]
	v_pk_add_f32 v[78:79], v[78:79], v[130:131]
	v_pk_add_f32 v[72:73], v[72:73], v[132:133]
	v_pk_add_f32 v[74:75], v[74:75], v[134:135]
	v_pk_add_f32 v[68:69], v[68:69], v[136:137]
	v_pk_add_f32 v[70:71], v[70:71], v[138:139]
	v_pk_add_f32 v[64:65], v[64:65], v[140:141]
	v_pk_add_f32 v[66:67], v[66:67], v[142:143]
	v_pk_add_f32 v[76:77], v[76:77], v[144:145]
	v_pk_add_f32 v[78:79], v[78:79], v[146:147]
	v_pk_add_f32 v[72:73], v[72:73], v[148:149]
	v_pk_add_f32 v[74:75], v[74:75], v[150:151]
	v_pk_add_f32 v[68:69], v[68:69], v[152:153]
	v_pk_add_f32 v[70:71], v[70:71], v[154:155]
	v_pk_add_f32 v[64:65], v[64:65], v[156:157]
	v_pk_add_f32 v[66:67], v[66:67], v[158:159]
	v_pk_add_f32 v[76:77], v[76:77], v[160:161]
	v_pk_add_f32 v[78:79], v[78:79], v[162:163]
	v_pk_add_f32 v[72:73], v[72:73], v[164:165]
	v_pk_add_f32 v[74:75], v[74:75], v[166:167]
	v_pk_add_f32 v[68:69], v[68:69], v[168:169]
	v_pk_add_f32 v[70:71], v[70:71], v[170:171]
	v_pk_add_f32 v[64:65], v[64:65], v[172:173]
	v_pk_add_f32 v[66:67], v[66:67], v[174:175]
	v_pk_add_f32 v[76:77], v[76:77], v[176:177]
	v_pk_add_f32 v[78:79], v[78:79], v[178:179]
	v_pk_add_f32 v[72:73], v[72:73], v[180:181]
	v_pk_add_f32 v[74:75], v[74:75], v[182:183]
	v_pk_add_f32 v[68:69], v[68:69], v[184:185]
	v_pk_add_f32 v[70:71], v[70:71], v[186:187]
	v_pk_add_f32 v[64:65], v[64:65], v[188:189]
	v_pk_add_f32 v[66:67], v[66:67], v[190:191]
	v_pk_add_f32 v[76:77], v[76:77], v[192:193]
	v_pk_add_f32 v[78:79], v[78:79], v[194:195]
	v_pk_add_f32 v[72:73], v[72:73], v[196:197]
	v_pk_add_f32 v[74:75], v[74:75], v[198:199]
	v_pk_add_f32 v[68:69], v[68:69], v[200:201]
	v_pk_add_f32 v[70:71], v[70:71], v[202:203]
	v_pk_add_f32 v[64:65], v[64:65], v[204:205]
	v_pk_add_f32 v[66:67], v[66:67], v[206:207]
	v_pk_add_f32 v[76:77], v[76:77], v[208:209]
	v_pk_add_f32 v[78:79], v[78:79], v[210:211]
	s_mov_b32 s100, s23
	v_lshl_add_u64 v[212:213], v[82:83], 0, s[100:101]
	global_load_dwordx4 v[116:119], v[212:213], off
	global_load_dwordx4 v[120:123], v[212:213], off offset:1024
	global_load_dwordx4 v[124:127], v[212:213], off offset:2048
	global_load_dwordx4 v[128:131], v[212:213], off offset:3072
	s_mov_b32 s100, s24
	v_lshl_add_u64 v[212:213], v[82:83], 0, s[100:101]
	global_load_dwordx4 v[132:135], v[212:213], off
	global_load_dwordx4 v[136:139], v[212:213], off offset:1024
	global_load_dwordx4 v[140:143], v[212:213], off offset:2048
	global_load_dwordx4 v[144:147], v[212:213], off offset:3072
	s_mov_b32 s100, s25
	v_lshl_add_u64 v[212:213], v[82:83], 0, s[100:101]
	global_load_dwordx4 v[148:151], v[212:213], off
	global_load_dwordx4 v[152:155], v[212:213], off offset:1024
	global_load_dwordx4 v[156:159], v[212:213], off offset:2048
	global_load_dwordx4 v[160:163], v[212:213], off offset:3072
	s_mov_b32 s100, s26
	v_lshl_add_u64 v[212:213], v[82:83], 0, s[100:101]
	global_load_dwordx4 v[164:167], v[212:213], off
	global_load_dwordx4 v[168:171], v[212:213], off offset:1024
	global_load_dwordx4 v[172:175], v[212:213], off offset:2048
	global_load_dwordx4 v[176:179], v[212:213], off offset:3072
	s_mov_b32 s100, s27
	v_lshl_add_u64 v[212:213], v[82:83], 0, s[100:101]
	global_load_dwordx4 v[180:183], v[212:213], off
	global_load_dwordx4 v[184:187], v[212:213], off offset:1024
	global_load_dwordx4 v[188:191], v[212:213], off offset:2048
	global_load_dwordx4 v[192:195], v[212:213], off offset:3072
	s_waitcnt vmcnt(0)
	v_pk_add_f32 v[72:73], v[72:73], v[116:117]
	v_pk_add_f32 v[74:75], v[74:75], v[118:119]
	v_pk_add_f32 v[68:69], v[68:69], v[120:121]
	v_pk_add_f32 v[70:71], v[70:71], v[122:123]
	v_pk_add_f32 v[64:65], v[64:65], v[124:125]
	v_pk_add_f32 v[66:67], v[66:67], v[126:127]
	v_pk_add_f32 v[76:77], v[76:77], v[128:129]
	v_pk_add_f32 v[78:79], v[78:79], v[130:131]
	v_pk_add_f32 v[72:73], v[72:73], v[132:133]
	v_pk_add_f32 v[74:75], v[74:75], v[134:135]
	v_pk_add_f32 v[68:69], v[68:69], v[136:137]
	v_pk_add_f32 v[70:71], v[70:71], v[138:139]
	v_pk_add_f32 v[64:65], v[64:65], v[140:141]
	v_pk_add_f32 v[66:67], v[66:67], v[142:143]
	v_pk_add_f32 v[76:77], v[76:77], v[144:145]
	v_pk_add_f32 v[78:79], v[78:79], v[146:147]
	v_pk_add_f32 v[72:73], v[72:73], v[148:149]
	v_pk_add_f32 v[74:75], v[74:75], v[150:151]
	v_pk_add_f32 v[68:69], v[68:69], v[152:153]
	v_pk_add_f32 v[70:71], v[70:71], v[154:155]
	v_pk_add_f32 v[64:65], v[64:65], v[156:157]
	v_pk_add_f32 v[66:67], v[66:67], v[158:159]
	v_pk_add_f32 v[76:77], v[76:77], v[160:161]
	v_pk_add_f32 v[78:79], v[78:79], v[162:163]
	v_pk_add_f32 v[72:73], v[72:73], v[164:165]
	v_pk_add_f32 v[74:75], v[74:75], v[166:167]
	v_pk_add_f32 v[68:69], v[68:69], v[168:169]
	v_pk_add_f32 v[70:71], v[70:71], v[170:171]
	v_pk_add_f32 v[64:65], v[64:65], v[172:173]
	v_pk_add_f32 v[66:67], v[66:67], v[174:175]
	v_pk_add_f32 v[76:77], v[76:77], v[176:177]
	v_pk_add_f32 v[78:79], v[78:79], v[178:179]
	v_pk_add_f32 v[72:73], v[72:73], v[180:181]
	v_pk_add_f32 v[74:75], v[74:75], v[182:183]
	v_pk_add_f32 v[68:69], v[68:69], v[184:185]
	v_pk_add_f32 v[70:71], v[70:71], v[186:187]
	v_pk_add_f32 v[64:65], v[64:65], v[188:189]
	v_pk_add_f32 v[66:67], v[66:67], v[190:191]
	v_pk_add_f32 v[76:77], v[76:77], v[192:193]
	v_pk_add_f32 v[78:79], v[78:79], v[194:195]
